# k35
# baseline (speedup 1.0000x reference)
; #define PG8_STAGE(bufoff, gbase, voff) do { _Pragma("unroll") for (int _i = 0; _i < 2; ++_i) \
;         __builtin_amdgcn_global_load_lds((const unsigned*)((const char*)(gbase) + (voff)[_i]), (PG8_LAS unsigned*)(lds + (bufoff) + ldsw + _i * 8192), 16, 0, 0); } while (0)
; #define PG8_LDA(dst, b, h) do { _Pragma("unroll") for (int m = 0; m < 4; ++m) _Pragma("unroll") for (int k = 0; k < 2; ++k) dst[m][k] = *(const PG8_LAS bf16x8*)(lds + PG8_SA(b, h) + aoff + m * 2048 + k * 1024); } while (0)
; #define PG8_LDB(dst, b, h) do { _Pragma("unroll") for (int n = 0; n < 2; ++n) _Pragma("unroll") for (int k = 0; k < 2; ++k) dst[n][k] = *(const PG8_LAS bf16x8*)(lds + PG8_SB(b, h) + boff + n * 2048 + k * 1024); } while (0)
; #define PG8_MMA(ai, bj, At, Bt) do { __builtin_amdgcn_s_setprio(1); _Pragma("unroll") for (int m = 0; m < 4; ++m) _Pragma("unroll") for (int n = 0; n < 2; ++n) _Pragma("unroll") for (int k = 0; k < 2; ++k) \
;         acc[ai][bj][m][n] = __builtin_amdgcn_mfma_f32_16x16x32_bf16(Bt[n][k], At[m][k], acc[ai][bj][m][n], 0, 0, 0); __builtin_amdgcn_s_setprio(0); } while (0)
; #define PG8_WAIT_V(n) asm volatile("s_waitcnt vmcnt(" #n ")" ::: "memory")
; #define PG8_WAIT_L(n) asm volatile("s_waitcnt lgkmcnt(" #n ")" ::: "memory")
; #define PG8_BAR __builtin_amdgcn_s_barrier()
; #define PG8_SCHED __builtin_amdgcn_sched_barrier(0)
; template <class Epi, class Sched, bool ALIGN_EPI = false, bool SP2 = false>
; __device__ __forceinline__ void gemm_phase(PG8_LAS unsigned char* lds, const Gemm g, const Sched& S, const Epi& E) {
;     ...
;             PG8_LDB(B0, 0, 0); PG8_LDB(B1, 0, 1); PG8_SCHED; PG8_LDA(At, 0, 0); PG8_STAGE(PG8_SA(1, 1), a1 + hstep, voffA);
;             PG8_WAIT_V(8); PG8_WAIT_L(0); PG8_BAR; PG8_MMA(0, 0, At, B0); PG8_MMA(0, 1, At, B1); PG8_BAR; PG8_SCHED;
;             PG8_LDA(At, 0, 1); PG8_STAGE(PG8_SB(0, 0), b2, voffB); PG8_STAGE(PG8_SB(0, 1), b2 + hstep, voffB); PG8_STAGE(PG8_SA(0, 0), a2, voffA);
;             PG8_WAIT_V(8); PG8_WAIT_L(0); PG8_BAR; PG8_MMA(1, 0, At, B0); PG8_MMA(1, 1, At, B1); PG8_BAR; PG8_SCHED;
.LBB0_215:
	ds_read_b128 v[130:133], v186
	ds_read_b128 v[134:137], v186 offset:1024
	ds_read_b128 v[138:141], v186 offset:2048
	ds_read_b128 v[166:169], v186 offset:3072
	ds_read_b128 v[170:173], v187
	ds_read_b128 v[174:177], v187 offset:1024
	ds_read_b128 v[178:181], v187 offset:2048
	ds_read_b128 v[182:185], v187 offset:3072
	s_add_u32 s30, s76, 0xfffc0080
	s_addc_u32 s31, s77, -1
	s_cmp_eq_u32 s75, 12
	s_cselect_b32 s81, s1, s31
	s_cselect_b32 s80, s8, s30
	s_cselect_b32 s79, s19, s63
	s_cselect_b32 s78, s33, s61
	v_lshl_add_u64 v[202:203], s[76:77], 0, v[158:159]
	s_add_i32 m0, s28, 0xc000
	ds_read_b128 v[190:193], v188
	ds_read_b128 v[194:197], v188 offset:1024
	ds_read_b128 v[198:201], v188 offset:2048
	ds_read_b128 v[206:209], v188 offset:3072
	ds_read_b128 v[210:213], v188 offset:4096
	ds_read_b128 v[214:217], v188 offset:5120
	ds_read_b128 v[218:221], v188 offset:6144
	ds_read_b128 v[222:225], v188 offset:7168
	global_load_lds_dwordx4 v[202:203], off
	v_lshl_add_u64 v[202:203], s[76:77], 0, v[160:161]
	s_add_i32 m0, s28, 0xe000
	s_nop 0
	global_load_lds_dwordx4 v[202:203], off
	s_waitcnt vmcnt(8)
	s_waitcnt lgkmcnt(0)
	s_barrier
	s_setprio 1
	s_waitcnt lgkmcnt(0)
	v_mfma_f32_16x16x32_bf16 v[126:129], v[130:133], v[190:193], v[126:129]
	v_mfma_f32_16x16x32_bf16 v[122:125], v[138:141], v[190:193], v[122:125]
	v_mfma_f32_16x16x32_bf16 v[118:121], v[130:133], v[198:201], v[118:121]
	v_mfma_f32_16x16x32_bf16 v[114:117], v[138:141], v[198:201], v[114:117]
	v_mfma_f32_16x16x32_bf16 v[110:113], v[130:133], v[210:213], v[110:113]
	v_mfma_f32_16x16x32_bf16 v[106:109], v[138:141], v[210:213], v[106:109]
	v_mfma_f32_16x16x32_bf16 v[102:105], v[130:133], v[218:221], v[102:105]
	v_mfma_f32_16x16x32_bf16 v[98:101], v[138:141], v[218:221], v[98:101]
	v_mfma_f32_16x16x32_bf16 v[126:129], v[134:137], v[194:197], v[126:129]
	v_mfma_f32_16x16x32_bf16 v[122:125], v[166:169], v[194:197], v[122:125]
	v_mfma_f32_16x16x32_bf16 v[118:121], v[134:137], v[206:209], v[118:121]
	v_mfma_f32_16x16x32_bf16 v[114:117], v[166:169], v[206:209], v[114:117]
	v_mfma_f32_16x16x32_bf16 v[110:113], v[134:137], v[214:217], v[110:113]
	v_mfma_f32_16x16x32_bf16 v[106:109], v[166:169], v[214:217], v[106:109]
	v_mfma_f32_16x16x32_bf16 v[102:105], v[134:137], v[222:225], v[102:105]
	v_mfma_f32_16x16x32_bf16 v[98:101], v[166:169], v[222:225], v[98:101]
	s_setprio 0
	s_setprio 1
	v_mfma_f32_16x16x32_bf16 v[62:65], v[170:173], v[190:193], v[62:65]
	v_mfma_f32_16x16x32_bf16 v[58:61], v[178:181], v[190:193], v[58:61]
	v_mfma_f32_16x16x32_bf16 v[54:57], v[170:173], v[198:201], v[54:57]
	v_mfma_f32_16x16x32_bf16 v[50:53], v[178:181], v[198:201], v[50:53]
	v_mfma_f32_16x16x32_bf16 v[46:49], v[170:173], v[210:213], v[46:49]
	v_mfma_f32_16x16x32_bf16 v[42:45], v[178:181], v[210:213], v[42:45]
	v_mfma_f32_16x16x32_bf16 v[38:41], v[170:173], v[218:221], v[38:41]
	v_mfma_f32_16x16x32_bf16 v[34:37], v[178:181], v[218:221], v[34:37]
	v_mfma_f32_16x16x32_bf16 v[62:65], v[174:177], v[194:197], v[62:65]
	v_mfma_f32_16x16x32_bf16 v[58:61], v[182:185], v[194:197], v[58:61]
	v_mfma_f32_16x16x32_bf16 v[54:57], v[174:177], v[206:209], v[54:57]
	v_mfma_f32_16x16x32_bf16 v[50:53], v[182:185], v[206:209], v[50:53]
	v_mfma_f32_16x16x32_bf16 v[46:49], v[174:177], v[214:217], v[46:49]
	v_mfma_f32_16x16x32_bf16 v[42:45], v[182:185], v[214:217], v[42:45]
	v_mfma_f32_16x16x32_bf16 v[38:41], v[174:177], v[222:225], v[38:41]
	s_barrier
	v_mfma_f32_16x16x32_bf16 v[34:37], v[182:185], v[222:225], v[34:37]
	s_setprio 0
	s_add_i32 s30, s7, s97
	v_lshl_add_u64 v[202:203], s[78:79], 0, v[146:147]
	s_mov_b32 m0, s30
	ds_read_b128 v[190:193], v188 offset:16384
	ds_read_b128 v[194:197], v188 offset:17408
	ds_read_b128 v[198:201], v188 offset:18432
	ds_read_b128 v[206:209], v188 offset:19456
	ds_read_b128 v[210:213], v188 offset:20480
	ds_read_b128 v[214:217], v188 offset:21504
	ds_read_b128 v[218:221], v188 offset:22528
	ds_read_b128 v[222:225], v188 offset:23552
	global_load_lds_dwordx4 v[202:203], off
	s_add_i32 m0, s30, 0x2000
	s_add_u32 s30, s78, 0x40000
	v_lshl_add_u64 v[226:227], s[78:79], 0, v[150:151]
	s_addc_u32 s31, s79, 0
	s_add_i32 s94, s92, s97
	global_load_lds_dwordx4 v[226:227], off
	v_lshl_add_u64 v[228:229], s[30:31], 0, v[146:147]
	s_mov_b32 m0, s94
	v_lshl_add_u64 v[230:231], s[80:81], 0, v[148:149]
	global_load_lds_dwordx4 v[228:229], off
	v_lshl_add_u64 v[228:229], s[30:31], 0, v[150:151]
	s_add_i32 m0, s94, 0x2000
	s_nop 0
	global_load_lds_dwordx4 v[228:229], off
	v_lshl_add_u64 v[228:229], s[80:81], 0, v[144:145]
	s_mov_b32 m0, s28
	s_nop 0
	global_load_lds_dwordx4 v[228:229], off
	s_mov_b32 m0, s29
	s_nop 0
	global_load_lds_dwordx4 v[230:231], off
	s_waitcnt vmcnt(8)
	s_waitcnt lgkmcnt(0)
	s_barrier
; #define PG8_STAGE(bufoff, gbase, voff) do { _Pragma("unroll") for (int _i = 0; _i < 2; ++_i) \
;         __builtin_amdgcn_global_load_lds((const unsigned*)((const char*)(gbase) + (voff)[_i]), (PG8_LAS unsigned*)(lds + (bufoff) + ldsw + _i * 8192), 16, 0, 0); } while (0)
; #define PG8_LDA(dst, b, h) do { _Pragma("unroll") for (int m = 0; m < 4; ++m) _Pragma("unroll") for (int k = 0; k < 2; ++k) dst[m][k] = *(const PG8_LAS bf16x8*)(lds + PG8_SA(b, h) + aoff + m * 2048 + k * 1024); } while (0)
; #define PG8_LDB(dst, b, h) do { _Pragma("unroll") for (int n = 0; n < 2; ++n) _Pragma("unroll") for (int k = 0; k < 2; ++k) dst[n][k] = *(const PG8_LAS bf16x8*)(lds + PG8_SB(b, h) + boff + n * 2048 + k * 1024); } while (0)
; #define PG8_MMA(ai, bj, At, Bt) do { __builtin_amdgcn_s_setprio(1); _Pragma("unroll") for (int m = 0; m < 4; ++m) _Pragma("unroll") for (int n = 0; n < 2; ++n) _Pragma("unroll") for (int k = 0; k < 2; ++k) \
;         acc[ai][bj][m][n] = __builtin_amdgcn_mfma_f32_16x16x32_bf16(Bt[n][k], At[m][k], acc[ai][bj][m][n], 0, 0, 0); __builtin_amdgcn_s_setprio(0); } while (0)
; #define PG8_WAIT_V(n) asm volatile("s_waitcnt vmcnt(" #n ")" ::: "memory")
; #define PG8_WAIT_L(n) asm volatile("s_waitcnt lgkmcnt(" #n ")" ::: "memory")
; #define PG8_BAR __builtin_amdgcn_s_barrier()
; #define PG8_SCHED __builtin_amdgcn_sched_barrier(0)
; template <class Epi, class Sched, bool ALIGN_EPI = false, bool SP2 = false>
; __device__ __forceinline__ void gemm_phase(PG8_LAS unsigned char* lds, const Gemm g, const Sched& S, const Epi& E) {
;     ...
;             PG8_WAIT_V(8); PG8_WAIT_L(0); PG8_BAR; PG8_MMA(1, 0, At, B0); PG8_MMA(1, 1, At, B1); PG8_BAR; PG8_SCHED;
;             PG8_LDB(B0, 1, 0); PG8_LDB(B1, 1, 1); PG8_SCHED; PG8_LDA(At, 1, 0); PG8_STAGE(PG8_SA(0, 1), a2 + hstep, voffA);
;             PG8_WAIT_V(8); PG8_WAIT_L(0); PG8_BAR; PG8_MMA(0, 0, At, B0); PG8_MMA(0, 1, At, B1); PG8_BAR; PG8_SCHED;
	s_setprio 1
	s_waitcnt lgkmcnt(0)
	v_mfma_f32_16x16x32_bf16 v[94:97], v[130:133], v[190:193], v[94:97]
	v_mfma_f32_16x16x32_bf16 v[90:93], v[138:141], v[190:193], v[90:93]
	v_mfma_f32_16x16x32_bf16 v[86:89], v[130:133], v[198:201], v[86:89]
	v_mfma_f32_16x16x32_bf16 v[82:85], v[138:141], v[198:201], v[82:85]
	v_mfma_f32_16x16x32_bf16 v[78:81], v[130:133], v[210:213], v[78:81]
	v_mfma_f32_16x16x32_bf16 v[74:77], v[138:141], v[210:213], v[74:77]
	v_mfma_f32_16x16x32_bf16 v[70:73], v[130:133], v[218:221], v[70:73]
	v_mfma_f32_16x16x32_bf16 v[66:69], v[138:141], v[218:221], v[66:69]
	v_mfma_f32_16x16x32_bf16 v[94:97], v[134:137], v[194:197], v[94:97]
	v_mfma_f32_16x16x32_bf16 v[90:93], v[166:169], v[194:197], v[90:93]
	v_mfma_f32_16x16x32_bf16 v[86:89], v[134:137], v[206:209], v[86:89]
	v_mfma_f32_16x16x32_bf16 v[82:85], v[166:169], v[206:209], v[82:85]
	v_mfma_f32_16x16x32_bf16 v[78:81], v[134:137], v[214:217], v[78:81]
	v_mfma_f32_16x16x32_bf16 v[74:77], v[166:169], v[214:217], v[74:77]
	v_mfma_f32_16x16x32_bf16 v[70:73], v[134:137], v[222:225], v[70:73]
	v_mfma_f32_16x16x32_bf16 v[66:69], v[166:169], v[222:225], v[66:69]
	s_setprio 0
	s_setprio 1
	v_mfma_f32_16x16x32_bf16 v[30:33], v[170:173], v[190:193], v[30:33]
	v_mfma_f32_16x16x32_bf16 v[26:29], v[178:181], v[190:193], v[26:29]
	v_mfma_f32_16x16x32_bf16 v[22:25], v[170:173], v[198:201], v[22:25]
	v_mfma_f32_16x16x32_bf16 v[18:21], v[178:181], v[198:201], v[18:21]
	v_mfma_f32_16x16x32_bf16 v[14:17], v[170:173], v[210:213], v[14:17]
	v_mfma_f32_16x16x32_bf16 v[10:13], v[178:181], v[210:213], v[10:13]
	v_mfma_f32_16x16x32_bf16 v[6:9], v[170:173], v[218:221], v[6:9]
	v_mfma_f32_16x16x32_bf16 v[2:5], v[178:181], v[218:221], v[2:5]
	v_mfma_f32_16x16x32_bf16 v[30:33], v[174:177], v[194:197], v[30:33]
	v_mfma_f32_16x16x32_bf16 v[26:29], v[182:185], v[194:197], v[26:29]
	v_mfma_f32_16x16x32_bf16 v[22:25], v[174:177], v[206:209], v[22:25]
	v_mfma_f32_16x16x32_bf16 v[18:21], v[182:185], v[206:209], v[18:21]
	v_mfma_f32_16x16x32_bf16 v[14:17], v[174:177], v[214:217], v[14:17]
	v_mfma_f32_16x16x32_bf16 v[10:13], v[182:185], v[214:217], v[10:13]
	v_mfma_f32_16x16x32_bf16 v[6:9], v[174:177], v[222:225], v[6:9]
	s_barrier
	v_mfma_f32_16x16x32_bf16 v[2:5], v[182:185], v[222:225], v[2:5]
	s_setprio 0
	s_add_i32 s94, 0, 0x18000
	v_add_u32_e32 v152, s94, v155
	s_add_i32 s95, 0, 0x1c000
	ds_read_b128 v[130:133], v152
	ds_read_b128 v[134:137], v152 offset:1024
	ds_read_b128 v[138:141], v152 offset:2048
	ds_read_b128 v[166:169], v152 offset:3072
	v_add_u32_e32 v152, s95, v155
	ds_read_b128 v[170:173], v152
	ds_read_b128 v[174:177], v152 offset:1024
	ds_read_b128 v[178:181], v152 offset:2048
	ds_read_b128 v[182:185], v152 offset:3072
	s_add_u32 s30, s80, 0x40000
	s_addc_u32 s31, s81, 0
	s_mov_b32 m0, s50
	v_lshl_add_u64 v[232:233], s[30:31], 0, v[144:145]
	ds_read_b128 v[190:193], v188 offset:32768
	ds_read_b128 v[194:197], v188 offset:33792
	ds_read_b128 v[198:201], v188 offset:34816
	ds_read_b128 v[206:209], v188 offset:35840
	ds_read_b128 v[210:213], v188 offset:36864
	ds_read_b128 v[214:217], v188 offset:37888
	ds_read_b128 v[218:221], v188 offset:38912
	ds_read_b128 v[222:225], v188 offset:39936
	global_load_lds_dwordx4 v[232:233], off
	v_lshl_add_u64 v[232:233], s[30:31], 0, v[148:149]
	s_mov_b32 m0, s51
	s_nop 0
	global_load_lds_dwordx4 v[232:233], off
	s_waitcnt vmcnt(8)
	s_waitcnt lgkmcnt(0)
	s_barrier
	s_setprio 1
	s_waitcnt lgkmcnt(0)
	v_mfma_f32_16x16x32_bf16 v[126:129], v[130:133], v[190:193], v[126:129]
	v_mfma_f32_16x16x32_bf16 v[122:125], v[138:141], v[190:193], v[122:125]
	v_mfma_f32_16x16x32_bf16 v[118:121], v[130:133], v[198:201], v[118:121]
	v_mfma_f32_16x16x32_bf16 v[114:117], v[138:141], v[198:201], v[114:117]
	v_mfma_f32_16x16x32_bf16 v[110:113], v[130:133], v[210:213], v[110:113]
	v_mfma_f32_16x16x32_bf16 v[106:109], v[138:141], v[210:213], v[106:109]
	v_mfma_f32_16x16x32_bf16 v[102:105], v[130:133], v[218:221], v[102:105]
	v_mfma_f32_16x16x32_bf16 v[98:101], v[138:141], v[218:221], v[98:101]
	v_mfma_f32_16x16x32_bf16 v[126:129], v[134:137], v[194:197], v[126:129]
	v_mfma_f32_16x16x32_bf16 v[122:125], v[166:169], v[194:197], v[122:125]
	v_mfma_f32_16x16x32_bf16 v[118:121], v[134:137], v[206:209], v[118:121]
	v_mfma_f32_16x16x32_bf16 v[114:117], v[166:169], v[206:209], v[114:117]
	v_mfma_f32_16x16x32_bf16 v[110:113], v[134:137], v[214:217], v[110:113]
	v_mfma_f32_16x16x32_bf16 v[106:109], v[166:169], v[214:217], v[106:109]
	v_mfma_f32_16x16x32_bf16 v[102:105], v[134:137], v[222:225], v[102:105]
	v_mfma_f32_16x16x32_bf16 v[98:101], v[166:169], v[222:225], v[98:101]
	s_setprio 0
	s_setprio 1
	v_mfma_f32_16x16x32_bf16 v[62:65], v[170:173], v[190:193], v[62:65]
	v_mfma_f32_16x16x32_bf16 v[58:61], v[178:181], v[190:193], v[58:61]
	v_mfma_f32_16x16x32_bf16 v[54:57], v[170:173], v[198:201], v[54:57]
	v_mfma_f32_16x16x32_bf16 v[50:53], v[178:181], v[198:201], v[50:53]
	v_mfma_f32_16x16x32_bf16 v[46:49], v[170:173], v[210:213], v[46:49]
	v_mfma_f32_16x16x32_bf16 v[42:45], v[178:181], v[210:213], v[42:45]
	v_mfma_f32_16x16x32_bf16 v[38:41], v[170:173], v[218:221], v[38:41]
	v_mfma_f32_16x16x32_bf16 v[34:37], v[178:181], v[218:221], v[34:37]
	v_mfma_f32_16x16x32_bf16 v[62:65], v[174:177], v[194:197], v[62:65]
	v_mfma_f32_16x16x32_bf16 v[58:61], v[182:185], v[194:197], v[58:61]
	v_mfma_f32_16x16x32_bf16 v[54:57], v[174:177], v[206:209], v[54:57]
	v_mfma_f32_16x16x32_bf16 v[50:53], v[182:185], v[206:209], v[50:53]
	v_mfma_f32_16x16x32_bf16 v[46:49], v[174:177], v[214:217], v[46:49]
	v_mfma_f32_16x16x32_bf16 v[42:45], v[182:185], v[214:217], v[42:45]
	v_mfma_f32_16x16x32_bf16 v[38:41], v[174:177], v[222:225], v[38:41]
	s_barrier
; #define PG8_STAGE(bufoff, gbase, voff) do { _Pragma("unroll") for (int _i = 0; _i < 2; ++_i) \
;         __builtin_amdgcn_global_load_lds((const unsigned*)((const char*)(gbase) + (voff)[_i]), (PG8_LAS unsigned*)(lds + (bufoff) + ldsw + _i * 8192), 16, 0, 0); } while (0)
; #define PG8_LDA(dst, b, h) do { _Pragma("unroll") for (int m = 0; m < 4; ++m) _Pragma("unroll") for (int k = 0; k < 2; ++k) dst[m][k] = *(const PG8_LAS bf16x8*)(lds + PG8_SA(b, h) + aoff + m * 2048 + k * 1024); } while (0)
; #define PG8_MMA(ai, bj, At, Bt) do { __builtin_amdgcn_s_setprio(1); _Pragma("unroll") for (int m = 0; m < 4; ++m) _Pragma("unroll") for (int n = 0; n < 2; ++n) _Pragma("unroll") for (int k = 0; k < 2; ++k) \
;         acc[ai][bj][m][n] = __builtin_amdgcn_mfma_f32_16x16x32_bf16(Bt[n][k], At[m][k], acc[ai][bj][m][n], 0, 0, 0); __builtin_amdgcn_s_setprio(0); } while (0)
; #define PG8_WAIT_V(n) asm volatile("s_waitcnt vmcnt(" #n ")" ::: "memory")
; #define PG8_WAIT_L(n) asm volatile("s_waitcnt lgkmcnt(" #n ")" ::: "memory")
; #define PG8_BAR __builtin_amdgcn_s_barrier()
; #define PG8_SCHED __builtin_amdgcn_sched_barrier(0)
; template <class Epi, class Sched, bool ALIGN_EPI = false, bool SP2 = false>
; __device__ __forceinline__ void gemm_phase(PG8_LAS unsigned char* lds, const Gemm g, const Sched& S, const Epi& E) {
;     ...
;             PG8_WAIT_V(8); PG8_WAIT_L(0); PG8_BAR; PG8_MMA(0, 0, At, B0); PG8_MMA(0, 1, At, B1); PG8_BAR; PG8_SCHED;
;             PG8_LDA(At, 1, 1); PG8_STAGE(PG8_SB(1, 0), b3, voffB); PG8_STAGE(PG8_SB(1, 1), b3 + hstep, voffB); PG8_STAGE(PG8_SA(1, 0), a3, voffA);
;             PG8_WAIT_V(8); PG8_WAIT_L(0); PG8_BAR; PG8_MMA(1, 0, At, B0); PG8_MMA(1, 1, At, B1); PG8_BAR; PG8_SCHED;
	v_mfma_f32_16x16x32_bf16 v[34:37], v[182:185], v[222:225], v[34:37]
	s_setprio 0
	s_add_i32 s30, s94, s97
	v_lshl_add_u64 v[202:203], v[202:203], 0, s[40:41]
	s_mov_b32 m0, s30
	ds_read_b128 v[190:193], v188 offset:49152
	ds_read_b128 v[194:197], v188 offset:50176
	ds_read_b128 v[198:201], v188 offset:51200
	ds_read_b128 v[206:209], v188 offset:52224
	ds_read_b128 v[210:213], v188 offset:53248
	ds_read_b128 v[214:217], v188 offset:54272
	ds_read_b128 v[218:221], v188 offset:55296
	ds_read_b128 v[222:225], v188 offset:56320
	global_load_lds_dwordx4 v[202:203], off
	s_add_i32 m0, s30, 0x2000
	s_add_u32 s30, s78, 0x40080
	v_lshl_add_u64 v[202:203], v[226:227], 0, s[40:41]
	s_addc_u32 s31, s79, 0
	s_add_i32 s78, s95, s97
	global_load_lds_dwordx4 v[202:203], off
	v_lshl_add_u64 v[202:203], s[30:31], 0, v[146:147]
	s_mov_b32 m0, s78
	s_nop 0
	global_load_lds_dwordx4 v[202:203], off
	v_lshl_add_u64 v[202:203], s[30:31], 0, v[150:151]
	s_add_i32 m0, s78, 0x2000
	s_nop 0
	global_load_lds_dwordx4 v[202:203], off
	v_lshl_add_u64 v[202:203], v[228:229], 0, s[40:41]
	s_mov_b32 m0, s57
	s_nop 0
	global_load_lds_dwordx4 v[202:203], off
	v_lshl_add_u64 v[202:203], v[230:231], 0, s[40:41]
	s_mov_b32 m0, s58
	s_nop 0
	global_load_lds_dwordx4 v[202:203], off
	s_waitcnt vmcnt(8)
	s_waitcnt lgkmcnt(0)
	s_barrier
	s_setprio 1
	s_waitcnt lgkmcnt(0)
	v_mfma_f32_16x16x32_bf16 v[94:97], v[130:133], v[190:193], v[94:97]
	v_mfma_f32_16x16x32_bf16 v[90:93], v[138:141], v[190:193], v[90:93]
	v_mfma_f32_16x16x32_bf16 v[86:89], v[130:133], v[198:201], v[86:89]
	v_mfma_f32_16x16x32_bf16 v[82:85], v[138:141], v[198:201], v[82:85]
	v_mfma_f32_16x16x32_bf16 v[78:81], v[130:133], v[210:213], v[78:81]
	v_mfma_f32_16x16x32_bf16 v[74:77], v[138:141], v[210:213], v[74:77]
	v_mfma_f32_16x16x32_bf16 v[70:73], v[130:133], v[218:221], v[70:73]
	v_mfma_f32_16x16x32_bf16 v[66:69], v[138:141], v[218:221], v[66:69]
	v_mfma_f32_16x16x32_bf16 v[94:97], v[134:137], v[194:197], v[94:97]
	v_mfma_f32_16x16x32_bf16 v[90:93], v[166:169], v[194:197], v[90:93]
	v_mfma_f32_16x16x32_bf16 v[86:89], v[134:137], v[206:209], v[86:89]
	v_mfma_f32_16x16x32_bf16 v[82:85], v[166:169], v[206:209], v[82:85]
	v_mfma_f32_16x16x32_bf16 v[78:81], v[134:137], v[214:217], v[78:81]
	v_mfma_f32_16x16x32_bf16 v[74:77], v[166:169], v[214:217], v[74:77]
	v_mfma_f32_16x16x32_bf16 v[70:73], v[134:137], v[222:225], v[70:73]
	v_mfma_f32_16x16x32_bf16 v[66:69], v[166:169], v[222:225], v[66:69]
	s_setprio 0
	s_setprio 1
	v_mfma_f32_16x16x32_bf16 v[30:33], v[170:173], v[190:193], v[30:33]
	v_mfma_f32_16x16x32_bf16 v[26:29], v[178:181], v[190:193], v[26:29]
	v_mfma_f32_16x16x32_bf16 v[22:25], v[170:173], v[198:201], v[22:25]
	v_mfma_f32_16x16x32_bf16 v[18:21], v[178:181], v[198:201], v[18:21]
	v_mfma_f32_16x16x32_bf16 v[14:17], v[170:173], v[210:213], v[14:17]
	v_mfma_f32_16x16x32_bf16 v[10:13], v[178:181], v[210:213], v[10:13]
	v_mfma_f32_16x16x32_bf16 v[6:9], v[170:173], v[218:221], v[6:9]
	v_mfma_f32_16x16x32_bf16 v[2:5], v[178:181], v[218:221], v[2:5]
	v_mfma_f32_16x16x32_bf16 v[30:33], v[174:177], v[194:197], v[30:33]
	v_mfma_f32_16x16x32_bf16 v[26:29], v[182:185], v[194:197], v[26:29]
	v_mfma_f32_16x16x32_bf16 v[22:25], v[174:177], v[206:209], v[22:25]
	v_mfma_f32_16x16x32_bf16 v[18:21], v[182:185], v[206:209], v[18:21]
	v_mfma_f32_16x16x32_bf16 v[14:17], v[174:177], v[214:217], v[14:17]
	v_mfma_f32_16x16x32_bf16 v[10:13], v[182:185], v[214:217], v[10:13]
	v_mfma_f32_16x16x32_bf16 v[6:9], v[174:177], v[222:225], v[6:9]
	s_barrier
	v_mfma_f32_16x16x32_bf16 v[2:5], v[182:185], v[222:225], v[2:5]
	s_setprio 0
	s_add_i32 s75, s75, 2
	s_add_u32 s76, s76, 0x100
	s_addc_u32 s77, s77, 0
	s_add_u32 s61, s61, 0x100
	s_addc_u32 s63, s63, 0
	s_cmp_gt_u32 s75, 13
	s_cbranch_scc0 .LBB0_215
	s_and_b64 vcc, exec, s[44:45]
	s_cbranch_vccz .LBB0_218
	s_barrier

; #define PG8_STAGE(bufoff, gbase, voff) do { _Pragma("unroll") for (int _i = 0; _i < 2; ++_i) \
;         __builtin_amdgcn_global_load_lds((const unsigned*)((const char*)(gbase) + (voff)[_i]), (PG8_LAS unsigned*)(lds + (bufoff) + ldsw + _i * 8192), 16, 0, 0); } while (0)
; #define PG8_LDA(dst, b, h) do { _Pragma("unroll") for (int m = 0; m < 4; ++m) _Pragma("unroll") for (int k = 0; k < 2; ++k) dst[m][k] = *(const PG8_LAS bf16x8*)(lds + PG8_SA(b, h) + aoff + m * 2048 + k * 1024); } while (0)
; #define PG8_LDB(dst, b, h) do { _Pragma("unroll") for (int n = 0; n < 2; ++n) _Pragma("unroll") for (int k = 0; k < 2; ++k) dst[n][k] = *(const PG8_LAS bf16x8*)(lds + PG8_SB(b, h) + boff + n * 2048 + k * 1024); } while (0)
; #define PG8_MMA(ai, bj, At, Bt) do { __builtin_amdgcn_s_setprio(1); _Pragma("unroll") for (int m = 0; m < 4; ++m) _Pragma("unroll") for (int n = 0; n < 2; ++n) _Pragma("unroll") for (int k = 0; k < 2; ++k) \
;         acc[ai][bj][m][n] = __builtin_amdgcn_mfma_f32_16x16x32_bf16(Bt[n][k], At[m][k], acc[ai][bj][m][n], 0, 0, 0); __builtin_amdgcn_s_setprio(0); } while (0)
; #define PG8_WAIT_V(n) asm volatile("s_waitcnt vmcnt(" #n ")" ::: "memory")
; #define PG8_WAIT_L(n) asm volatile("s_waitcnt lgkmcnt(" #n ")" ::: "memory")
; #define PG8_BAR __builtin_amdgcn_s_barrier()
; #define PG8_SCHED __builtin_amdgcn_sched_barrier(0)
; template <class Epi, class Sched, bool ALIGN_EPI = false, bool SP2 = false>
; __device__ __forceinline__ void gemm_phase(PG8_LAS unsigned char* lds, const Gemm g, const Sched& S, const Epi& E) {
;     ...
;             PG8_LDB(B0, 0, 0); PG8_LDB(B1, 0, 1); PG8_SCHED; PG8_LDA(At, 0, 0); PG8_STAGE(PG8_SA(1, 1), a1 + hstep, voffA);
;             PG8_WAIT_V(8); PG8_WAIT_L(0); PG8_BAR; PG8_MMA(0, 0, At, B0); PG8_MMA(0, 1, At, B1); PG8_BAR; PG8_SCHED;
;             PG8_LDA(At, 0, 1); PG8_STAGE(PG8_SB(0, 0), b2, voffB); PG8_STAGE(PG8_SB(0, 1), b2 + hstep, voffB); PG8_STAGE(PG8_SA(0, 0), a2, voffA);
;             PG8_WAIT_V(8); PG8_WAIT_L(0); PG8_BAR; PG8_MMA(1, 0, At, B0); PG8_MMA(1, 1, At, B1); PG8_BAR; PG8_SCHED;
.LBB0_752:
	ds_read_b128 v[122:125], v184
	ds_read_b128 v[126:129], v184 offset:1024
	ds_read_b128 v[130:133], v184 offset:2048
	ds_read_b128 v[134:137], v184 offset:3072
	ds_read_b128 v[138:141], v185
	ds_read_b128 v[142:145], v185 offset:1024
	ds_read_b128 v[150:153], v185 offset:2048
	ds_read_b128 v[154:157], v185 offset:3072
	s_add_u32 s30, s26, 0xfffc0080
	s_addc_u32 s31, s27, -1
	s_cmp_eq_u32 s64, 12
	s_cselect_b32 s41, s19, s31
	s_cselect_b32 s40, s60, s30
	s_cselect_b32 s39, s17, s63
	s_cselect_b32 s38, s61, s62
	v_lshl_add_u64 v[218:219], s[26:27], 0, v[170:171]
	s_add_i32 m0, s25, 0xc000
	ds_read_b128 v[178:181], v186
	ds_read_b128 v[188:191], v186 offset:1024
	ds_read_b128 v[192:195], v186 offset:2048
	ds_read_b128 v[196:199], v186 offset:3072
	ds_read_b128 v[200:203], v186 offset:4096
	ds_read_b128 v[206:209], v186 offset:5120
	ds_read_b128 v[210:213], v186 offset:6144
	ds_read_b128 v[214:217], v186 offset:7168
	global_load_lds_dwordx4 v[218:219], off
	v_lshl_add_u64 v[218:219], s[26:27], 0, v[172:173]
	s_add_i32 m0, s25, 0xe000
	s_nop 0
	global_load_lds_dwordx4 v[218:219], off
	s_waitcnt vmcnt(8)
	s_waitcnt lgkmcnt(0)
	s_barrier
	s_setprio 1
	s_waitcnt lgkmcnt(0)
	v_mfma_f32_16x16x32_bf16 v[158:161], v[122:125], v[178:181], v[158:161]
	v_mfma_f32_16x16x32_bf16 v[146:149], v[130:133], v[178:181], v[146:149]
	v_mfma_f32_16x16x32_bf16 v[114:117], v[122:125], v[192:195], v[114:117]
	v_mfma_f32_16x16x32_bf16 v[106:109], v[130:133], v[192:195], v[106:109]
	v_mfma_f32_16x16x32_bf16 v[94:97], v[122:125], v[200:203], v[94:97]
	v_mfma_f32_16x16x32_bf16 v[90:93], v[130:133], v[200:203], v[90:93]
	v_mfma_f32_16x16x32_bf16 v[82:85], v[122:125], v[210:213], v[82:85]
	v_mfma_f32_16x16x32_bf16 v[74:77], v[130:133], v[210:213], v[74:77]
	v_mfma_f32_16x16x32_bf16 v[158:161], v[126:129], v[188:191], v[158:161]
	v_mfma_f32_16x16x32_bf16 v[146:149], v[134:137], v[188:191], v[146:149]
	v_mfma_f32_16x16x32_bf16 v[114:117], v[126:129], v[196:199], v[114:117]
	v_mfma_f32_16x16x32_bf16 v[106:109], v[134:137], v[196:199], v[106:109]
	v_mfma_f32_16x16x32_bf16 v[94:97], v[126:129], v[206:209], v[94:97]
	v_mfma_f32_16x16x32_bf16 v[90:93], v[134:137], v[206:209], v[90:93]
	v_mfma_f32_16x16x32_bf16 v[82:85], v[126:129], v[214:217], v[82:85]
	v_mfma_f32_16x16x32_bf16 v[74:77], v[134:137], v[214:217], v[74:77]
	s_setprio 0
	s_setprio 1
	v_mfma_f32_16x16x32_bf16 v[118:121], v[138:141], v[178:181], v[118:121]
	v_mfma_f32_16x16x32_bf16 v[110:113], v[150:153], v[178:181], v[110:113]
	v_mfma_f32_16x16x32_bf16 v[102:105], v[138:141], v[192:195], v[102:105]
	v_mfma_f32_16x16x32_bf16 v[98:101], v[150:153], v[192:195], v[98:101]
	v_mfma_f32_16x16x32_bf16 v[86:89], v[138:141], v[200:203], v[86:89]
	v_mfma_f32_16x16x32_bf16 v[78:81], v[150:153], v[200:203], v[78:81]
	v_mfma_f32_16x16x32_bf16 v[70:73], v[138:141], v[210:213], v[70:73]
	v_mfma_f32_16x16x32_bf16 v[66:69], v[150:153], v[210:213], v[66:69]
	v_mfma_f32_16x16x32_bf16 v[118:121], v[142:145], v[188:191], v[118:121]
	v_mfma_f32_16x16x32_bf16 v[110:113], v[154:157], v[188:191], v[110:113]
	v_mfma_f32_16x16x32_bf16 v[102:105], v[142:145], v[196:199], v[102:105]
	v_mfma_f32_16x16x32_bf16 v[98:101], v[154:157], v[196:199], v[98:101]
	v_mfma_f32_16x16x32_bf16 v[86:89], v[142:145], v[206:209], v[86:89]
	v_mfma_f32_16x16x32_bf16 v[78:81], v[154:157], v[206:209], v[78:81]
	v_mfma_f32_16x16x32_bf16 v[70:73], v[142:145], v[214:217], v[70:73]
	s_barrier
	v_mfma_f32_16x16x32_bf16 v[66:69], v[154:157], v[214:217], v[66:69]
	s_setprio 0
	s_add_i32 s30, s57, s33
	v_lshl_add_u64 v[218:219], s[38:39], 0, v[164:165]
	s_mov_b32 m0, s30
	ds_read_b128 v[178:181], v186 offset:16384
	ds_read_b128 v[188:191], v186 offset:17408
	ds_read_b128 v[192:195], v186 offset:18432
	ds_read_b128 v[196:199], v186 offset:19456
	ds_read_b128 v[200:203], v186 offset:20480
	ds_read_b128 v[206:209], v186 offset:21504
	ds_read_b128 v[210:213], v186 offset:22528
	ds_read_b128 v[214:217], v186 offset:23552
	global_load_lds_dwordx4 v[218:219], off
	s_add_i32 m0, s30, 0x2000
	s_add_u32 s30, s38, 0x40000
	v_lshl_add_u64 v[220:221], s[38:39], 0, v[168:169]
	s_addc_u32 s31, s39, 0
	s_add_i32 s65, s58, s33
	global_load_lds_dwordx4 v[220:221], off
	v_lshl_add_u64 v[222:223], s[30:31], 0, v[164:165]
	s_mov_b32 m0, s65
	v_lshl_add_u64 v[224:225], s[40:41], 0, v[166:167]
	global_load_lds_dwordx4 v[222:223], off
	v_lshl_add_u64 v[222:223], s[30:31], 0, v[168:169]
	s_add_i32 m0, s65, 0x2000
	s_nop 0
	global_load_lds_dwordx4 v[222:223], off
	v_lshl_add_u64 v[222:223], s[40:41], 0, v[162:163]
	s_mov_b32 m0, s25
	s_nop 0
	global_load_lds_dwordx4 v[222:223], off
	s_mov_b32 m0, s44
	s_nop 0
	global_load_lds_dwordx4 v[224:225], off
	s_waitcnt vmcnt(8)
	s_waitcnt lgkmcnt(0)
	s_barrier
; #define PG8_STAGE(bufoff, gbase, voff) do { _Pragma("unroll") for (int _i = 0; _i < 2; ++_i) \
;         __builtin_amdgcn_global_load_lds((const unsigned*)((const char*)(gbase) + (voff)[_i]), (PG8_LAS unsigned*)(lds + (bufoff) + ldsw + _i * 8192), 16, 0, 0); } while (0)
; #define PG8_LDA(dst, b, h) do { _Pragma("unroll") for (int m = 0; m < 4; ++m) _Pragma("unroll") for (int k = 0; k < 2; ++k) dst[m][k] = *(const PG8_LAS bf16x8*)(lds + PG8_SA(b, h) + aoff + m * 2048 + k * 1024); } while (0)
; #define PG8_LDB(dst, b, h) do { _Pragma("unroll") for (int n = 0; n < 2; ++n) _Pragma("unroll") for (int k = 0; k < 2; ++k) dst[n][k] = *(const PG8_LAS bf16x8*)(lds + PG8_SB(b, h) + boff + n * 2048 + k * 1024); } while (0)
; #define PG8_MMA(ai, bj, At, Bt) do { __builtin_amdgcn_s_setprio(1); _Pragma("unroll") for (int m = 0; m < 4; ++m) _Pragma("unroll") for (int n = 0; n < 2; ++n) _Pragma("unroll") for (int k = 0; k < 2; ++k) \
;         acc[ai][bj][m][n] = __builtin_amdgcn_mfma_f32_16x16x32_bf16(Bt[n][k], At[m][k], acc[ai][bj][m][n], 0, 0, 0); __builtin_amdgcn_s_setprio(0); } while (0)
; #define PG8_WAIT_V(n) asm volatile("s_waitcnt vmcnt(" #n ")" ::: "memory")
; #define PG8_WAIT_L(n) asm volatile("s_waitcnt lgkmcnt(" #n ")" ::: "memory")
; #define PG8_BAR __builtin_amdgcn_s_barrier()
; #define PG8_SCHED __builtin_amdgcn_sched_barrier(0)
; template <class Epi, class Sched, bool ALIGN_EPI = false, bool SP2 = false>
; __device__ __forceinline__ void gemm_phase(PG8_LAS unsigned char* lds, const Gemm g, const Sched& S, const Epi& E) {
;     ...
;             PG8_WAIT_V(8); PG8_WAIT_L(0); PG8_BAR; PG8_MMA(1, 0, At, B0); PG8_MMA(1, 1, At, B1); PG8_BAR; PG8_SCHED;
;             PG8_LDB(B0, 1, 0); PG8_LDB(B1, 1, 1); PG8_SCHED; PG8_LDA(At, 1, 0); PG8_STAGE(PG8_SA(0, 1), a2 + hstep, voffA);
;             PG8_WAIT_V(8); PG8_WAIT_L(0); PG8_BAR; PG8_MMA(0, 0, At, B0); PG8_MMA(0, 1, At, B1); PG8_BAR; PG8_SCHED;
	s_setprio 1
	s_waitcnt lgkmcnt(0)
	v_mfma_f32_16x16x32_bf16 v[62:65], v[122:125], v[178:181], v[62:65]
	v_mfma_f32_16x16x32_bf16 v[58:61], v[130:133], v[178:181], v[58:61]
	v_mfma_f32_16x16x32_bf16 v[50:53], v[122:125], v[192:195], v[50:53]
	v_mfma_f32_16x16x32_bf16 v[42:45], v[130:133], v[192:195], v[42:45]
	v_mfma_f32_16x16x32_bf16 v[30:33], v[122:125], v[200:203], v[30:33]
	v_mfma_f32_16x16x32_bf16 v[26:29], v[130:133], v[200:203], v[26:29]
	v_mfma_f32_16x16x32_bf16 v[18:21], v[122:125], v[210:213], v[18:21]
	v_mfma_f32_16x16x32_bf16 v[10:13], v[130:133], v[210:213], v[10:13]
	v_mfma_f32_16x16x32_bf16 v[62:65], v[126:129], v[188:191], v[62:65]
	v_mfma_f32_16x16x32_bf16 v[58:61], v[134:137], v[188:191], v[58:61]
	v_mfma_f32_16x16x32_bf16 v[50:53], v[126:129], v[196:199], v[50:53]
	v_mfma_f32_16x16x32_bf16 v[42:45], v[134:137], v[196:199], v[42:45]
	v_mfma_f32_16x16x32_bf16 v[30:33], v[126:129], v[206:209], v[30:33]
	v_mfma_f32_16x16x32_bf16 v[26:29], v[134:137], v[206:209], v[26:29]
	v_mfma_f32_16x16x32_bf16 v[18:21], v[126:129], v[214:217], v[18:21]
	v_mfma_f32_16x16x32_bf16 v[10:13], v[134:137], v[214:217], v[10:13]
	s_setprio 0
	s_setprio 1
	v_mfma_f32_16x16x32_bf16 v[54:57], v[138:141], v[178:181], v[54:57]
	v_mfma_f32_16x16x32_bf16 v[46:49], v[150:153], v[178:181], v[46:49]
	v_mfma_f32_16x16x32_bf16 v[38:41], v[138:141], v[192:195], v[38:41]
	v_mfma_f32_16x16x32_bf16 v[34:37], v[150:153], v[192:195], v[34:37]
	v_mfma_f32_16x16x32_bf16 v[22:25], v[138:141], v[200:203], v[22:25]
	v_mfma_f32_16x16x32_bf16 v[14:17], v[150:153], v[200:203], v[14:17]
	v_mfma_f32_16x16x32_bf16 v[6:9], v[138:141], v[210:213], v[6:9]
	v_mfma_f32_16x16x32_bf16 v[2:5], v[150:153], v[210:213], v[2:5]
	v_mfma_f32_16x16x32_bf16 v[54:57], v[142:145], v[188:191], v[54:57]
	v_mfma_f32_16x16x32_bf16 v[46:49], v[154:157], v[188:191], v[46:49]
	v_mfma_f32_16x16x32_bf16 v[38:41], v[142:145], v[196:199], v[38:41]
	v_mfma_f32_16x16x32_bf16 v[34:37], v[154:157], v[196:199], v[34:37]
	v_mfma_f32_16x16x32_bf16 v[22:25], v[142:145], v[206:209], v[22:25]
	v_mfma_f32_16x16x32_bf16 v[14:17], v[154:157], v[206:209], v[14:17]
	v_mfma_f32_16x16x32_bf16 v[6:9], v[142:145], v[214:217], v[6:9]
	s_barrier
	v_mfma_f32_16x16x32_bf16 v[2:5], v[154:157], v[214:217], v[2:5]
	s_setprio 0
	s_add_i32 s65, 0, 0x18000
	s_add_i32 s66, 0, 0x1c000
	v_add_u32_e32 v134, s65, v182
	v_add_u32_e32 v154, s66, v182
	ds_read_b128 v[122:125], v134
	ds_read_b128 v[126:129], v134 offset:1024
	ds_read_b128 v[130:133], v134 offset:2048
	ds_read_b128 v[134:137], v134 offset:3072
	ds_read_b128 v[138:141], v154
	ds_read_b128 v[142:145], v154 offset:1024
	ds_read_b128 v[150:153], v154 offset:2048
	ds_read_b128 v[154:157], v154 offset:3072
	s_add_u32 s30, s40, 0x40000
	s_addc_u32 s31, s41, 0
	s_mov_b32 m0, s45
	v_lshl_add_u64 v[226:227], s[30:31], 0, v[162:163]
	ds_read_b128 v[178:181], v186 offset:32768
	ds_read_b128 v[188:191], v186 offset:33792
	ds_read_b128 v[192:195], v186 offset:34816
	ds_read_b128 v[196:199], v186 offset:35840
	ds_read_b128 v[200:203], v186 offset:36864
	ds_read_b128 v[206:209], v186 offset:37888
	ds_read_b128 v[210:213], v186 offset:38912
	ds_read_b128 v[214:217], v186 offset:39936
	global_load_lds_dwordx4 v[226:227], off
	v_lshl_add_u64 v[226:227], s[30:31], 0, v[166:167]
	s_mov_b32 m0, s50
	s_nop 0
	global_load_lds_dwordx4 v[226:227], off
	s_waitcnt vmcnt(8)
	s_waitcnt lgkmcnt(0)
	s_barrier
	s_setprio 1
	s_waitcnt lgkmcnt(0)
	v_mfma_f32_16x16x32_bf16 v[158:161], v[122:125], v[178:181], v[158:161]
	v_mfma_f32_16x16x32_bf16 v[146:149], v[130:133], v[178:181], v[146:149]
	v_mfma_f32_16x16x32_bf16 v[114:117], v[122:125], v[192:195], v[114:117]
	v_mfma_f32_16x16x32_bf16 v[106:109], v[130:133], v[192:195], v[106:109]
	v_mfma_f32_16x16x32_bf16 v[94:97], v[122:125], v[200:203], v[94:97]
	v_mfma_f32_16x16x32_bf16 v[90:93], v[130:133], v[200:203], v[90:93]
	v_mfma_f32_16x16x32_bf16 v[82:85], v[122:125], v[210:213], v[82:85]
	v_mfma_f32_16x16x32_bf16 v[74:77], v[130:133], v[210:213], v[74:77]
	v_mfma_f32_16x16x32_bf16 v[158:161], v[126:129], v[188:191], v[158:161]
	v_mfma_f32_16x16x32_bf16 v[146:149], v[134:137], v[188:191], v[146:149]
	v_mfma_f32_16x16x32_bf16 v[114:117], v[126:129], v[196:199], v[114:117]
	v_mfma_f32_16x16x32_bf16 v[106:109], v[134:137], v[196:199], v[106:109]
	v_mfma_f32_16x16x32_bf16 v[94:97], v[126:129], v[206:209], v[94:97]
	v_mfma_f32_16x16x32_bf16 v[90:93], v[134:137], v[206:209], v[90:93]
	v_mfma_f32_16x16x32_bf16 v[82:85], v[126:129], v[214:217], v[82:85]
	v_mfma_f32_16x16x32_bf16 v[74:77], v[134:137], v[214:217], v[74:77]
	s_setprio 0
	s_setprio 1
	v_mfma_f32_16x16x32_bf16 v[118:121], v[138:141], v[178:181], v[118:121]
	v_mfma_f32_16x16x32_bf16 v[110:113], v[150:153], v[178:181], v[110:113]
	v_mfma_f32_16x16x32_bf16 v[102:105], v[138:141], v[192:195], v[102:105]
	v_mfma_f32_16x16x32_bf16 v[98:101], v[150:153], v[192:195], v[98:101]
	v_mfma_f32_16x16x32_bf16 v[86:89], v[138:141], v[200:203], v[86:89]
	v_mfma_f32_16x16x32_bf16 v[78:81], v[150:153], v[200:203], v[78:81]
	v_mfma_f32_16x16x32_bf16 v[70:73], v[138:141], v[210:213], v[70:73]
	v_mfma_f32_16x16x32_bf16 v[66:69], v[150:153], v[210:213], v[66:69]
	v_mfma_f32_16x16x32_bf16 v[118:121], v[142:145], v[188:191], v[118:121]
	v_mfma_f32_16x16x32_bf16 v[110:113], v[154:157], v[188:191], v[110:113]
	v_mfma_f32_16x16x32_bf16 v[102:105], v[142:145], v[196:199], v[102:105]
	v_mfma_f32_16x16x32_bf16 v[98:101], v[154:157], v[196:199], v[98:101]
	v_mfma_f32_16x16x32_bf16 v[86:89], v[142:145], v[206:209], v[86:89]
	v_mfma_f32_16x16x32_bf16 v[78:81], v[154:157], v[206:209], v[78:81]
	v_mfma_f32_16x16x32_bf16 v[70:73], v[142:145], v[214:217], v[70:73]
	s_barrier
; #define PG8_STAGE(bufoff, gbase, voff) do { _Pragma("unroll") for (int _i = 0; _i < 2; ++_i) \
;         __builtin_amdgcn_global_load_lds((const unsigned*)((const char*)(gbase) + (voff)[_i]), (PG8_LAS unsigned*)(lds + (bufoff) + ldsw + _i * 8192), 16, 0, 0); } while (0)
; #define PG8_LDA(dst, b, h) do { _Pragma("unroll") for (int m = 0; m < 4; ++m) _Pragma("unroll") for (int k = 0; k < 2; ++k) dst[m][k] = *(const PG8_LAS bf16x8*)(lds + PG8_SA(b, h) + aoff + m * 2048 + k * 1024); } while (0)
; #define PG8_MMA(ai, bj, At, Bt) do { __builtin_amdgcn_s_setprio(1); _Pragma("unroll") for (int m = 0; m < 4; ++m) _Pragma("unroll") for (int n = 0; n < 2; ++n) _Pragma("unroll") for (int k = 0; k < 2; ++k) \
;         acc[ai][bj][m][n] = __builtin_amdgcn_mfma_f32_16x16x32_bf16(Bt[n][k], At[m][k], acc[ai][bj][m][n], 0, 0, 0); __builtin_amdgcn_s_setprio(0); } while (0)
; #define PG8_WAIT_V(n) asm volatile("s_waitcnt vmcnt(" #n ")" ::: "memory")
; #define PG8_WAIT_L(n) asm volatile("s_waitcnt lgkmcnt(" #n ")" ::: "memory")
; #define PG8_BAR __builtin_amdgcn_s_barrier()
; #define PG8_SCHED __builtin_amdgcn_sched_barrier(0)
; template <class Epi, class Sched, bool ALIGN_EPI = false, bool SP2 = false>
; __device__ __forceinline__ void gemm_phase(PG8_LAS unsigned char* lds, const Gemm g, const Sched& S, const Epi& E) {
;     ...
;             PG8_WAIT_V(8); PG8_WAIT_L(0); PG8_BAR; PG8_MMA(0, 0, At, B0); PG8_MMA(0, 1, At, B1); PG8_BAR; PG8_SCHED;
;             PG8_LDA(At, 1, 1); PG8_STAGE(PG8_SB(1, 0), b3, voffB); PG8_STAGE(PG8_SB(1, 1), b3 + hstep, voffB); PG8_STAGE(PG8_SA(1, 0), a3, voffA);
;             PG8_WAIT_V(8); PG8_WAIT_L(0); PG8_BAR; PG8_MMA(1, 0, At, B0); PG8_MMA(1, 1, At, B1); PG8_BAR; PG8_SCHED;
	v_mfma_f32_16x16x32_bf16 v[66:69], v[154:157], v[214:217], v[66:69]
	s_setprio 0
	s_add_i32 s30, s65, s33
	v_lshl_add_u64 v[218:219], v[218:219], 0, s[10:11]
	s_mov_b32 m0, s30
	ds_read_b128 v[178:181], v186 offset:49152
	ds_read_b128 v[188:191], v186 offset:50176
	ds_read_b128 v[192:195], v186 offset:51200
	ds_read_b128 v[196:199], v186 offset:52224
	ds_read_b128 v[200:203], v186 offset:53248
	ds_read_b128 v[206:209], v186 offset:54272
	ds_read_b128 v[210:213], v186 offset:55296
	ds_read_b128 v[214:217], v186 offset:56320
	global_load_lds_dwordx4 v[218:219], off
	s_add_i32 m0, s30, 0x2000
	s_add_u32 s30, s38, 0x40080
	v_lshl_add_u64 v[218:219], v[220:221], 0, s[10:11]
	s_addc_u32 s31, s39, 0
	s_add_i32 s38, s66, s33
	global_load_lds_dwordx4 v[218:219], off
	v_lshl_add_u64 v[218:219], s[30:31], 0, v[164:165]
	s_mov_b32 m0, s38
	s_nop 0
	global_load_lds_dwordx4 v[218:219], off
	v_lshl_add_u64 v[218:219], s[30:31], 0, v[168:169]
	s_add_i32 m0, s38, 0x2000
	s_nop 0
	global_load_lds_dwordx4 v[218:219], off
	v_lshl_add_u64 v[218:219], v[222:223], 0, s[10:11]
	s_mov_b32 m0, s52
	s_nop 0
	global_load_lds_dwordx4 v[218:219], off
	v_lshl_add_u64 v[218:219], v[224:225], 0, s[10:11]
	s_mov_b32 m0, s53
	s_nop 0
	global_load_lds_dwordx4 v[218:219], off
	s_waitcnt vmcnt(8)
	s_waitcnt lgkmcnt(0)
	s_barrier
	s_setprio 1
	s_waitcnt lgkmcnt(0)
	v_mfma_f32_16x16x32_bf16 v[62:65], v[122:125], v[178:181], v[62:65]
	v_mfma_f32_16x16x32_bf16 v[58:61], v[130:133], v[178:181], v[58:61]
	v_mfma_f32_16x16x32_bf16 v[50:53], v[122:125], v[192:195], v[50:53]
	v_mfma_f32_16x16x32_bf16 v[42:45], v[130:133], v[192:195], v[42:45]
	v_mfma_f32_16x16x32_bf16 v[30:33], v[122:125], v[200:203], v[30:33]
	v_mfma_f32_16x16x32_bf16 v[26:29], v[130:133], v[200:203], v[26:29]
	v_mfma_f32_16x16x32_bf16 v[18:21], v[122:125], v[210:213], v[18:21]
	v_mfma_f32_16x16x32_bf16 v[10:13], v[130:133], v[210:213], v[10:13]
	v_mfma_f32_16x16x32_bf16 v[62:65], v[126:129], v[188:191], v[62:65]
	v_mfma_f32_16x16x32_bf16 v[58:61], v[134:137], v[188:191], v[58:61]
	v_mfma_f32_16x16x32_bf16 v[50:53], v[126:129], v[196:199], v[50:53]
	v_mfma_f32_16x16x32_bf16 v[42:45], v[134:137], v[196:199], v[42:45]
	v_mfma_f32_16x16x32_bf16 v[30:33], v[126:129], v[206:209], v[30:33]
	v_mfma_f32_16x16x32_bf16 v[26:29], v[134:137], v[206:209], v[26:29]
	v_mfma_f32_16x16x32_bf16 v[18:21], v[126:129], v[214:217], v[18:21]
	v_mfma_f32_16x16x32_bf16 v[10:13], v[134:137], v[214:217], v[10:13]
	s_setprio 0
	s_setprio 1
	v_mfma_f32_16x16x32_bf16 v[54:57], v[138:141], v[178:181], v[54:57]
	v_mfma_f32_16x16x32_bf16 v[46:49], v[150:153], v[178:181], v[46:49]
	v_mfma_f32_16x16x32_bf16 v[38:41], v[138:141], v[192:195], v[38:41]
	v_mfma_f32_16x16x32_bf16 v[34:37], v[150:153], v[192:195], v[34:37]
	v_mfma_f32_16x16x32_bf16 v[22:25], v[138:141], v[200:203], v[22:25]
	v_mfma_f32_16x16x32_bf16 v[14:17], v[150:153], v[200:203], v[14:17]
	v_mfma_f32_16x16x32_bf16 v[6:9], v[138:141], v[210:213], v[6:9]
	v_mfma_f32_16x16x32_bf16 v[2:5], v[150:153], v[210:213], v[2:5]
	v_mfma_f32_16x16x32_bf16 v[54:57], v[142:145], v[188:191], v[54:57]
	v_mfma_f32_16x16x32_bf16 v[46:49], v[154:157], v[188:191], v[46:49]
	v_mfma_f32_16x16x32_bf16 v[38:41], v[142:145], v[196:199], v[38:41]
	v_mfma_f32_16x16x32_bf16 v[34:37], v[154:157], v[196:199], v[34:37]
	v_mfma_f32_16x16x32_bf16 v[22:25], v[142:145], v[206:209], v[22:25]
	v_mfma_f32_16x16x32_bf16 v[14:17], v[154:157], v[206:209], v[14:17]
	v_mfma_f32_16x16x32_bf16 v[6:9], v[142:145], v[214:217], v[6:9]
	s_barrier
	v_mfma_f32_16x16x32_bf16 v[2:5], v[154:157], v[214:217], v[2:5]
	s_setprio 0
	s_add_i32 s64, s64, 2
	s_add_u32 s26, s26, 0x100
	s_addc_u32 s27, s27, 0
	s_add_u32 s62, s62, 0x100
	s_addc_u32 s63, s63, 0
	s_cmp_gt_u32 s64, 13
	s_cbranch_scc0 .LBB0_752
	s_and_b64 vcc, exec, s[12:13]
	s_cbranch_vccz .LBB0_755
	s_barrier

; #define PG8_STAGE(bufoff, gbase, voff) do { _Pragma("unroll") for (int _i = 0; _i < 2; ++_i) \
;         __builtin_amdgcn_global_load_lds((const unsigned*)((const char*)(gbase) + (voff)[_i]), (PG8_LAS unsigned*)(lds + (bufoff) + ldsw + _i * 8192), 16, 0, 0); } while (0)
; #define PG8_LDA(dst, b, h) do { _Pragma("unroll") for (int m = 0; m < 4; ++m) _Pragma("unroll") for (int k = 0; k < 2; ++k) dst[m][k] = *(const PG8_LAS bf16x8*)(lds + PG8_SA(b, h) + aoff + m * 2048 + k * 1024); } while (0)
; #define PG8_LDB(dst, b, h) do { _Pragma("unroll") for (int n = 0; n < 2; ++n) _Pragma("unroll") for (int k = 0; k < 2; ++k) dst[n][k] = *(const PG8_LAS bf16x8*)(lds + PG8_SB(b, h) + boff + n * 2048 + k * 1024); } while (0)
; #define PG8_MMA(ai, bj, At, Bt) do { __builtin_amdgcn_s_setprio(1); _Pragma("unroll") for (int m = 0; m < 4; ++m) _Pragma("unroll") for (int n = 0; n < 2; ++n) _Pragma("unroll") for (int k = 0; k < 2; ++k) \
;         acc[ai][bj][m][n] = __builtin_amdgcn_mfma_f32_16x16x32_bf16(Bt[n][k], At[m][k], acc[ai][bj][m][n], 0, 0, 0); __builtin_amdgcn_s_setprio(0); } while (0)
; #define PG8_WAIT_V(n) asm volatile("s_waitcnt vmcnt(" #n ")" ::: "memory")
; #define PG8_WAIT_L(n) asm volatile("s_waitcnt lgkmcnt(" #n ")" ::: "memory")
; #define PG8_BAR __builtin_amdgcn_s_barrier()
; #define PG8_SCHED __builtin_amdgcn_sched_barrier(0)
; template <class Epi, class Sched, bool ALIGN_EPI = false, bool SP2 = false>
; __device__ __forceinline__ void gemm_phase(PG8_LAS unsigned char* lds, const Gemm g, const Sched& S, const Epi& E) {
;     ...
;             PG8_LDB(B0, 0, 0); PG8_LDB(B1, 0, 1); PG8_SCHED; PG8_LDA(At, 0, 0); PG8_STAGE(PG8_SA(1, 1), a1 + hstep, voffA);
;             PG8_WAIT_V(8); PG8_WAIT_L(0); PG8_BAR; PG8_MMA(0, 0, At, B0); PG8_MMA(0, 1, At, B1); PG8_BAR; PG8_SCHED;
;             PG8_LDA(At, 0, 1); PG8_STAGE(PG8_SB(0, 0), b2, voffB); PG8_STAGE(PG8_SB(0, 1), b2 + hstep, voffB); PG8_STAGE(PG8_SA(0, 0), a2, voffA);
;             PG8_WAIT_V(8); PG8_WAIT_L(0); PG8_BAR; PG8_MMA(1, 0, At, B0); PG8_MMA(1, 1, At, B1); PG8_BAR; PG8_SCHED;
.LBB0_901:
	ds_read_b128 v[154:157], v150
	ds_read_b128 v[158:161], v150 offset:1024
	ds_read_b128 v[162:165], v150 offset:2048
	ds_read_b128 v[166:169], v150 offset:3072
	ds_read_b128 v[170:173], v151
	ds_read_b128 v[174:177], v151 offset:1024
	ds_read_b128 v[178:181], v151 offset:2048
	ds_read_b128 v[182:185], v151 offset:3072
	s_add_u32 s30, s44, 0xfffc0080
	s_addc_u32 s31, s45, -1
	s_cmp_eq_u32 s75, 12
	s_cselect_b32 s53, s25, s31
	s_cselect_b32 s52, s71, s30
	s_cselect_b32 s51, s23, s74
	s_cselect_b32 s50, s72, s73
	v_lshl_add_u64 v[146:147], s[44:45], 0, v[138:139]
	s_add_i32 m0, s41, 0xc000
	ds_read_b128 v[186:189], v152
	ds_read_b128 v[190:193], v152 offset:1024
	ds_read_b128 v[194:197], v152 offset:2048
	ds_read_b128 v[198:201], v152 offset:3072
	ds_read_b128 v[206:209], v152 offset:4096
	ds_read_b128 v[210:213], v152 offset:5120
	ds_read_b128 v[214:217], v152 offset:6144
	ds_read_b128 v[218:221], v152 offset:7168
	global_load_lds_dwordx4 v[146:147], off
	v_lshl_add_u64 v[146:147], s[44:45], 0, v[140:141]
	s_add_i32 m0, s41, 0xe000
	s_nop 0
	global_load_lds_dwordx4 v[146:147], off
	s_waitcnt vmcnt(8)
	s_waitcnt lgkmcnt(0)
	s_barrier
	s_setprio 1
	s_waitcnt lgkmcnt(0)
	v_mfma_f32_16x16x32_bf16 v[126:129], v[154:157], v[186:189], v[126:129]
	v_mfma_f32_16x16x32_bf16 v[122:125], v[162:165], v[186:189], v[122:125]
	v_mfma_f32_16x16x32_bf16 v[114:117], v[154:157], v[194:197], v[114:117]
	v_mfma_f32_16x16x32_bf16 v[106:109], v[162:165], v[194:197], v[106:109]
	v_mfma_f32_16x16x32_bf16 v[98:101], v[154:157], v[206:209], v[98:101]
	v_mfma_f32_16x16x32_bf16 v[90:93], v[162:165], v[206:209], v[90:93]
	v_mfma_f32_16x16x32_bf16 v[82:85], v[154:157], v[214:217], v[82:85]
	v_mfma_f32_16x16x32_bf16 v[74:77], v[162:165], v[214:217], v[74:77]
	v_mfma_f32_16x16x32_bf16 v[126:129], v[158:161], v[190:193], v[126:129]
	v_mfma_f32_16x16x32_bf16 v[122:125], v[166:169], v[190:193], v[122:125]
	v_mfma_f32_16x16x32_bf16 v[114:117], v[158:161], v[198:201], v[114:117]
	v_mfma_f32_16x16x32_bf16 v[106:109], v[166:169], v[198:201], v[106:109]
	v_mfma_f32_16x16x32_bf16 v[98:101], v[158:161], v[210:213], v[98:101]
	v_mfma_f32_16x16x32_bf16 v[90:93], v[166:169], v[210:213], v[90:93]
	v_mfma_f32_16x16x32_bf16 v[82:85], v[158:161], v[218:221], v[82:85]
	v_mfma_f32_16x16x32_bf16 v[74:77], v[166:169], v[218:221], v[74:77]
	s_setprio 0
	s_setprio 1
	v_mfma_f32_16x16x32_bf16 v[118:121], v[170:173], v[186:189], v[118:121]
	v_mfma_f32_16x16x32_bf16 v[110:113], v[178:181], v[186:189], v[110:113]
	v_mfma_f32_16x16x32_bf16 v[102:105], v[170:173], v[194:197], v[102:105]
	v_mfma_f32_16x16x32_bf16 v[94:97], v[178:181], v[194:197], v[94:97]
	v_mfma_f32_16x16x32_bf16 v[86:89], v[170:173], v[206:209], v[86:89]
	v_mfma_f32_16x16x32_bf16 v[78:81], v[178:181], v[206:209], v[78:81]
	v_mfma_f32_16x16x32_bf16 v[70:73], v[170:173], v[214:217], v[70:73]
	v_mfma_f32_16x16x32_bf16 v[66:69], v[178:181], v[214:217], v[66:69]
	v_mfma_f32_16x16x32_bf16 v[118:121], v[174:177], v[190:193], v[118:121]
	v_mfma_f32_16x16x32_bf16 v[110:113], v[182:185], v[190:193], v[110:113]
	v_mfma_f32_16x16x32_bf16 v[102:105], v[174:177], v[198:201], v[102:105]
	v_mfma_f32_16x16x32_bf16 v[94:97], v[182:185], v[198:201], v[94:97]
	v_mfma_f32_16x16x32_bf16 v[86:89], v[174:177], v[210:213], v[86:89]
	v_mfma_f32_16x16x32_bf16 v[78:81], v[182:185], v[210:213], v[78:81]
	v_mfma_f32_16x16x32_bf16 v[70:73], v[174:177], v[218:221], v[70:73]
	s_barrier
	v_mfma_f32_16x16x32_bf16 v[66:69], v[182:185], v[218:221], v[66:69]
	s_setprio 0
	s_add_i32 s30, s64, s56
	v_lshl_add_u64 v[146:147], s[50:51], 0, v[132:133]
	s_mov_b32 m0, s30
	ds_read_b128 v[186:189], v152 offset:16384
	ds_read_b128 v[190:193], v152 offset:17408
	ds_read_b128 v[194:197], v152 offset:18432
	ds_read_b128 v[198:201], v152 offset:19456
	ds_read_b128 v[206:209], v152 offset:20480
	ds_read_b128 v[210:213], v152 offset:21504
	ds_read_b128 v[214:217], v152 offset:22528
	ds_read_b128 v[218:221], v152 offset:23552
	global_load_lds_dwordx4 v[146:147], off
	s_add_i32 m0, s30, 0x2000
	s_add_u32 s30, s50, 0x40000
	v_lshl_add_u64 v[202:203], s[50:51], 0, v[136:137]
	s_addc_u32 s31, s51, 0
	s_add_i32 s76, s65, s56
	global_load_lds_dwordx4 v[202:203], off
	v_lshl_add_u64 v[222:223], s[30:31], 0, v[132:133]
	s_mov_b32 m0, s76
	v_lshl_add_u64 v[224:225], s[52:53], 0, v[134:135]
	global_load_lds_dwordx4 v[222:223], off
	v_lshl_add_u64 v[222:223], s[30:31], 0, v[136:137]
	s_add_i32 m0, s76, 0x2000
	s_nop 0
	global_load_lds_dwordx4 v[222:223], off
	v_lshl_add_u64 v[222:223], s[52:53], 0, v[130:131]
	s_mov_b32 m0, s41
	s_nop 0
	global_load_lds_dwordx4 v[222:223], off
	s_mov_b32 m0, s57
	s_nop 0
	global_load_lds_dwordx4 v[224:225], off
	s_waitcnt vmcnt(8)
	s_waitcnt lgkmcnt(0)
	s_barrier
; #define PG8_STAGE(bufoff, gbase, voff) do { _Pragma("unroll") for (int _i = 0; _i < 2; ++_i) \
;         __builtin_amdgcn_global_load_lds((const unsigned*)((const char*)(gbase) + (voff)[_i]), (PG8_LAS unsigned*)(lds + (bufoff) + ldsw + _i * 8192), 16, 0, 0); } while (0)
; #define PG8_LDA(dst, b, h) do { _Pragma("unroll") for (int m = 0; m < 4; ++m) _Pragma("unroll") for (int k = 0; k < 2; ++k) dst[m][k] = *(const PG8_LAS bf16x8*)(lds + PG8_SA(b, h) + aoff + m * 2048 + k * 1024); } while (0)
; #define PG8_LDB(dst, b, h) do { _Pragma("unroll") for (int n = 0; n < 2; ++n) _Pragma("unroll") for (int k = 0; k < 2; ++k) dst[n][k] = *(const PG8_LAS bf16x8*)(lds + PG8_SB(b, h) + boff + n * 2048 + k * 1024); } while (0)
; #define PG8_MMA(ai, bj, At, Bt) do { __builtin_amdgcn_s_setprio(1); _Pragma("unroll") for (int m = 0; m < 4; ++m) _Pragma("unroll") for (int n = 0; n < 2; ++n) _Pragma("unroll") for (int k = 0; k < 2; ++k) \
;         acc[ai][bj][m][n] = __builtin_amdgcn_mfma_f32_16x16x32_bf16(Bt[n][k], At[m][k], acc[ai][bj][m][n], 0, 0, 0); __builtin_amdgcn_s_setprio(0); } while (0)
; #define PG8_WAIT_V(n) asm volatile("s_waitcnt vmcnt(" #n ")" ::: "memory")
; #define PG8_WAIT_L(n) asm volatile("s_waitcnt lgkmcnt(" #n ")" ::: "memory")
; #define PG8_BAR __builtin_amdgcn_s_barrier()
; #define PG8_SCHED __builtin_amdgcn_sched_barrier(0)
; template <class Epi, class Sched, bool ALIGN_EPI = false, bool SP2 = false>
; __device__ __forceinline__ void gemm_phase(PG8_LAS unsigned char* lds, const Gemm g, const Sched& S, const Epi& E) {
;     ...
;             PG8_WAIT_V(8); PG8_WAIT_L(0); PG8_BAR; PG8_MMA(1, 0, At, B0); PG8_MMA(1, 1, At, B1); PG8_BAR; PG8_SCHED;
;             PG8_LDB(B0, 1, 0); PG8_LDB(B1, 1, 1); PG8_SCHED; PG8_LDA(At, 1, 0); PG8_STAGE(PG8_SA(0, 1), a2 + hstep, voffA);
;             PG8_WAIT_V(8); PG8_WAIT_L(0); PG8_BAR; PG8_MMA(0, 0, At, B0); PG8_MMA(0, 1, At, B1); PG8_BAR; PG8_SCHED;
	s_setprio 1
	s_waitcnt lgkmcnt(0)
	v_mfma_f32_16x16x32_bf16 v[62:65], v[154:157], v[186:189], v[62:65]
	v_mfma_f32_16x16x32_bf16 v[58:61], v[162:165], v[186:189], v[58:61]
	v_mfma_f32_16x16x32_bf16 v[50:53], v[154:157], v[194:197], v[50:53]
	v_mfma_f32_16x16x32_bf16 v[42:45], v[162:165], v[194:197], v[42:45]
	v_mfma_f32_16x16x32_bf16 v[34:37], v[154:157], v[206:209], v[34:37]
	v_mfma_f32_16x16x32_bf16 v[26:29], v[162:165], v[206:209], v[26:29]
	v_mfma_f32_16x16x32_bf16 v[18:21], v[154:157], v[214:217], v[18:21]
	v_mfma_f32_16x16x32_bf16 v[10:13], v[162:165], v[214:217], v[10:13]
	v_mfma_f32_16x16x32_bf16 v[62:65], v[158:161], v[190:193], v[62:65]
	v_mfma_f32_16x16x32_bf16 v[58:61], v[166:169], v[190:193], v[58:61]
	v_mfma_f32_16x16x32_bf16 v[50:53], v[158:161], v[198:201], v[50:53]
	v_mfma_f32_16x16x32_bf16 v[42:45], v[166:169], v[198:201], v[42:45]
	v_mfma_f32_16x16x32_bf16 v[34:37], v[158:161], v[210:213], v[34:37]
	v_mfma_f32_16x16x32_bf16 v[26:29], v[166:169], v[210:213], v[26:29]
	v_mfma_f32_16x16x32_bf16 v[18:21], v[158:161], v[218:221], v[18:21]
	v_mfma_f32_16x16x32_bf16 v[10:13], v[166:169], v[218:221], v[10:13]
	s_setprio 0
	s_setprio 1
	v_mfma_f32_16x16x32_bf16 v[54:57], v[170:173], v[186:189], v[54:57]
	v_mfma_f32_16x16x32_bf16 v[46:49], v[178:181], v[186:189], v[46:49]
	v_mfma_f32_16x16x32_bf16 v[38:41], v[170:173], v[194:197], v[38:41]
	v_mfma_f32_16x16x32_bf16 v[30:33], v[178:181], v[194:197], v[30:33]
	v_mfma_f32_16x16x32_bf16 v[22:25], v[170:173], v[206:209], v[22:25]
	v_mfma_f32_16x16x32_bf16 v[14:17], v[178:181], v[206:209], v[14:17]
	v_mfma_f32_16x16x32_bf16 v[6:9], v[170:173], v[214:217], v[6:9]
	v_mfma_f32_16x16x32_bf16 v[2:5], v[178:181], v[214:217], v[2:5]
	v_mfma_f32_16x16x32_bf16 v[54:57], v[174:177], v[190:193], v[54:57]
	v_mfma_f32_16x16x32_bf16 v[46:49], v[182:185], v[190:193], v[46:49]
	v_mfma_f32_16x16x32_bf16 v[38:41], v[174:177], v[198:201], v[38:41]
	v_mfma_f32_16x16x32_bf16 v[30:33], v[182:185], v[198:201], v[30:33]
	v_mfma_f32_16x16x32_bf16 v[22:25], v[174:177], v[210:213], v[22:25]
	v_mfma_f32_16x16x32_bf16 v[14:17], v[182:185], v[210:213], v[14:17]
	v_mfma_f32_16x16x32_bf16 v[6:9], v[174:177], v[218:221], v[6:9]
	s_barrier
	v_mfma_f32_16x16x32_bf16 v[2:5], v[182:185], v[218:221], v[2:5]
	s_setprio 0
	s_add_i32 s76, 0, 0x18000
	v_add_u32_e32 v153, s76, v148
	s_add_i32 s77, 0, 0x1c000
	ds_read_b128 v[154:157], v153
	ds_read_b128 v[158:161], v153 offset:1024
	ds_read_b128 v[162:165], v153 offset:2048
	ds_read_b128 v[166:169], v153 offset:3072
	v_add_u32_e32 v153, s77, v148
	ds_read_b128 v[170:173], v153
	ds_read_b128 v[174:177], v153 offset:1024
	ds_read_b128 v[178:181], v153 offset:2048
	ds_read_b128 v[182:185], v153 offset:3072
	s_add_u32 s30, s52, 0x40000
	s_addc_u32 s31, s53, 0
	s_mov_b32 m0, s58
	v_lshl_add_u64 v[226:227], s[30:31], 0, v[130:131]
	ds_read_b128 v[186:189], v152 offset:32768
	ds_read_b128 v[190:193], v152 offset:33792
	ds_read_b128 v[194:197], v152 offset:34816
	ds_read_b128 v[198:201], v152 offset:35840
	ds_read_b128 v[206:209], v152 offset:36864
	ds_read_b128 v[210:213], v152 offset:37888
	ds_read_b128 v[214:217], v152 offset:38912
	ds_read_b128 v[218:221], v152 offset:39936
	global_load_lds_dwordx4 v[226:227], off
	v_lshl_add_u64 v[226:227], s[30:31], 0, v[134:135]
	s_mov_b32 m0, s59
	s_nop 0
	global_load_lds_dwordx4 v[226:227], off
	s_waitcnt vmcnt(8)
	s_waitcnt lgkmcnt(0)
	s_barrier
	s_setprio 1
	s_waitcnt lgkmcnt(0)
	v_mfma_f32_16x16x32_bf16 v[126:129], v[154:157], v[186:189], v[126:129]
	v_mfma_f32_16x16x32_bf16 v[122:125], v[162:165], v[186:189], v[122:125]
	v_mfma_f32_16x16x32_bf16 v[114:117], v[154:157], v[194:197], v[114:117]
	v_mfma_f32_16x16x32_bf16 v[106:109], v[162:165], v[194:197], v[106:109]
	v_mfma_f32_16x16x32_bf16 v[98:101], v[154:157], v[206:209], v[98:101]
	v_mfma_f32_16x16x32_bf16 v[90:93], v[162:165], v[206:209], v[90:93]
	v_mfma_f32_16x16x32_bf16 v[82:85], v[154:157], v[214:217], v[82:85]
	v_mfma_f32_16x16x32_bf16 v[74:77], v[162:165], v[214:217], v[74:77]
	v_mfma_f32_16x16x32_bf16 v[126:129], v[158:161], v[190:193], v[126:129]
	v_mfma_f32_16x16x32_bf16 v[122:125], v[166:169], v[190:193], v[122:125]
	v_mfma_f32_16x16x32_bf16 v[114:117], v[158:161], v[198:201], v[114:117]
	v_mfma_f32_16x16x32_bf16 v[106:109], v[166:169], v[198:201], v[106:109]
	v_mfma_f32_16x16x32_bf16 v[98:101], v[158:161], v[210:213], v[98:101]
	v_mfma_f32_16x16x32_bf16 v[90:93], v[166:169], v[210:213], v[90:93]
	v_mfma_f32_16x16x32_bf16 v[82:85], v[158:161], v[218:221], v[82:85]
	v_mfma_f32_16x16x32_bf16 v[74:77], v[166:169], v[218:221], v[74:77]
	s_setprio 0
	s_setprio 1
	v_mfma_f32_16x16x32_bf16 v[118:121], v[170:173], v[186:189], v[118:121]
	v_mfma_f32_16x16x32_bf16 v[110:113], v[178:181], v[186:189], v[110:113]
	v_mfma_f32_16x16x32_bf16 v[102:105], v[170:173], v[194:197], v[102:105]
	v_mfma_f32_16x16x32_bf16 v[94:97], v[178:181], v[194:197], v[94:97]
	v_mfma_f32_16x16x32_bf16 v[86:89], v[170:173], v[206:209], v[86:89]
	v_mfma_f32_16x16x32_bf16 v[78:81], v[178:181], v[206:209], v[78:81]
	v_mfma_f32_16x16x32_bf16 v[70:73], v[170:173], v[214:217], v[70:73]
	v_mfma_f32_16x16x32_bf16 v[66:69], v[178:181], v[214:217], v[66:69]
	v_mfma_f32_16x16x32_bf16 v[118:121], v[174:177], v[190:193], v[118:121]
	v_mfma_f32_16x16x32_bf16 v[110:113], v[182:185], v[190:193], v[110:113]
	v_mfma_f32_16x16x32_bf16 v[102:105], v[174:177], v[198:201], v[102:105]
	v_mfma_f32_16x16x32_bf16 v[94:97], v[182:185], v[198:201], v[94:97]
	v_mfma_f32_16x16x32_bf16 v[86:89], v[174:177], v[210:213], v[86:89]
	v_mfma_f32_16x16x32_bf16 v[78:81], v[182:185], v[210:213], v[78:81]
	v_mfma_f32_16x16x32_bf16 v[70:73], v[174:177], v[218:221], v[70:73]
	s_barrier
; #define PG8_STAGE(bufoff, gbase, voff) do { _Pragma("unroll") for (int _i = 0; _i < 2; ++_i) \
;         __builtin_amdgcn_global_load_lds((const unsigned*)((const char*)(gbase) + (voff)[_i]), (PG8_LAS unsigned*)(lds + (bufoff) + ldsw + _i * 8192), 16, 0, 0); } while (0)
; #define PG8_LDA(dst, b, h) do { _Pragma("unroll") for (int m = 0; m < 4; ++m) _Pragma("unroll") for (int k = 0; k < 2; ++k) dst[m][k] = *(const PG8_LAS bf16x8*)(lds + PG8_SA(b, h) + aoff + m * 2048 + k * 1024); } while (0)
; #define PG8_MMA(ai, bj, At, Bt) do { __builtin_amdgcn_s_setprio(1); _Pragma("unroll") for (int m = 0; m < 4; ++m) _Pragma("unroll") for (int n = 0; n < 2; ++n) _Pragma("unroll") for (int k = 0; k < 2; ++k) \
;         acc[ai][bj][m][n] = __builtin_amdgcn_mfma_f32_16x16x32_bf16(Bt[n][k], At[m][k], acc[ai][bj][m][n], 0, 0, 0); __builtin_amdgcn_s_setprio(0); } while (0)
; #define PG8_WAIT_V(n) asm volatile("s_waitcnt vmcnt(" #n ")" ::: "memory")
; #define PG8_WAIT_L(n) asm volatile("s_waitcnt lgkmcnt(" #n ")" ::: "memory")
; #define PG8_BAR __builtin_amdgcn_s_barrier()
; #define PG8_SCHED __builtin_amdgcn_sched_barrier(0)
; template <class Epi, class Sched, bool ALIGN_EPI = false, bool SP2 = false>
; __device__ __forceinline__ void gemm_phase(PG8_LAS unsigned char* lds, const Gemm g, const Sched& S, const Epi& E) {
;     ...
;             PG8_WAIT_V(8); PG8_WAIT_L(0); PG8_BAR; PG8_MMA(0, 0, At, B0); PG8_MMA(0, 1, At, B1); PG8_BAR; PG8_SCHED;
;             PG8_LDA(At, 1, 1); PG8_STAGE(PG8_SB(1, 0), b3, voffB); PG8_STAGE(PG8_SB(1, 1), b3 + hstep, voffB); PG8_STAGE(PG8_SA(1, 0), a3, voffA);
;             PG8_WAIT_V(8); PG8_WAIT_L(0); PG8_BAR; PG8_MMA(1, 0, At, B0); PG8_MMA(1, 1, At, B1); PG8_BAR; PG8_SCHED;
	v_mfma_f32_16x16x32_bf16 v[66:69], v[182:185], v[218:221], v[66:69]
	s_setprio 0
	s_add_i32 s30, s76, s56
	v_lshl_add_u64 v[146:147], v[146:147], 0, s[10:11]
	s_mov_b32 m0, s30
	ds_read_b128 v[186:189], v152 offset:49152
	ds_read_b128 v[190:193], v152 offset:50176
	ds_read_b128 v[194:197], v152 offset:51200
	ds_read_b128 v[198:201], v152 offset:52224
	ds_read_b128 v[206:209], v152 offset:53248
	ds_read_b128 v[210:213], v152 offset:54272
	ds_read_b128 v[214:217], v152 offset:55296
	ds_read_b128 v[218:221], v152 offset:56320
	global_load_lds_dwordx4 v[146:147], off
	s_add_i32 m0, s30, 0x2000
	s_add_u32 s30, s50, 0x40080
	v_lshl_add_u64 v[146:147], v[202:203], 0, s[10:11]
	s_addc_u32 s31, s51, 0
	s_add_i32 s50, s77, s56
	global_load_lds_dwordx4 v[146:147], off
	v_lshl_add_u64 v[146:147], s[30:31], 0, v[132:133]
	s_mov_b32 m0, s50
	s_nop 0
	global_load_lds_dwordx4 v[146:147], off
	v_lshl_add_u64 v[146:147], s[30:31], 0, v[136:137]
	s_add_i32 m0, s50, 0x2000
	s_nop 0
	global_load_lds_dwordx4 v[146:147], off
	v_lshl_add_u64 v[146:147], v[222:223], 0, s[10:11]
	s_mov_b32 m0, s61
	s_nop 0
	global_load_lds_dwordx4 v[146:147], off
	v_lshl_add_u64 v[146:147], v[224:225], 0, s[10:11]
	s_mov_b32 m0, s62
	s_nop 0
	global_load_lds_dwordx4 v[146:147], off
	s_waitcnt vmcnt(8)
	s_waitcnt lgkmcnt(0)
	s_barrier
	s_setprio 1
	s_waitcnt lgkmcnt(0)
	v_mfma_f32_16x16x32_bf16 v[62:65], v[154:157], v[186:189], v[62:65]
	v_mfma_f32_16x16x32_bf16 v[58:61], v[162:165], v[186:189], v[58:61]
	v_mfma_f32_16x16x32_bf16 v[50:53], v[154:157], v[194:197], v[50:53]
	v_mfma_f32_16x16x32_bf16 v[42:45], v[162:165], v[194:197], v[42:45]
	v_mfma_f32_16x16x32_bf16 v[34:37], v[154:157], v[206:209], v[34:37]
	v_mfma_f32_16x16x32_bf16 v[26:29], v[162:165], v[206:209], v[26:29]
	v_mfma_f32_16x16x32_bf16 v[18:21], v[154:157], v[214:217], v[18:21]
	v_mfma_f32_16x16x32_bf16 v[10:13], v[162:165], v[214:217], v[10:13]
	v_mfma_f32_16x16x32_bf16 v[62:65], v[158:161], v[190:193], v[62:65]
	v_mfma_f32_16x16x32_bf16 v[58:61], v[166:169], v[190:193], v[58:61]
	v_mfma_f32_16x16x32_bf16 v[50:53], v[158:161], v[198:201], v[50:53]
	v_mfma_f32_16x16x32_bf16 v[42:45], v[166:169], v[198:201], v[42:45]
	v_mfma_f32_16x16x32_bf16 v[34:37], v[158:161], v[210:213], v[34:37]
	v_mfma_f32_16x16x32_bf16 v[26:29], v[166:169], v[210:213], v[26:29]
	v_mfma_f32_16x16x32_bf16 v[18:21], v[158:161], v[218:221], v[18:21]
	v_mfma_f32_16x16x32_bf16 v[10:13], v[166:169], v[218:221], v[10:13]
	s_setprio 0
	s_setprio 1
	v_mfma_f32_16x16x32_bf16 v[54:57], v[170:173], v[186:189], v[54:57]
	v_mfma_f32_16x16x32_bf16 v[46:49], v[178:181], v[186:189], v[46:49]
	v_mfma_f32_16x16x32_bf16 v[38:41], v[170:173], v[194:197], v[38:41]
	v_mfma_f32_16x16x32_bf16 v[30:33], v[178:181], v[194:197], v[30:33]
	v_mfma_f32_16x16x32_bf16 v[22:25], v[170:173], v[206:209], v[22:25]
	v_mfma_f32_16x16x32_bf16 v[14:17], v[178:181], v[206:209], v[14:17]
	v_mfma_f32_16x16x32_bf16 v[6:9], v[170:173], v[214:217], v[6:9]
	v_mfma_f32_16x16x32_bf16 v[2:5], v[178:181], v[214:217], v[2:5]
	v_mfma_f32_16x16x32_bf16 v[54:57], v[174:177], v[190:193], v[54:57]
	v_mfma_f32_16x16x32_bf16 v[46:49], v[182:185], v[190:193], v[46:49]
	v_mfma_f32_16x16x32_bf16 v[38:41], v[174:177], v[198:201], v[38:41]
	v_mfma_f32_16x16x32_bf16 v[30:33], v[182:185], v[198:201], v[30:33]
	v_mfma_f32_16x16x32_bf16 v[22:25], v[174:177], v[210:213], v[22:25]
	v_mfma_f32_16x16x32_bf16 v[14:17], v[182:185], v[210:213], v[14:17]
	v_mfma_f32_16x16x32_bf16 v[6:9], v[174:177], v[218:221], v[6:9]
	s_barrier
	v_mfma_f32_16x16x32_bf16 v[2:5], v[182:185], v[218:221], v[2:5]
	s_setprio 0
	s_add_i32 s75, s75, 2
	s_add_u32 s44, s44, 0x100
	s_addc_u32 s45, s45, 0
	s_add_u32 s73, s73, 0x100
	s_addc_u32 s74, s74, 0
	s_cmp_gt_u32 s75, 13
	s_cbranch_scc0 .LBB0_901
	s_and_b64 vcc, exec, s[12:13]
	s_cbranch_vccz .LBB0_904
	s_barrier

; #define PG8_STAGE(bufoff, gbase, voff) do { _Pragma("unroll") for (int _i = 0; _i < 2; ++_i) \
;         __builtin_amdgcn_global_load_lds((const unsigned*)((const char*)(gbase) + (voff)[_i]), (PG8_LAS unsigned*)(lds + (bufoff) + ldsw + _i * 8192), 16, 0, 0); } while (0)
; #define PG8_LDA(dst, b, h) do { _Pragma("unroll") for (int m = 0; m < 4; ++m) _Pragma("unroll") for (int k = 0; k < 2; ++k) dst[m][k] = *(const PG8_LAS bf16x8*)(lds + PG8_SA(b, h) + aoff + m * 2048 + k * 1024); } while (0)
; #define PG8_LDB(dst, b, h) do { _Pragma("unroll") for (int n = 0; n < 2; ++n) _Pragma("unroll") for (int k = 0; k < 2; ++k) dst[n][k] = *(const PG8_LAS bf16x8*)(lds + PG8_SB(b, h) + boff + n * 2048 + k * 1024); } while (0)
; #define PG8_MMA(ai, bj, At, Bt) do { __builtin_amdgcn_s_setprio(1); _Pragma("unroll") for (int m = 0; m < 4; ++m) _Pragma("unroll") for (int n = 0; n < 2; ++n) _Pragma("unroll") for (int k = 0; k < 2; ++k) \
;         acc[ai][bj][m][n] = __builtin_amdgcn_mfma_f32_16x16x32_bf16(Bt[n][k], At[m][k], acc[ai][bj][m][n], 0, 0, 0); __builtin_amdgcn_s_setprio(0); } while (0)
; #define PG8_WAIT_V(n) asm volatile("s_waitcnt vmcnt(" #n ")" ::: "memory")
; #define PG8_WAIT_L(n) asm volatile("s_waitcnt lgkmcnt(" #n ")" ::: "memory")
; #define PG8_BAR __builtin_amdgcn_s_barrier()
; #define PG8_SCHED __builtin_amdgcn_sched_barrier(0)
; template <class Epi, class Sched, bool ALIGN_EPI = false, bool SP2 = false>
; __device__ __forceinline__ void gemm_phase(PG8_LAS unsigned char* lds, const Gemm g, const Sched& S, const Epi& E) {
;     ...
;             PG8_LDB(B0, 0, 0); PG8_LDB(B1, 0, 1); PG8_SCHED; PG8_LDA(At, 0, 0); PG8_STAGE(PG8_SA(1, 1), a1 + hstep, voffA);
;             PG8_WAIT_V(8); PG8_WAIT_L(0); PG8_BAR; PG8_MMA(0, 0, At, B0); PG8_MMA(0, 1, At, B1); PG8_BAR; PG8_SCHED;
;             PG8_LDA(At, 0, 1); PG8_STAGE(PG8_SB(0, 0), b2, voffB); PG8_STAGE(PG8_SB(0, 1), b2 + hstep, voffB); PG8_STAGE(PG8_SA(0, 0), a2, voffA);
;             PG8_WAIT_V(8); PG8_WAIT_L(0); PG8_BAR; PG8_MMA(1, 0, At, B0); PG8_MMA(1, 1, At, B1); PG8_BAR; PG8_SCHED;
.LBB0_984:
	ds_read_b128 v[122:125], v184
	ds_read_b128 v[126:129], v184 offset:1024
	ds_read_b128 v[130:133], v184 offset:2048
	ds_read_b128 v[134:137], v184 offset:3072
	ds_read_b128 v[142:145], v185
	ds_read_b128 v[146:149], v185 offset:1024
	ds_read_b128 v[150:153], v185 offset:2048
	ds_read_b128 v[158:161], v185 offset:3072
	s_add_u32 s30, s26, 0xfff00080
	s_addc_u32 s31, s27, -1
	s_cmp_eq_u32 s64, 60
	s_cselect_b32 s41, s19, s31
	s_cselect_b32 s40, s60, s30
	s_cselect_b32 s39, s17, s63
	s_cselect_b32 s38, s61, s62
	v_lshl_add_u64 v[218:219], s[26:27], 0, v[170:171]
	s_add_i32 m0, s25, 0xc000
	ds_read_b128 v[178:181], v186
	ds_read_b128 v[188:191], v186 offset:1024
	ds_read_b128 v[192:195], v186 offset:2048
	ds_read_b128 v[196:199], v186 offset:3072
	ds_read_b128 v[200:203], v186 offset:4096
	ds_read_b128 v[206:209], v186 offset:5120
	ds_read_b128 v[210:213], v186 offset:6144
	ds_read_b128 v[214:217], v186 offset:7168
	global_load_lds_dwordx4 v[218:219], off
	v_lshl_add_u64 v[218:219], s[26:27], 0, v[172:173]
	s_add_i32 m0, s25, 0xe000
	s_nop 0
	global_load_lds_dwordx4 v[218:219], off
	s_waitcnt vmcnt(8)
	s_waitcnt lgkmcnt(0)
	s_barrier
	s_setprio 1
	s_waitcnt lgkmcnt(0)
	v_mfma_f32_16x16x32_bf16 v[154:157], v[122:125], v[178:181], v[154:157]
	v_mfma_f32_16x16x32_bf16 v[138:141], v[130:133], v[178:181], v[138:141]
	v_mfma_f32_16x16x32_bf16 v[114:117], v[122:125], v[192:195], v[114:117]
	v_mfma_f32_16x16x32_bf16 v[106:109], v[130:133], v[192:195], v[106:109]
	v_mfma_f32_16x16x32_bf16 v[94:97], v[122:125], v[200:203], v[94:97]
	v_mfma_f32_16x16x32_bf16 v[90:93], v[130:133], v[200:203], v[90:93]
	v_mfma_f32_16x16x32_bf16 v[82:85], v[122:125], v[210:213], v[82:85]
	v_mfma_f32_16x16x32_bf16 v[74:77], v[130:133], v[210:213], v[74:77]
	v_mfma_f32_16x16x32_bf16 v[154:157], v[126:129], v[188:191], v[154:157]
	v_mfma_f32_16x16x32_bf16 v[138:141], v[134:137], v[188:191], v[138:141]
	v_mfma_f32_16x16x32_bf16 v[114:117], v[126:129], v[196:199], v[114:117]
	v_mfma_f32_16x16x32_bf16 v[106:109], v[134:137], v[196:199], v[106:109]
	v_mfma_f32_16x16x32_bf16 v[94:97], v[126:129], v[206:209], v[94:97]
	v_mfma_f32_16x16x32_bf16 v[90:93], v[134:137], v[206:209], v[90:93]
	v_mfma_f32_16x16x32_bf16 v[82:85], v[126:129], v[214:217], v[82:85]
	v_mfma_f32_16x16x32_bf16 v[74:77], v[134:137], v[214:217], v[74:77]
	s_setprio 0
	s_setprio 1
	v_mfma_f32_16x16x32_bf16 v[118:121], v[142:145], v[178:181], v[118:121]
	v_mfma_f32_16x16x32_bf16 v[110:113], v[150:153], v[178:181], v[110:113]
	v_mfma_f32_16x16x32_bf16 v[102:105], v[142:145], v[192:195], v[102:105]
	v_mfma_f32_16x16x32_bf16 v[98:101], v[150:153], v[192:195], v[98:101]
	v_mfma_f32_16x16x32_bf16 v[86:89], v[142:145], v[200:203], v[86:89]
	v_mfma_f32_16x16x32_bf16 v[78:81], v[150:153], v[200:203], v[78:81]
	v_mfma_f32_16x16x32_bf16 v[70:73], v[142:145], v[210:213], v[70:73]
	v_mfma_f32_16x16x32_bf16 v[66:69], v[150:153], v[210:213], v[66:69]
	v_mfma_f32_16x16x32_bf16 v[118:121], v[146:149], v[188:191], v[118:121]
	v_mfma_f32_16x16x32_bf16 v[110:113], v[158:161], v[188:191], v[110:113]
	v_mfma_f32_16x16x32_bf16 v[102:105], v[146:149], v[196:199], v[102:105]
	v_mfma_f32_16x16x32_bf16 v[98:101], v[158:161], v[196:199], v[98:101]
	v_mfma_f32_16x16x32_bf16 v[86:89], v[146:149], v[206:209], v[86:89]
	v_mfma_f32_16x16x32_bf16 v[78:81], v[158:161], v[206:209], v[78:81]
	v_mfma_f32_16x16x32_bf16 v[70:73], v[146:149], v[214:217], v[70:73]
	s_barrier
	v_mfma_f32_16x16x32_bf16 v[66:69], v[158:161], v[214:217], v[66:69]
	s_setprio 0
	s_add_i32 s30, s57, s33
	v_lshl_add_u64 v[218:219], s[38:39], 0, v[164:165]
	s_mov_b32 m0, s30
	ds_read_b128 v[178:181], v186 offset:16384
	ds_read_b128 v[188:191], v186 offset:17408
	ds_read_b128 v[192:195], v186 offset:18432
	ds_read_b128 v[196:199], v186 offset:19456
	ds_read_b128 v[200:203], v186 offset:20480
	ds_read_b128 v[206:209], v186 offset:21504
	ds_read_b128 v[210:213], v186 offset:22528
	ds_read_b128 v[214:217], v186 offset:23552
	global_load_lds_dwordx4 v[218:219], off
	s_add_i32 m0, s30, 0x2000
	s_add_u32 s30, s38, 0x100000
	v_lshl_add_u64 v[220:221], s[38:39], 0, v[168:169]
	s_addc_u32 s31, s39, 0
	s_add_i32 s65, s58, s33
	global_load_lds_dwordx4 v[220:221], off
	v_lshl_add_u64 v[222:223], s[30:31], 0, v[164:165]
	s_mov_b32 m0, s65
	v_lshl_add_u64 v[224:225], s[40:41], 0, v[166:167]
	global_load_lds_dwordx4 v[222:223], off
	v_lshl_add_u64 v[222:223], s[30:31], 0, v[168:169]
	s_add_i32 m0, s65, 0x2000
	s_nop 0
	global_load_lds_dwordx4 v[222:223], off
	v_lshl_add_u64 v[222:223], s[40:41], 0, v[162:163]
	s_mov_b32 m0, s25
	s_nop 0
	global_load_lds_dwordx4 v[222:223], off
	s_mov_b32 m0, s44
	s_nop 0
	global_load_lds_dwordx4 v[224:225], off
	s_waitcnt vmcnt(8)
	s_waitcnt lgkmcnt(0)
	s_barrier
; #define PG8_STAGE(bufoff, gbase, voff) do { _Pragma("unroll") for (int _i = 0; _i < 2; ++_i) \
;         __builtin_amdgcn_global_load_lds((const unsigned*)((const char*)(gbase) + (voff)[_i]), (PG8_LAS unsigned*)(lds + (bufoff) + ldsw + _i * 8192), 16, 0, 0); } while (0)
; #define PG8_LDA(dst, b, h) do { _Pragma("unroll") for (int m = 0; m < 4; ++m) _Pragma("unroll") for (int k = 0; k < 2; ++k) dst[m][k] = *(const PG8_LAS bf16x8*)(lds + PG8_SA(b, h) + aoff + m * 2048 + k * 1024); } while (0)
; #define PG8_LDB(dst, b, h) do { _Pragma("unroll") for (int n = 0; n < 2; ++n) _Pragma("unroll") for (int k = 0; k < 2; ++k) dst[n][k] = *(const PG8_LAS bf16x8*)(lds + PG8_SB(b, h) + boff + n * 2048 + k * 1024); } while (0)
; #define PG8_MMA(ai, bj, At, Bt) do { __builtin_amdgcn_s_setprio(1); _Pragma("unroll") for (int m = 0; m < 4; ++m) _Pragma("unroll") for (int n = 0; n < 2; ++n) _Pragma("unroll") for (int k = 0; k < 2; ++k) \
;         acc[ai][bj][m][n] = __builtin_amdgcn_mfma_f32_16x16x32_bf16(Bt[n][k], At[m][k], acc[ai][bj][m][n], 0, 0, 0); __builtin_amdgcn_s_setprio(0); } while (0)
; #define PG8_WAIT_V(n) asm volatile("s_waitcnt vmcnt(" #n ")" ::: "memory")
; #define PG8_WAIT_L(n) asm volatile("s_waitcnt lgkmcnt(" #n ")" ::: "memory")
; #define PG8_BAR __builtin_amdgcn_s_barrier()
; #define PG8_SCHED __builtin_amdgcn_sched_barrier(0)
; template <class Epi, class Sched, bool ALIGN_EPI = false, bool SP2 = false>
; __device__ __forceinline__ void gemm_phase(PG8_LAS unsigned char* lds, const Gemm g, const Sched& S, const Epi& E) {
;     ...
;             PG8_WAIT_V(8); PG8_WAIT_L(0); PG8_BAR; PG8_MMA(1, 0, At, B0); PG8_MMA(1, 1, At, B1); PG8_BAR; PG8_SCHED;
;             PG8_LDB(B0, 1, 0); PG8_LDB(B1, 1, 1); PG8_SCHED; PG8_LDA(At, 1, 0); PG8_STAGE(PG8_SA(0, 1), a2 + hstep, voffA);
;             PG8_WAIT_V(8); PG8_WAIT_L(0); PG8_BAR; PG8_MMA(0, 0, At, B0); PG8_MMA(0, 1, At, B1); PG8_BAR; PG8_SCHED;
	s_setprio 1
	s_waitcnt lgkmcnt(0)
	v_mfma_f32_16x16x32_bf16 v[62:65], v[122:125], v[178:181], v[62:65]
	v_mfma_f32_16x16x32_bf16 v[58:61], v[130:133], v[178:181], v[58:61]
	v_mfma_f32_16x16x32_bf16 v[50:53], v[122:125], v[192:195], v[50:53]
	v_mfma_f32_16x16x32_bf16 v[42:45], v[130:133], v[192:195], v[42:45]
	v_mfma_f32_16x16x32_bf16 v[30:33], v[122:125], v[200:203], v[30:33]
	v_mfma_f32_16x16x32_bf16 v[26:29], v[130:133], v[200:203], v[26:29]
	v_mfma_f32_16x16x32_bf16 v[18:21], v[122:125], v[210:213], v[18:21]
	v_mfma_f32_16x16x32_bf16 v[10:13], v[130:133], v[210:213], v[10:13]
	v_mfma_f32_16x16x32_bf16 v[62:65], v[126:129], v[188:191], v[62:65]
	v_mfma_f32_16x16x32_bf16 v[58:61], v[134:137], v[188:191], v[58:61]
	v_mfma_f32_16x16x32_bf16 v[50:53], v[126:129], v[196:199], v[50:53]
	v_mfma_f32_16x16x32_bf16 v[42:45], v[134:137], v[196:199], v[42:45]
	v_mfma_f32_16x16x32_bf16 v[30:33], v[126:129], v[206:209], v[30:33]
	v_mfma_f32_16x16x32_bf16 v[26:29], v[134:137], v[206:209], v[26:29]
	v_mfma_f32_16x16x32_bf16 v[18:21], v[126:129], v[214:217], v[18:21]
	v_mfma_f32_16x16x32_bf16 v[10:13], v[134:137], v[214:217], v[10:13]
	s_setprio 0
	s_setprio 1
	v_mfma_f32_16x16x32_bf16 v[54:57], v[142:145], v[178:181], v[54:57]
	v_mfma_f32_16x16x32_bf16 v[46:49], v[150:153], v[178:181], v[46:49]
	v_mfma_f32_16x16x32_bf16 v[38:41], v[142:145], v[192:195], v[38:41]
	v_mfma_f32_16x16x32_bf16 v[34:37], v[150:153], v[192:195], v[34:37]
	v_mfma_f32_16x16x32_bf16 v[22:25], v[142:145], v[200:203], v[22:25]
	v_mfma_f32_16x16x32_bf16 v[14:17], v[150:153], v[200:203], v[14:17]
	v_mfma_f32_16x16x32_bf16 v[6:9], v[142:145], v[210:213], v[6:9]
	v_mfma_f32_16x16x32_bf16 v[2:5], v[150:153], v[210:213], v[2:5]
	v_mfma_f32_16x16x32_bf16 v[54:57], v[146:149], v[188:191], v[54:57]
	v_mfma_f32_16x16x32_bf16 v[46:49], v[158:161], v[188:191], v[46:49]
	v_mfma_f32_16x16x32_bf16 v[38:41], v[146:149], v[196:199], v[38:41]
	v_mfma_f32_16x16x32_bf16 v[34:37], v[158:161], v[196:199], v[34:37]
	v_mfma_f32_16x16x32_bf16 v[22:25], v[146:149], v[206:209], v[22:25]
	v_mfma_f32_16x16x32_bf16 v[14:17], v[158:161], v[206:209], v[14:17]
	v_mfma_f32_16x16x32_bf16 v[6:9], v[146:149], v[214:217], v[6:9]
	s_barrier
	v_mfma_f32_16x16x32_bf16 v[2:5], v[158:161], v[214:217], v[2:5]
	s_setprio 0
	s_add_i32 s65, 0, 0x18000
	s_add_i32 s66, 0, 0x1c000
	v_add_u32_e32 v134, s65, v182
	v_add_u32_e32 v158, s66, v182
	ds_read_b128 v[122:125], v134
	ds_read_b128 v[126:129], v134 offset:1024
	ds_read_b128 v[130:133], v134 offset:2048
	ds_read_b128 v[134:137], v134 offset:3072
	ds_read_b128 v[142:145], v158
	ds_read_b128 v[146:149], v158 offset:1024
	ds_read_b128 v[150:153], v158 offset:2048
	ds_read_b128 v[158:161], v158 offset:3072
	s_add_u32 s30, s40, 0x100000
	s_addc_u32 s31, s41, 0
	s_mov_b32 m0, s45
	v_lshl_add_u64 v[226:227], s[30:31], 0, v[162:163]
	ds_read_b128 v[178:181], v186 offset:32768
	ds_read_b128 v[188:191], v186 offset:33792
	ds_read_b128 v[192:195], v186 offset:34816
	ds_read_b128 v[196:199], v186 offset:35840
	ds_read_b128 v[200:203], v186 offset:36864
	ds_read_b128 v[206:209], v186 offset:37888
	ds_read_b128 v[210:213], v186 offset:38912
	ds_read_b128 v[214:217], v186 offset:39936
	global_load_lds_dwordx4 v[226:227], off
	v_lshl_add_u64 v[226:227], s[30:31], 0, v[166:167]
	s_mov_b32 m0, s50
	s_nop 0
	global_load_lds_dwordx4 v[226:227], off
	s_waitcnt vmcnt(8)
	s_waitcnt lgkmcnt(0)
	s_barrier
	s_setprio 1
	s_waitcnt lgkmcnt(0)
	v_mfma_f32_16x16x32_bf16 v[154:157], v[122:125], v[178:181], v[154:157]
	v_mfma_f32_16x16x32_bf16 v[138:141], v[130:133], v[178:181], v[138:141]
	v_mfma_f32_16x16x32_bf16 v[114:117], v[122:125], v[192:195], v[114:117]
	v_mfma_f32_16x16x32_bf16 v[106:109], v[130:133], v[192:195], v[106:109]
	v_mfma_f32_16x16x32_bf16 v[94:97], v[122:125], v[200:203], v[94:97]
	v_mfma_f32_16x16x32_bf16 v[90:93], v[130:133], v[200:203], v[90:93]
	v_mfma_f32_16x16x32_bf16 v[82:85], v[122:125], v[210:213], v[82:85]
	v_mfma_f32_16x16x32_bf16 v[74:77], v[130:133], v[210:213], v[74:77]
	v_mfma_f32_16x16x32_bf16 v[154:157], v[126:129], v[188:191], v[154:157]
	v_mfma_f32_16x16x32_bf16 v[138:141], v[134:137], v[188:191], v[138:141]
	v_mfma_f32_16x16x32_bf16 v[114:117], v[126:129], v[196:199], v[114:117]
	v_mfma_f32_16x16x32_bf16 v[106:109], v[134:137], v[196:199], v[106:109]
	v_mfma_f32_16x16x32_bf16 v[94:97], v[126:129], v[206:209], v[94:97]
	v_mfma_f32_16x16x32_bf16 v[90:93], v[134:137], v[206:209], v[90:93]
	v_mfma_f32_16x16x32_bf16 v[82:85], v[126:129], v[214:217], v[82:85]
	v_mfma_f32_16x16x32_bf16 v[74:77], v[134:137], v[214:217], v[74:77]
	s_setprio 0
	s_setprio 1
	v_mfma_f32_16x16x32_bf16 v[118:121], v[142:145], v[178:181], v[118:121]
	v_mfma_f32_16x16x32_bf16 v[110:113], v[150:153], v[178:181], v[110:113]
	v_mfma_f32_16x16x32_bf16 v[102:105], v[142:145], v[192:195], v[102:105]
	v_mfma_f32_16x16x32_bf16 v[98:101], v[150:153], v[192:195], v[98:101]
	v_mfma_f32_16x16x32_bf16 v[86:89], v[142:145], v[200:203], v[86:89]
	v_mfma_f32_16x16x32_bf16 v[78:81], v[150:153], v[200:203], v[78:81]
	v_mfma_f32_16x16x32_bf16 v[70:73], v[142:145], v[210:213], v[70:73]
	v_mfma_f32_16x16x32_bf16 v[66:69], v[150:153], v[210:213], v[66:69]
	v_mfma_f32_16x16x32_bf16 v[118:121], v[146:149], v[188:191], v[118:121]
	v_mfma_f32_16x16x32_bf16 v[110:113], v[158:161], v[188:191], v[110:113]
	v_mfma_f32_16x16x32_bf16 v[102:105], v[146:149], v[196:199], v[102:105]
	v_mfma_f32_16x16x32_bf16 v[98:101], v[158:161], v[196:199], v[98:101]
	v_mfma_f32_16x16x32_bf16 v[86:89], v[146:149], v[206:209], v[86:89]
	v_mfma_f32_16x16x32_bf16 v[78:81], v[158:161], v[206:209], v[78:81]
	v_mfma_f32_16x16x32_bf16 v[70:73], v[146:149], v[214:217], v[70:73]
	s_barrier
; #define PG8_STAGE(bufoff, gbase, voff) do { _Pragma("unroll") for (int _i = 0; _i < 2; ++_i) \
;         __builtin_amdgcn_global_load_lds((const unsigned*)((const char*)(gbase) + (voff)[_i]), (PG8_LAS unsigned*)(lds + (bufoff) + ldsw + _i * 8192), 16, 0, 0); } while (0)
; #define PG8_LDA(dst, b, h) do { _Pragma("unroll") for (int m = 0; m < 4; ++m) _Pragma("unroll") for (int k = 0; k < 2; ++k) dst[m][k] = *(const PG8_LAS bf16x8*)(lds + PG8_SA(b, h) + aoff + m * 2048 + k * 1024); } while (0)
; #define PG8_MMA(ai, bj, At, Bt) do { __builtin_amdgcn_s_setprio(1); _Pragma("unroll") for (int m = 0; m < 4; ++m) _Pragma("unroll") for (int n = 0; n < 2; ++n) _Pragma("unroll") for (int k = 0; k < 2; ++k) \
;         acc[ai][bj][m][n] = __builtin_amdgcn_mfma_f32_16x16x32_bf16(Bt[n][k], At[m][k], acc[ai][bj][m][n], 0, 0, 0); __builtin_amdgcn_s_setprio(0); } while (0)
; #define PG8_WAIT_V(n) asm volatile("s_waitcnt vmcnt(" #n ")" ::: "memory")
; #define PG8_WAIT_L(n) asm volatile("s_waitcnt lgkmcnt(" #n ")" ::: "memory")
; #define PG8_BAR __builtin_amdgcn_s_barrier()
; #define PG8_SCHED __builtin_amdgcn_sched_barrier(0)
; template <class Epi, class Sched, bool ALIGN_EPI = false, bool SP2 = false>
; __device__ __forceinline__ void gemm_phase(PG8_LAS unsigned char* lds, const Gemm g, const Sched& S, const Epi& E) {
;     ...
;             PG8_WAIT_V(8); PG8_WAIT_L(0); PG8_BAR; PG8_MMA(0, 0, At, B0); PG8_MMA(0, 1, At, B1); PG8_BAR; PG8_SCHED;
;             PG8_LDA(At, 1, 1); PG8_STAGE(PG8_SB(1, 0), b3, voffB); PG8_STAGE(PG8_SB(1, 1), b3 + hstep, voffB); PG8_STAGE(PG8_SA(1, 0), a3, voffA);
;             PG8_WAIT_V(8); PG8_WAIT_L(0); PG8_BAR; PG8_MMA(1, 0, At, B0); PG8_MMA(1, 1, At, B1); PG8_BAR; PG8_SCHED;
	v_mfma_f32_16x16x32_bf16 v[66:69], v[158:161], v[214:217], v[66:69]
	s_setprio 0
	s_add_i32 s30, s65, s33
	v_lshl_add_u64 v[218:219], v[218:219], 0, s[10:11]
	s_mov_b32 m0, s30
	ds_read_b128 v[178:181], v186 offset:49152
	ds_read_b128 v[188:191], v186 offset:50176
	ds_read_b128 v[192:195], v186 offset:51200
	ds_read_b128 v[196:199], v186 offset:52224
	ds_read_b128 v[200:203], v186 offset:53248
	ds_read_b128 v[206:209], v186 offset:54272
	ds_read_b128 v[210:213], v186 offset:55296
	ds_read_b128 v[214:217], v186 offset:56320
	global_load_lds_dwordx4 v[218:219], off
	s_add_i32 m0, s30, 0x2000
	s_add_u32 s30, s38, 0x100080
	v_lshl_add_u64 v[218:219], v[220:221], 0, s[10:11]
	s_addc_u32 s31, s39, 0
	s_add_i32 s38, s66, s33
	global_load_lds_dwordx4 v[218:219], off
	v_lshl_add_u64 v[218:219], s[30:31], 0, v[164:165]
	s_mov_b32 m0, s38
	s_nop 0
	global_load_lds_dwordx4 v[218:219], off
	v_lshl_add_u64 v[218:219], s[30:31], 0, v[168:169]
	s_add_i32 m0, s38, 0x2000
	s_nop 0
	global_load_lds_dwordx4 v[218:219], off
	v_lshl_add_u64 v[218:219], v[222:223], 0, s[10:11]
	s_mov_b32 m0, s52
	s_nop 0
	global_load_lds_dwordx4 v[218:219], off
	v_lshl_add_u64 v[218:219], v[224:225], 0, s[10:11]
	s_mov_b32 m0, s53
	s_nop 0
	global_load_lds_dwordx4 v[218:219], off
	s_waitcnt vmcnt(8)
	s_waitcnt lgkmcnt(0)
	s_barrier
	s_setprio 1
	s_waitcnt lgkmcnt(0)
	v_mfma_f32_16x16x32_bf16 v[62:65], v[122:125], v[178:181], v[62:65]
	v_mfma_f32_16x16x32_bf16 v[58:61], v[130:133], v[178:181], v[58:61]
	v_mfma_f32_16x16x32_bf16 v[50:53], v[122:125], v[192:195], v[50:53]
	v_mfma_f32_16x16x32_bf16 v[42:45], v[130:133], v[192:195], v[42:45]
	v_mfma_f32_16x16x32_bf16 v[30:33], v[122:125], v[200:203], v[30:33]
	v_mfma_f32_16x16x32_bf16 v[26:29], v[130:133], v[200:203], v[26:29]
	v_mfma_f32_16x16x32_bf16 v[18:21], v[122:125], v[210:213], v[18:21]
	v_mfma_f32_16x16x32_bf16 v[10:13], v[130:133], v[210:213], v[10:13]
	v_mfma_f32_16x16x32_bf16 v[62:65], v[126:129], v[188:191], v[62:65]
	v_mfma_f32_16x16x32_bf16 v[58:61], v[134:137], v[188:191], v[58:61]
	v_mfma_f32_16x16x32_bf16 v[50:53], v[126:129], v[196:199], v[50:53]
	v_mfma_f32_16x16x32_bf16 v[42:45], v[134:137], v[196:199], v[42:45]
	v_mfma_f32_16x16x32_bf16 v[30:33], v[126:129], v[206:209], v[30:33]
	v_mfma_f32_16x16x32_bf16 v[26:29], v[134:137], v[206:209], v[26:29]
	v_mfma_f32_16x16x32_bf16 v[18:21], v[126:129], v[214:217], v[18:21]
	v_mfma_f32_16x16x32_bf16 v[10:13], v[134:137], v[214:217], v[10:13]
	s_setprio 0
	s_setprio 1
	v_mfma_f32_16x16x32_bf16 v[54:57], v[142:145], v[178:181], v[54:57]
	v_mfma_f32_16x16x32_bf16 v[46:49], v[150:153], v[178:181], v[46:49]
	v_mfma_f32_16x16x32_bf16 v[38:41], v[142:145], v[192:195], v[38:41]
	v_mfma_f32_16x16x32_bf16 v[34:37], v[150:153], v[192:195], v[34:37]
	v_mfma_f32_16x16x32_bf16 v[22:25], v[142:145], v[200:203], v[22:25]
	v_mfma_f32_16x16x32_bf16 v[14:17], v[150:153], v[200:203], v[14:17]
	v_mfma_f32_16x16x32_bf16 v[6:9], v[142:145], v[210:213], v[6:9]
	v_mfma_f32_16x16x32_bf16 v[2:5], v[150:153], v[210:213], v[2:5]
	v_mfma_f32_16x16x32_bf16 v[54:57], v[146:149], v[188:191], v[54:57]
	v_mfma_f32_16x16x32_bf16 v[46:49], v[158:161], v[188:191], v[46:49]
	v_mfma_f32_16x16x32_bf16 v[38:41], v[146:149], v[196:199], v[38:41]
	v_mfma_f32_16x16x32_bf16 v[34:37], v[158:161], v[196:199], v[34:37]
	v_mfma_f32_16x16x32_bf16 v[22:25], v[146:149], v[206:209], v[22:25]
	v_mfma_f32_16x16x32_bf16 v[14:17], v[158:161], v[206:209], v[14:17]
	v_mfma_f32_16x16x32_bf16 v[6:9], v[146:149], v[214:217], v[6:9]
	s_barrier
	v_mfma_f32_16x16x32_bf16 v[2:5], v[158:161], v[214:217], v[2:5]
	s_setprio 0
	s_add_i32 s64, s64, 2
	s_add_u32 s26, s26, 0x100
	s_addc_u32 s27, s27, 0
	s_add_u32 s62, s62, 0x100
	s_addc_u32 s63, s63, 0
	s_cmp_gt_u32 s64, 61
	s_cbranch_scc0 .LBB0_984
	s_and_b64 vcc, exec, s[12:13]
	s_cbranch_vccz .LBB0_987
	s_barrier

; #define PG8_STAGE(bufoff, gbase, voff) do { _Pragma("unroll") for (int _i = 0; _i < 2; ++_i) \
;         __builtin_amdgcn_global_load_lds((const unsigned*)((const char*)(gbase) + (voff)[_i]), (PG8_LAS unsigned*)(lds + (bufoff) + ldsw + _i * 8192), 16, 0, 0); } while (0)
; #define PG8_LDA(dst, b, h) do { _Pragma("unroll") for (int m = 0; m < 4; ++m) _Pragma("unroll") for (int k = 0; k < 2; ++k) dst[m][k] = *(const PG8_LAS bf16x8*)(lds + PG8_SA(b, h) + aoff + m * 2048 + k * 1024); } while (0)
; #define PG8_LDB(dst, b, h) do { _Pragma("unroll") for (int n = 0; n < 2; ++n) _Pragma("unroll") for (int k = 0; k < 2; ++k) dst[n][k] = *(const PG8_LAS bf16x8*)(lds + PG8_SB(b, h) + boff + n * 2048 + k * 1024); } while (0)
; #define PG8_MMA(ai, bj, At, Bt) do { __builtin_amdgcn_s_setprio(1); _Pragma("unroll") for (int m = 0; m < 4; ++m) _Pragma("unroll") for (int n = 0; n < 2; ++n) _Pragma("unroll") for (int k = 0; k < 2; ++k) \
;         acc[ai][bj][m][n] = __builtin_amdgcn_mfma_f32_16x16x32_bf16(Bt[n][k], At[m][k], acc[ai][bj][m][n], 0, 0, 0); __builtin_amdgcn_s_setprio(0); } while (0)
; #define PG8_WAIT_V(n) asm volatile("s_waitcnt vmcnt(" #n ")" ::: "memory")
; #define PG8_WAIT_L(n) asm volatile("s_waitcnt lgkmcnt(" #n ")" ::: "memory")
; #define PG8_BAR __builtin_amdgcn_s_barrier()
; #define PG8_SCHED __builtin_amdgcn_sched_barrier(0)
; template <class Epi, class Sched, bool ALIGN_EPI = false, bool SP2 = false>
; __device__ __forceinline__ void gemm_phase(PG8_LAS unsigned char* lds, const Gemm g, const Sched& S, const Epi& E) {
;     ...
;             PG8_LDB(B0, 0, 0); PG8_LDB(B1, 0, 1); PG8_SCHED; PG8_LDA(At, 0, 0); PG8_STAGE(PG8_SA(1, 1), a1 + hstep, voffA);
;             PG8_WAIT_V(8); PG8_WAIT_L(0); PG8_BAR; PG8_MMA(0, 0, At, B0); PG8_MMA(0, 1, At, B1); PG8_BAR; PG8_SCHED;
;             PG8_LDA(At, 0, 1); PG8_STAGE(PG8_SB(0, 0), b2, voffB); PG8_STAGE(PG8_SB(0, 1), b2 + hstep, voffB); PG8_STAGE(PG8_SA(0, 0), a2, voffA);
;             PG8_WAIT_V(8); PG8_WAIT_L(0); PG8_BAR; PG8_MMA(1, 0, At, B0); PG8_MMA(1, 1, At, B1); PG8_BAR; PG8_SCHED;
.LBB0_1136:
	ds_read_b128 v[130:133], v186
	ds_read_b128 v[134:137], v186 offset:1024
	ds_read_b128 v[138:141], v186 offset:2048
	ds_read_b128 v[166:169], v186 offset:3072
	ds_read_b128 v[170:173], v187
	ds_read_b128 v[174:177], v187 offset:1024
	ds_read_b128 v[178:181], v187 offset:2048
	ds_read_b128 v[182:185], v187 offset:3072
	s_add_u32 s30, s70, 0xfffc0080
	s_addc_u32 s31, s71, -1
	s_cmp_eq_u32 s69, 12
	s_cselect_b32 s75, s1, s31
	s_cselect_b32 s74, s8, s30
	s_cselect_b32 s73, s21, s63
	s_cselect_b32 s72, s33, s61
	v_lshl_add_u64 v[202:203], s[70:71], 0, v[158:159]
	s_add_i32 m0, s28, 0xc000
	ds_read_b128 v[190:193], v188
	ds_read_b128 v[194:197], v188 offset:1024
	ds_read_b128 v[198:201], v188 offset:2048
	ds_read_b128 v[206:209], v188 offset:3072
	ds_read_b128 v[210:213], v188 offset:4096
	ds_read_b128 v[214:217], v188 offset:5120
	ds_read_b128 v[218:221], v188 offset:6144
	ds_read_b128 v[222:225], v188 offset:7168
	global_load_lds_dwordx4 v[202:203], off
	v_lshl_add_u64 v[202:203], s[70:71], 0, v[160:161]
	s_add_i32 m0, s28, 0xe000
	s_nop 0
	global_load_lds_dwordx4 v[202:203], off
	s_waitcnt vmcnt(8)
	s_waitcnt lgkmcnt(0)
	s_barrier
	s_setprio 1
	s_waitcnt lgkmcnt(0)
	v_mfma_f32_16x16x32_bf16 v[126:129], v[130:133], v[190:193], v[126:129]
	v_mfma_f32_16x16x32_bf16 v[122:125], v[138:141], v[190:193], v[122:125]
	v_mfma_f32_16x16x32_bf16 v[118:121], v[130:133], v[198:201], v[118:121]
	v_mfma_f32_16x16x32_bf16 v[114:117], v[138:141], v[198:201], v[114:117]
	v_mfma_f32_16x16x32_bf16 v[110:113], v[130:133], v[210:213], v[110:113]
	v_mfma_f32_16x16x32_bf16 v[106:109], v[138:141], v[210:213], v[106:109]
	v_mfma_f32_16x16x32_bf16 v[102:105], v[130:133], v[218:221], v[102:105]
	v_mfma_f32_16x16x32_bf16 v[98:101], v[138:141], v[218:221], v[98:101]
	v_mfma_f32_16x16x32_bf16 v[126:129], v[134:137], v[194:197], v[126:129]
	v_mfma_f32_16x16x32_bf16 v[122:125], v[166:169], v[194:197], v[122:125]
	v_mfma_f32_16x16x32_bf16 v[118:121], v[134:137], v[206:209], v[118:121]
	v_mfma_f32_16x16x32_bf16 v[114:117], v[166:169], v[206:209], v[114:117]
	v_mfma_f32_16x16x32_bf16 v[110:113], v[134:137], v[214:217], v[110:113]
	v_mfma_f32_16x16x32_bf16 v[106:109], v[166:169], v[214:217], v[106:109]
	v_mfma_f32_16x16x32_bf16 v[102:105], v[134:137], v[222:225], v[102:105]
	v_mfma_f32_16x16x32_bf16 v[98:101], v[166:169], v[222:225], v[98:101]
	s_setprio 0
	s_setprio 1
	v_mfma_f32_16x16x32_bf16 v[62:65], v[170:173], v[190:193], v[62:65]
	v_mfma_f32_16x16x32_bf16 v[58:61], v[178:181], v[190:193], v[58:61]
	v_mfma_f32_16x16x32_bf16 v[54:57], v[170:173], v[198:201], v[54:57]
	v_mfma_f32_16x16x32_bf16 v[50:53], v[178:181], v[198:201], v[50:53]
	v_mfma_f32_16x16x32_bf16 v[46:49], v[170:173], v[210:213], v[46:49]
	v_mfma_f32_16x16x32_bf16 v[42:45], v[178:181], v[210:213], v[42:45]
	v_mfma_f32_16x16x32_bf16 v[38:41], v[170:173], v[218:221], v[38:41]
	v_mfma_f32_16x16x32_bf16 v[34:37], v[178:181], v[218:221], v[34:37]
	v_mfma_f32_16x16x32_bf16 v[62:65], v[174:177], v[194:197], v[62:65]
	v_mfma_f32_16x16x32_bf16 v[58:61], v[182:185], v[194:197], v[58:61]
	v_mfma_f32_16x16x32_bf16 v[54:57], v[174:177], v[206:209], v[54:57]
	v_mfma_f32_16x16x32_bf16 v[50:53], v[182:185], v[206:209], v[50:53]
	v_mfma_f32_16x16x32_bf16 v[46:49], v[174:177], v[214:217], v[46:49]
	v_mfma_f32_16x16x32_bf16 v[42:45], v[182:185], v[214:217], v[42:45]
	v_mfma_f32_16x16x32_bf16 v[38:41], v[174:177], v[222:225], v[38:41]
	s_barrier
	v_mfma_f32_16x16x32_bf16 v[34:37], v[182:185], v[222:225], v[34:37]
	s_setprio 0
	s_add_i32 s30, s7, s81
	v_lshl_add_u64 v[202:203], s[72:73], 0, v[146:147]
	s_mov_b32 m0, s30
	ds_read_b128 v[190:193], v188 offset:16384
	ds_read_b128 v[194:197], v188 offset:17408
	ds_read_b128 v[198:201], v188 offset:18432
	ds_read_b128 v[206:209], v188 offset:19456
	ds_read_b128 v[210:213], v188 offset:20480
	ds_read_b128 v[214:217], v188 offset:21504
	ds_read_b128 v[218:221], v188 offset:22528
	ds_read_b128 v[222:225], v188 offset:23552
	global_load_lds_dwordx4 v[202:203], off
	s_add_i32 m0, s30, 0x2000
	s_add_u32 s30, s72, 0x40000
	v_lshl_add_u64 v[226:227], s[72:73], 0, v[150:151]
	s_addc_u32 s31, s73, 0
	s_add_i32 s94, s92, s81
	global_load_lds_dwordx4 v[226:227], off
	v_lshl_add_u64 v[228:229], s[30:31], 0, v[146:147]
	s_mov_b32 m0, s94
	v_lshl_add_u64 v[230:231], s[74:75], 0, v[148:149]
	global_load_lds_dwordx4 v[228:229], off
	v_lshl_add_u64 v[228:229], s[30:31], 0, v[150:151]
	s_add_i32 m0, s94, 0x2000
	s_nop 0
	global_load_lds_dwordx4 v[228:229], off
	v_lshl_add_u64 v[228:229], s[74:75], 0, v[144:145]
	s_mov_b32 m0, s28
	s_nop 0
	global_load_lds_dwordx4 v[228:229], off
	s_mov_b32 m0, s29
	s_nop 0
	global_load_lds_dwordx4 v[230:231], off
	s_waitcnt vmcnt(8)
	s_waitcnt lgkmcnt(0)
	s_barrier
; #define PG8_STAGE(bufoff, gbase, voff) do { _Pragma("unroll") for (int _i = 0; _i < 2; ++_i) \
;         __builtin_amdgcn_global_load_lds((const unsigned*)((const char*)(gbase) + (voff)[_i]), (PG8_LAS unsigned*)(lds + (bufoff) + ldsw + _i * 8192), 16, 0, 0); } while (0)
; #define PG8_LDA(dst, b, h) do { _Pragma("unroll") for (int m = 0; m < 4; ++m) _Pragma("unroll") for (int k = 0; k < 2; ++k) dst[m][k] = *(const PG8_LAS bf16x8*)(lds + PG8_SA(b, h) + aoff + m * 2048 + k * 1024); } while (0)
; #define PG8_LDB(dst, b, h) do { _Pragma("unroll") for (int n = 0; n < 2; ++n) _Pragma("unroll") for (int k = 0; k < 2; ++k) dst[n][k] = *(const PG8_LAS bf16x8*)(lds + PG8_SB(b, h) + boff + n * 2048 + k * 1024); } while (0)
; #define PG8_MMA(ai, bj, At, Bt) do { __builtin_amdgcn_s_setprio(1); _Pragma("unroll") for (int m = 0; m < 4; ++m) _Pragma("unroll") for (int n = 0; n < 2; ++n) _Pragma("unroll") for (int k = 0; k < 2; ++k) \
;         acc[ai][bj][m][n] = __builtin_amdgcn_mfma_f32_16x16x32_bf16(Bt[n][k], At[m][k], acc[ai][bj][m][n], 0, 0, 0); __builtin_amdgcn_s_setprio(0); } while (0)
; #define PG8_WAIT_V(n) asm volatile("s_waitcnt vmcnt(" #n ")" ::: "memory")
; #define PG8_WAIT_L(n) asm volatile("s_waitcnt lgkmcnt(" #n ")" ::: "memory")
; #define PG8_BAR __builtin_amdgcn_s_barrier()
; #define PG8_SCHED __builtin_amdgcn_sched_barrier(0)
; template <class Epi, class Sched, bool ALIGN_EPI = false, bool SP2 = false>
; __device__ __forceinline__ void gemm_phase(PG8_LAS unsigned char* lds, const Gemm g, const Sched& S, const Epi& E) {
;     ...
;             PG8_WAIT_V(8); PG8_WAIT_L(0); PG8_BAR; PG8_MMA(1, 0, At, B0); PG8_MMA(1, 1, At, B1); PG8_BAR; PG8_SCHED;
;             PG8_LDB(B0, 1, 0); PG8_LDB(B1, 1, 1); PG8_SCHED; PG8_LDA(At, 1, 0); PG8_STAGE(PG8_SA(0, 1), a2 + hstep, voffA);
;             PG8_WAIT_V(8); PG8_WAIT_L(0); PG8_BAR; PG8_MMA(0, 0, At, B0); PG8_MMA(0, 1, At, B1); PG8_BAR; PG8_SCHED;
	s_setprio 1
	s_waitcnt lgkmcnt(0)
	v_mfma_f32_16x16x32_bf16 v[94:97], v[130:133], v[190:193], v[94:97]
	v_mfma_f32_16x16x32_bf16 v[90:93], v[138:141], v[190:193], v[90:93]
	v_mfma_f32_16x16x32_bf16 v[86:89], v[130:133], v[198:201], v[86:89]
	v_mfma_f32_16x16x32_bf16 v[82:85], v[138:141], v[198:201], v[82:85]
	v_mfma_f32_16x16x32_bf16 v[78:81], v[130:133], v[210:213], v[78:81]
	v_mfma_f32_16x16x32_bf16 v[74:77], v[138:141], v[210:213], v[74:77]
	v_mfma_f32_16x16x32_bf16 v[70:73], v[130:133], v[218:221], v[70:73]
	v_mfma_f32_16x16x32_bf16 v[66:69], v[138:141], v[218:221], v[66:69]
	v_mfma_f32_16x16x32_bf16 v[94:97], v[134:137], v[194:197], v[94:97]
	v_mfma_f32_16x16x32_bf16 v[90:93], v[166:169], v[194:197], v[90:93]
	v_mfma_f32_16x16x32_bf16 v[86:89], v[134:137], v[206:209], v[86:89]
	v_mfma_f32_16x16x32_bf16 v[82:85], v[166:169], v[206:209], v[82:85]
	v_mfma_f32_16x16x32_bf16 v[78:81], v[134:137], v[214:217], v[78:81]
	v_mfma_f32_16x16x32_bf16 v[74:77], v[166:169], v[214:217], v[74:77]
	v_mfma_f32_16x16x32_bf16 v[70:73], v[134:137], v[222:225], v[70:73]
	v_mfma_f32_16x16x32_bf16 v[66:69], v[166:169], v[222:225], v[66:69]
	s_setprio 0
	s_setprio 1
	v_mfma_f32_16x16x32_bf16 v[30:33], v[170:173], v[190:193], v[30:33]
	v_mfma_f32_16x16x32_bf16 v[26:29], v[178:181], v[190:193], v[26:29]
	v_mfma_f32_16x16x32_bf16 v[22:25], v[170:173], v[198:201], v[22:25]
	v_mfma_f32_16x16x32_bf16 v[18:21], v[178:181], v[198:201], v[18:21]
	v_mfma_f32_16x16x32_bf16 v[14:17], v[170:173], v[210:213], v[14:17]
	v_mfma_f32_16x16x32_bf16 v[10:13], v[178:181], v[210:213], v[10:13]
	v_mfma_f32_16x16x32_bf16 v[6:9], v[170:173], v[218:221], v[6:9]
	v_mfma_f32_16x16x32_bf16 v[2:5], v[178:181], v[218:221], v[2:5]
	v_mfma_f32_16x16x32_bf16 v[30:33], v[174:177], v[194:197], v[30:33]
	v_mfma_f32_16x16x32_bf16 v[26:29], v[182:185], v[194:197], v[26:29]
	v_mfma_f32_16x16x32_bf16 v[22:25], v[174:177], v[206:209], v[22:25]
	v_mfma_f32_16x16x32_bf16 v[18:21], v[182:185], v[206:209], v[18:21]
	v_mfma_f32_16x16x32_bf16 v[14:17], v[174:177], v[214:217], v[14:17]
	v_mfma_f32_16x16x32_bf16 v[10:13], v[182:185], v[214:217], v[10:13]
	v_mfma_f32_16x16x32_bf16 v[6:9], v[174:177], v[222:225], v[6:9]
	s_barrier
	v_mfma_f32_16x16x32_bf16 v[2:5], v[182:185], v[222:225], v[2:5]
	s_setprio 0
	s_add_i32 s94, 0, 0x18000
	v_add_u32_e32 v152, s94, v155
	s_add_i32 s95, 0, 0x1c000
	ds_read_b128 v[130:133], v152
	ds_read_b128 v[134:137], v152 offset:1024
	ds_read_b128 v[138:141], v152 offset:2048
	ds_read_b128 v[166:169], v152 offset:3072
	v_add_u32_e32 v152, s95, v155
	ds_read_b128 v[170:173], v152
	ds_read_b128 v[174:177], v152 offset:1024
	ds_read_b128 v[178:181], v152 offset:2048
	ds_read_b128 v[182:185], v152 offset:3072
	s_add_u32 s30, s74, 0x40000
	s_addc_u32 s31, s75, 0
	s_mov_b32 m0, s82
	v_lshl_add_u64 v[232:233], s[30:31], 0, v[144:145]
	ds_read_b128 v[190:193], v188 offset:32768
	ds_read_b128 v[194:197], v188 offset:33792
	ds_read_b128 v[198:201], v188 offset:34816
	ds_read_b128 v[206:209], v188 offset:35840
	ds_read_b128 v[210:213], v188 offset:36864
	ds_read_b128 v[214:217], v188 offset:37888
	ds_read_b128 v[218:221], v188 offset:38912
	ds_read_b128 v[222:225], v188 offset:39936
	global_load_lds_dwordx4 v[232:233], off
	v_lshl_add_u64 v[232:233], s[30:31], 0, v[148:149]
	s_mov_b32 m0, s83
	s_nop 0
	global_load_lds_dwordx4 v[232:233], off
	s_waitcnt vmcnt(8)
	s_waitcnt lgkmcnt(0)
	s_barrier
	s_setprio 1
	s_waitcnt lgkmcnt(0)
	v_mfma_f32_16x16x32_bf16 v[126:129], v[130:133], v[190:193], v[126:129]
	v_mfma_f32_16x16x32_bf16 v[122:125], v[138:141], v[190:193], v[122:125]
	v_mfma_f32_16x16x32_bf16 v[118:121], v[130:133], v[198:201], v[118:121]
	v_mfma_f32_16x16x32_bf16 v[114:117], v[138:141], v[198:201], v[114:117]
	v_mfma_f32_16x16x32_bf16 v[110:113], v[130:133], v[210:213], v[110:113]
	v_mfma_f32_16x16x32_bf16 v[106:109], v[138:141], v[210:213], v[106:109]
	v_mfma_f32_16x16x32_bf16 v[102:105], v[130:133], v[218:221], v[102:105]
	v_mfma_f32_16x16x32_bf16 v[98:101], v[138:141], v[218:221], v[98:101]
	v_mfma_f32_16x16x32_bf16 v[126:129], v[134:137], v[194:197], v[126:129]
	v_mfma_f32_16x16x32_bf16 v[122:125], v[166:169], v[194:197], v[122:125]
	v_mfma_f32_16x16x32_bf16 v[118:121], v[134:137], v[206:209], v[118:121]
	v_mfma_f32_16x16x32_bf16 v[114:117], v[166:169], v[206:209], v[114:117]
	v_mfma_f32_16x16x32_bf16 v[110:113], v[134:137], v[214:217], v[110:113]
	v_mfma_f32_16x16x32_bf16 v[106:109], v[166:169], v[214:217], v[106:109]
	v_mfma_f32_16x16x32_bf16 v[102:105], v[134:137], v[222:225], v[102:105]
	v_mfma_f32_16x16x32_bf16 v[98:101], v[166:169], v[222:225], v[98:101]
	s_setprio 0
	s_setprio 1
	v_mfma_f32_16x16x32_bf16 v[62:65], v[170:173], v[190:193], v[62:65]
	v_mfma_f32_16x16x32_bf16 v[58:61], v[178:181], v[190:193], v[58:61]
	v_mfma_f32_16x16x32_bf16 v[54:57], v[170:173], v[198:201], v[54:57]
	v_mfma_f32_16x16x32_bf16 v[50:53], v[178:181], v[198:201], v[50:53]
	v_mfma_f32_16x16x32_bf16 v[46:49], v[170:173], v[210:213], v[46:49]
	v_mfma_f32_16x16x32_bf16 v[42:45], v[178:181], v[210:213], v[42:45]
	v_mfma_f32_16x16x32_bf16 v[38:41], v[170:173], v[218:221], v[38:41]
	v_mfma_f32_16x16x32_bf16 v[34:37], v[178:181], v[218:221], v[34:37]
	v_mfma_f32_16x16x32_bf16 v[62:65], v[174:177], v[194:197], v[62:65]
	v_mfma_f32_16x16x32_bf16 v[58:61], v[182:185], v[194:197], v[58:61]
	v_mfma_f32_16x16x32_bf16 v[54:57], v[174:177], v[206:209], v[54:57]
	v_mfma_f32_16x16x32_bf16 v[50:53], v[182:185], v[206:209], v[50:53]
	v_mfma_f32_16x16x32_bf16 v[46:49], v[174:177], v[214:217], v[46:49]
	v_mfma_f32_16x16x32_bf16 v[42:45], v[182:185], v[214:217], v[42:45]
	v_mfma_f32_16x16x32_bf16 v[38:41], v[174:177], v[222:225], v[38:41]
	s_barrier
; #define PG8_STAGE(bufoff, gbase, voff) do { _Pragma("unroll") for (int _i = 0; _i < 2; ++_i) \
;         __builtin_amdgcn_global_load_lds((const unsigned*)((const char*)(gbase) + (voff)[_i]), (PG8_LAS unsigned*)(lds + (bufoff) + ldsw + _i * 8192), 16, 0, 0); } while (0)
; #define PG8_LDA(dst, b, h) do { _Pragma("unroll") for (int m = 0; m < 4; ++m) _Pragma("unroll") for (int k = 0; k < 2; ++k) dst[m][k] = *(const PG8_LAS bf16x8*)(lds + PG8_SA(b, h) + aoff + m * 2048 + k * 1024); } while (0)
; #define PG8_MMA(ai, bj, At, Bt) do { __builtin_amdgcn_s_setprio(1); _Pragma("unroll") for (int m = 0; m < 4; ++m) _Pragma("unroll") for (int n = 0; n < 2; ++n) _Pragma("unroll") for (int k = 0; k < 2; ++k) \
;         acc[ai][bj][m][n] = __builtin_amdgcn_mfma_f32_16x16x32_bf16(Bt[n][k], At[m][k], acc[ai][bj][m][n], 0, 0, 0); __builtin_amdgcn_s_setprio(0); } while (0)
; #define PG8_WAIT_V(n) asm volatile("s_waitcnt vmcnt(" #n ")" ::: "memory")
; #define PG8_WAIT_L(n) asm volatile("s_waitcnt lgkmcnt(" #n ")" ::: "memory")
; #define PG8_BAR __builtin_amdgcn_s_barrier()
; #define PG8_SCHED __builtin_amdgcn_sched_barrier(0)
; template <class Epi, class Sched, bool ALIGN_EPI = false, bool SP2 = false>
; __device__ __forceinline__ void gemm_phase(PG8_LAS unsigned char* lds, const Gemm g, const Sched& S, const Epi& E) {
;     ...
;         for (int t = 0; t < nt; t += 2) {
;             const bool last = (t == nt - 2);
;             const char* a1 = cA + (size_t)(t + 1) * kstep;
;             const char* a2 = last ? nA : cA + (size_t)(t + 2) * kstep; const char* b2 = last ? nB : cB + (size_t)(t + 2) * kstep;
;             const char* a3 = a2 + kstep; const char* b3 = b2 + kstep;
;     ...
;             PG8_WAIT_V(8); PG8_WAIT_L(0); PG8_BAR; PG8_MMA(0, 0, At, B0); PG8_MMA(0, 1, At, B1); PG8_BAR; PG8_SCHED;
;             PG8_LDA(At, 1, 1); PG8_STAGE(PG8_SB(1, 0), b3, voffB); PG8_STAGE(PG8_SB(1, 1), b3 + hstep, voffB); PG8_STAGE(PG8_SA(1, 0), a3, voffA);
;             PG8_WAIT_V(8); PG8_WAIT_L(0); PG8_BAR; PG8_MMA(1, 0, At, B0); PG8_MMA(1, 1, At, B1); PG8_BAR; PG8_SCHED;
;     ...
;         if constexpr (ALIGN_EPI) { if (wr == 0) PG8_BAR; }
	v_mfma_f32_16x16x32_bf16 v[34:37], v[182:185], v[222:225], v[34:37]
	s_setprio 0
	s_add_i32 s30, s94, s81
	v_lshl_add_u64 v[202:203], v[202:203], 0, s[40:41]
	s_mov_b32 m0, s30
	ds_read_b128 v[190:193], v188 offset:49152
	ds_read_b128 v[194:197], v188 offset:50176
	ds_read_b128 v[198:201], v188 offset:51200
	ds_read_b128 v[206:209], v188 offset:52224
	ds_read_b128 v[210:213], v188 offset:53248
	ds_read_b128 v[214:217], v188 offset:54272
	ds_read_b128 v[218:221], v188 offset:55296
	ds_read_b128 v[222:225], v188 offset:56320
	global_load_lds_dwordx4 v[202:203], off
	s_add_i32 m0, s30, 0x2000
	s_add_u32 s30, s72, 0x40080
	v_lshl_add_u64 v[202:203], v[226:227], 0, s[40:41]
	s_addc_u32 s31, s73, 0
	s_add_i32 s72, s95, s81
	global_load_lds_dwordx4 v[202:203], off
	v_lshl_add_u64 v[202:203], s[30:31], 0, v[146:147]
	s_mov_b32 m0, s72
	s_nop 0
	global_load_lds_dwordx4 v[202:203], off
	v_lshl_add_u64 v[202:203], s[30:31], 0, v[150:151]
	s_add_i32 m0, s72, 0x2000
	s_nop 0
	global_load_lds_dwordx4 v[202:203], off
	v_lshl_add_u64 v[202:203], v[228:229], 0, s[40:41]
	s_mov_b32 m0, s97
	s_nop 0
	global_load_lds_dwordx4 v[202:203], off
	v_lshl_add_u64 v[202:203], v[230:231], 0, s[40:41]
	s_mov_b32 m0, s50
	s_nop 0
	global_load_lds_dwordx4 v[202:203], off
	s_waitcnt vmcnt(8)
	s_waitcnt lgkmcnt(0)
	s_barrier
	s_setprio 1
	s_waitcnt lgkmcnt(0)
	v_mfma_f32_16x16x32_bf16 v[94:97], v[130:133], v[190:193], v[94:97]
	v_mfma_f32_16x16x32_bf16 v[90:93], v[138:141], v[190:193], v[90:93]
	v_mfma_f32_16x16x32_bf16 v[86:89], v[130:133], v[198:201], v[86:89]
	v_mfma_f32_16x16x32_bf16 v[82:85], v[138:141], v[198:201], v[82:85]
	v_mfma_f32_16x16x32_bf16 v[78:81], v[130:133], v[210:213], v[78:81]
	v_mfma_f32_16x16x32_bf16 v[74:77], v[138:141], v[210:213], v[74:77]
	v_mfma_f32_16x16x32_bf16 v[70:73], v[130:133], v[218:221], v[70:73]
	v_mfma_f32_16x16x32_bf16 v[66:69], v[138:141], v[218:221], v[66:69]
	v_mfma_f32_16x16x32_bf16 v[94:97], v[134:137], v[194:197], v[94:97]
	v_mfma_f32_16x16x32_bf16 v[90:93], v[166:169], v[194:197], v[90:93]
	v_mfma_f32_16x16x32_bf16 v[86:89], v[134:137], v[206:209], v[86:89]
	v_mfma_f32_16x16x32_bf16 v[82:85], v[166:169], v[206:209], v[82:85]
	v_mfma_f32_16x16x32_bf16 v[78:81], v[134:137], v[214:217], v[78:81]
	v_mfma_f32_16x16x32_bf16 v[74:77], v[166:169], v[214:217], v[74:77]
	v_mfma_f32_16x16x32_bf16 v[70:73], v[134:137], v[222:225], v[70:73]
	v_mfma_f32_16x16x32_bf16 v[66:69], v[166:169], v[222:225], v[66:69]
	s_setprio 0
	s_setprio 1
	v_mfma_f32_16x16x32_bf16 v[30:33], v[170:173], v[190:193], v[30:33]
	v_mfma_f32_16x16x32_bf16 v[26:29], v[178:181], v[190:193], v[26:29]
	v_mfma_f32_16x16x32_bf16 v[22:25], v[170:173], v[198:201], v[22:25]
	v_mfma_f32_16x16x32_bf16 v[18:21], v[178:181], v[198:201], v[18:21]
	v_mfma_f32_16x16x32_bf16 v[14:17], v[170:173], v[210:213], v[14:17]
	v_mfma_f32_16x16x32_bf16 v[10:13], v[178:181], v[210:213], v[10:13]
	v_mfma_f32_16x16x32_bf16 v[6:9], v[170:173], v[218:221], v[6:9]
	v_mfma_f32_16x16x32_bf16 v[2:5], v[178:181], v[218:221], v[2:5]
	v_mfma_f32_16x16x32_bf16 v[30:33], v[174:177], v[194:197], v[30:33]
	v_mfma_f32_16x16x32_bf16 v[26:29], v[182:185], v[194:197], v[26:29]
	v_mfma_f32_16x16x32_bf16 v[22:25], v[174:177], v[206:209], v[22:25]
	v_mfma_f32_16x16x32_bf16 v[18:21], v[182:185], v[206:209], v[18:21]
	v_mfma_f32_16x16x32_bf16 v[14:17], v[174:177], v[214:217], v[14:17]
	v_mfma_f32_16x16x32_bf16 v[10:13], v[182:185], v[214:217], v[10:13]
	v_mfma_f32_16x16x32_bf16 v[6:9], v[174:177], v[222:225], v[6:9]
	s_barrier
	v_mfma_f32_16x16x32_bf16 v[2:5], v[182:185], v[222:225], v[2:5]
	s_setprio 0
	s_add_i32 s69, s69, 2
	s_add_u32 s70, s70, 0x100
	s_addc_u32 s71, s71, 0
	s_add_u32 s61, s61, 0x100
	s_addc_u32 s63, s63, 0
	s_cmp_gt_u32 s69, 13
	s_cbranch_scc0 .LBB0_1136
	s_and_b64 vcc, exec, s[44:45]
	s_cbranch_vccz .LBB0_1139
	s_barrier

; #define PG8_STAGE(bufoff, gbase, voff) do { _Pragma("unroll") for (int _i = 0; _i < 2; ++_i) \
;         __builtin_amdgcn_global_load_lds((const unsigned*)((const char*)(gbase) + (voff)[_i]), (PG8_LAS unsigned*)(lds + (bufoff) + ldsw + _i * 8192), 16, 0, 0); } while (0)
; #define PG8_LDA(dst, b, h) do { _Pragma("unroll") for (int m = 0; m < 4; ++m) _Pragma("unroll") for (int k = 0; k < 2; ++k) dst[m][k] = *(const PG8_LAS bf16x8*)(lds + PG8_SA(b, h) + aoff + m * 2048 + k * 1024); } while (0)
; #define PG8_LDB(dst, b, h) do { _Pragma("unroll") for (int n = 0; n < 2; ++n) _Pragma("unroll") for (int k = 0; k < 2; ++k) dst[n][k] = *(const PG8_LAS bf16x8*)(lds + PG8_SB(b, h) + boff + n * 2048 + k * 1024); } while (0)
; #define PG8_MMA(ai, bj, At, Bt) do { __builtin_amdgcn_s_setprio(1); _Pragma("unroll") for (int m = 0; m < 4; ++m) _Pragma("unroll") for (int n = 0; n < 2; ++n) _Pragma("unroll") for (int k = 0; k < 2; ++k) \
;         acc[ai][bj][m][n] = __builtin_amdgcn_mfma_f32_16x16x32_bf16(Bt[n][k], At[m][k], acc[ai][bj][m][n], 0, 0, 0); __builtin_amdgcn_s_setprio(0); } while (0)
; #define PG8_WAIT_V(n) asm volatile("s_waitcnt vmcnt(" #n ")" ::: "memory")
; #define PG8_WAIT_L(n) asm volatile("s_waitcnt lgkmcnt(" #n ")" ::: "memory")
; #define PG8_BAR __builtin_amdgcn_s_barrier()
; #define PG8_SCHED __builtin_amdgcn_sched_barrier(0)
; template <class Epi, class Sched, bool ALIGN_EPI = false, bool SP2 = false>
; __device__ __forceinline__ void gemm_phase(PG8_LAS unsigned char* lds, const Gemm g, const Sched& S, const Epi& E) {
;     ...
;             const bool last = (t == nt - 2);
;             const char* a1 = cA + (size_t)(t + 1) * kstep;
;             const char* a2 = last ? nA : cA + (size_t)(t + 2) * kstep; const char* b2 = last ? nB : cB + (size_t)(t + 2) * kstep;
;             const char* a3 = a2 + kstep; const char* b3 = b2 + kstep;
;             if (last && has_next) S.a_ready(nxt);
;             if constexpr (SP2) {
;             PG8_LDB(B0, 0, 0); PG8_LDB(B1, 0, 1); PG8_SCHED; PG8_LDA(At, 0, 0); PG8_STAGE(PG8_SA(1, 1), a1 + hstep, voffA);
;             PG8_WAIT_V(8); PG8_WAIT_L(0); PG8_BAR; PG8_MMA(0, 0, At, B0); PG8_MMA(0, 1, At, B1); PG8_BAR; PG8_SCHED;
;             PG8_LDA(At, 0, 1); PG8_STAGE(PG8_SB(0, 0), b2, voffB); PG8_STAGE(PG8_SB(0, 1), b2 + hstep, voffB); PG8_STAGE(PG8_SA(0, 0), a2, voffA);
.LBB0_1673:
	ds_read_b128 v[122:125], v184
	ds_read_b128 v[126:129], v184 offset:1024
	ds_read_b128 v[130:133], v184 offset:2048
	ds_read_b128 v[134:137], v184 offset:3072
	ds_read_b128 v[142:145], v185
	ds_read_b128 v[146:149], v185 offset:1024
	ds_read_b128 v[150:153], v185 offset:2048
	ds_read_b128 v[158:161], v185 offset:3072
	s_add_u32 s30, s26, 0xfffc0080
	s_addc_u32 s31, s27, -1
	s_cmp_eq_u32 s58, 12
	s_cselect_b32 s39, s19, s31
	s_cselect_b32 s38, s54, s30
	s_cselect_b32 s37, s17, s57
	s_cselect_b32 s36, s55, s56
	v_lshl_add_u64 v[218:219], s[26:27], 0, v[170:171]
	s_add_i32 m0, s25, 0xc000
	ds_read_b128 v[178:181], v186
	ds_read_b128 v[188:191], v186 offset:1024
	ds_read_b128 v[192:195], v186 offset:2048
	ds_read_b128 v[196:199], v186 offset:3072
	ds_read_b128 v[200:203], v186 offset:4096
	ds_read_b128 v[206:209], v186 offset:5120
	ds_read_b128 v[210:213], v186 offset:6144
	ds_read_b128 v[214:217], v186 offset:7168
	global_load_lds_dwordx4 v[218:219], off
	v_lshl_add_u64 v[218:219], s[26:27], 0, v[172:173]
	s_add_i32 m0, s25, 0xe000
	s_nop 0
	global_load_lds_dwordx4 v[218:219], off
	s_waitcnt vmcnt(8)
	s_waitcnt lgkmcnt(0)
	s_barrier
	s_setprio 1
	s_waitcnt lgkmcnt(0)
	v_mfma_f32_16x16x32_bf16 v[154:157], v[122:125], v[178:181], v[154:157]
	v_mfma_f32_16x16x32_bf16 v[138:141], v[130:133], v[178:181], v[138:141]
	v_mfma_f32_16x16x32_bf16 v[114:117], v[122:125], v[192:195], v[114:117]
	v_mfma_f32_16x16x32_bf16 v[106:109], v[130:133], v[192:195], v[106:109]
	v_mfma_f32_16x16x32_bf16 v[94:97], v[122:125], v[200:203], v[94:97]
	v_mfma_f32_16x16x32_bf16 v[90:93], v[130:133], v[200:203], v[90:93]
	v_mfma_f32_16x16x32_bf16 v[82:85], v[122:125], v[210:213], v[82:85]
	v_mfma_f32_16x16x32_bf16 v[74:77], v[130:133], v[210:213], v[74:77]
	v_mfma_f32_16x16x32_bf16 v[154:157], v[126:129], v[188:191], v[154:157]
	v_mfma_f32_16x16x32_bf16 v[138:141], v[134:137], v[188:191], v[138:141]
	v_mfma_f32_16x16x32_bf16 v[114:117], v[126:129], v[196:199], v[114:117]
	v_mfma_f32_16x16x32_bf16 v[106:109], v[134:137], v[196:199], v[106:109]
	v_mfma_f32_16x16x32_bf16 v[94:97], v[126:129], v[206:209], v[94:97]
	v_mfma_f32_16x16x32_bf16 v[90:93], v[134:137], v[206:209], v[90:93]
	v_mfma_f32_16x16x32_bf16 v[82:85], v[126:129], v[214:217], v[82:85]
	v_mfma_f32_16x16x32_bf16 v[74:77], v[134:137], v[214:217], v[74:77]
	s_setprio 0
	s_setprio 1
	v_mfma_f32_16x16x32_bf16 v[118:121], v[142:145], v[178:181], v[118:121]
	v_mfma_f32_16x16x32_bf16 v[110:113], v[150:153], v[178:181], v[110:113]
	v_mfma_f32_16x16x32_bf16 v[102:105], v[142:145], v[192:195], v[102:105]
	v_mfma_f32_16x16x32_bf16 v[98:101], v[150:153], v[192:195], v[98:101]
	v_mfma_f32_16x16x32_bf16 v[86:89], v[142:145], v[200:203], v[86:89]
	v_mfma_f32_16x16x32_bf16 v[78:81], v[150:153], v[200:203], v[78:81]
	v_mfma_f32_16x16x32_bf16 v[70:73], v[142:145], v[210:213], v[70:73]
	v_mfma_f32_16x16x32_bf16 v[66:69], v[150:153], v[210:213], v[66:69]
	v_mfma_f32_16x16x32_bf16 v[118:121], v[146:149], v[188:191], v[118:121]
	v_mfma_f32_16x16x32_bf16 v[110:113], v[158:161], v[188:191], v[110:113]
	v_mfma_f32_16x16x32_bf16 v[102:105], v[146:149], v[196:199], v[102:105]
	v_mfma_f32_16x16x32_bf16 v[98:101], v[158:161], v[196:199], v[98:101]
	v_mfma_f32_16x16x32_bf16 v[86:89], v[146:149], v[206:209], v[86:89]
	v_mfma_f32_16x16x32_bf16 v[78:81], v[158:161], v[206:209], v[78:81]
	v_mfma_f32_16x16x32_bf16 v[70:73], v[146:149], v[214:217], v[70:73]
	s_barrier
	v_mfma_f32_16x16x32_bf16 v[66:69], v[158:161], v[214:217], v[66:69]
	s_setprio 0
	s_add_i32 s30, s51, s33
	v_lshl_add_u64 v[218:219], s[36:37], 0, v[164:165]
	s_mov_b32 m0, s30
	ds_read_b128 v[178:181], v186 offset:16384
	ds_read_b128 v[188:191], v186 offset:17408
	ds_read_b128 v[192:195], v186 offset:18432
	ds_read_b128 v[196:199], v186 offset:19456
	ds_read_b128 v[200:203], v186 offset:20480
	ds_read_b128 v[206:209], v186 offset:21504
	ds_read_b128 v[210:213], v186 offset:22528
	ds_read_b128 v[214:217], v186 offset:23552
	global_load_lds_dwordx4 v[218:219], off
	s_add_i32 m0, s30, 0x2000
	s_add_u32 s30, s36, 0x40000
	v_lshl_add_u64 v[220:221], s[36:37], 0, v[168:169]
	s_addc_u32 s31, s37, 0
	s_add_i32 s59, s52, s33
	global_load_lds_dwordx4 v[220:221], off
	v_lshl_add_u64 v[222:223], s[30:31], 0, v[164:165]
	s_mov_b32 m0, s59
	v_lshl_add_u64 v[224:225], s[38:39], 0, v[166:167]
	global_load_lds_dwordx4 v[222:223], off
	v_lshl_add_u64 v[222:223], s[30:31], 0, v[168:169]
	s_add_i32 m0, s59, 0x2000
	s_nop 0
	global_load_lds_dwordx4 v[222:223], off
	v_lshl_add_u64 v[222:223], s[38:39], 0, v[162:163]
	s_mov_b32 m0, s25
	s_nop 0
	global_load_lds_dwordx4 v[222:223], off
	s_mov_b32 m0, s40
	s_nop 0
	global_load_lds_dwordx4 v[224:225], off
	s_waitcnt vmcnt(8)
	s_waitcnt lgkmcnt(0)
	s_barrier
; #define PG8_STAGE(bufoff, gbase, voff) do { _Pragma("unroll") for (int _i = 0; _i < 2; ++_i) \
;         __builtin_amdgcn_global_load_lds((const unsigned*)((const char*)(gbase) + (voff)[_i]), (PG8_LAS unsigned*)(lds + (bufoff) + ldsw + _i * 8192), 16, 0, 0); } while (0)
; #define PG8_LDA(dst, b, h) do { _Pragma("unroll") for (int m = 0; m < 4; ++m) _Pragma("unroll") for (int k = 0; k < 2; ++k) dst[m][k] = *(const PG8_LAS bf16x8*)(lds + PG8_SA(b, h) + aoff + m * 2048 + k * 1024); } while (0)
; #define PG8_LDB(dst, b, h) do { _Pragma("unroll") for (int n = 0; n < 2; ++n) _Pragma("unroll") for (int k = 0; k < 2; ++k) dst[n][k] = *(const PG8_LAS bf16x8*)(lds + PG8_SB(b, h) + boff + n * 2048 + k * 1024); } while (0)
; #define PG8_MMA(ai, bj, At, Bt) do { __builtin_amdgcn_s_setprio(1); _Pragma("unroll") for (int m = 0; m < 4; ++m) _Pragma("unroll") for (int n = 0; n < 2; ++n) _Pragma("unroll") for (int k = 0; k < 2; ++k) \
;         acc[ai][bj][m][n] = __builtin_amdgcn_mfma_f32_16x16x32_bf16(Bt[n][k], At[m][k], acc[ai][bj][m][n], 0, 0, 0); __builtin_amdgcn_s_setprio(0); } while (0)
; #define PG8_WAIT_V(n) asm volatile("s_waitcnt vmcnt(" #n ")" ::: "memory")
; #define PG8_WAIT_L(n) asm volatile("s_waitcnt lgkmcnt(" #n ")" ::: "memory")
; #define PG8_BAR __builtin_amdgcn_s_barrier()
; #define PG8_SCHED __builtin_amdgcn_sched_barrier(0)
; template <class Epi, class Sched, bool ALIGN_EPI = false, bool SP2 = false>
; __device__ __forceinline__ void gemm_phase(PG8_LAS unsigned char* lds, const Gemm g, const Sched& S, const Epi& E) {
;     ...
;             PG8_WAIT_V(8); PG8_WAIT_L(0); PG8_BAR; PG8_MMA(1, 0, At, B0); PG8_MMA(1, 1, At, B1); PG8_BAR; PG8_SCHED;
;             PG8_LDB(B0, 1, 0); PG8_LDB(B1, 1, 1); PG8_SCHED; PG8_LDA(At, 1, 0); PG8_STAGE(PG8_SA(0, 1), a2 + hstep, voffA);
;             PG8_WAIT_V(8); PG8_WAIT_L(0); PG8_BAR; PG8_MMA(0, 0, At, B0); PG8_MMA(0, 1, At, B1); PG8_BAR; PG8_SCHED;
	s_setprio 1
	s_waitcnt lgkmcnt(0)
	v_mfma_f32_16x16x32_bf16 v[62:65], v[122:125], v[178:181], v[62:65]
	v_mfma_f32_16x16x32_bf16 v[58:61], v[130:133], v[178:181], v[58:61]
	v_mfma_f32_16x16x32_bf16 v[50:53], v[122:125], v[192:195], v[50:53]
	v_mfma_f32_16x16x32_bf16 v[42:45], v[130:133], v[192:195], v[42:45]
	v_mfma_f32_16x16x32_bf16 v[30:33], v[122:125], v[200:203], v[30:33]
	v_mfma_f32_16x16x32_bf16 v[26:29], v[130:133], v[200:203], v[26:29]
	v_mfma_f32_16x16x32_bf16 v[18:21], v[122:125], v[210:213], v[18:21]
	v_mfma_f32_16x16x32_bf16 v[10:13], v[130:133], v[210:213], v[10:13]
	v_mfma_f32_16x16x32_bf16 v[62:65], v[126:129], v[188:191], v[62:65]
	v_mfma_f32_16x16x32_bf16 v[58:61], v[134:137], v[188:191], v[58:61]
	v_mfma_f32_16x16x32_bf16 v[50:53], v[126:129], v[196:199], v[50:53]
	v_mfma_f32_16x16x32_bf16 v[42:45], v[134:137], v[196:199], v[42:45]
	v_mfma_f32_16x16x32_bf16 v[30:33], v[126:129], v[206:209], v[30:33]
	v_mfma_f32_16x16x32_bf16 v[26:29], v[134:137], v[206:209], v[26:29]
	v_mfma_f32_16x16x32_bf16 v[18:21], v[126:129], v[214:217], v[18:21]
	v_mfma_f32_16x16x32_bf16 v[10:13], v[134:137], v[214:217], v[10:13]
	s_setprio 0
	s_setprio 1
	v_mfma_f32_16x16x32_bf16 v[54:57], v[142:145], v[178:181], v[54:57]
	v_mfma_f32_16x16x32_bf16 v[46:49], v[150:153], v[178:181], v[46:49]
	v_mfma_f32_16x16x32_bf16 v[38:41], v[142:145], v[192:195], v[38:41]
	v_mfma_f32_16x16x32_bf16 v[34:37], v[150:153], v[192:195], v[34:37]
	v_mfma_f32_16x16x32_bf16 v[22:25], v[142:145], v[200:203], v[22:25]
	v_mfma_f32_16x16x32_bf16 v[14:17], v[150:153], v[200:203], v[14:17]
	v_mfma_f32_16x16x32_bf16 v[6:9], v[142:145], v[210:213], v[6:9]
	v_mfma_f32_16x16x32_bf16 v[2:5], v[150:153], v[210:213], v[2:5]
	v_mfma_f32_16x16x32_bf16 v[54:57], v[146:149], v[188:191], v[54:57]
	v_mfma_f32_16x16x32_bf16 v[46:49], v[158:161], v[188:191], v[46:49]
	v_mfma_f32_16x16x32_bf16 v[38:41], v[146:149], v[196:199], v[38:41]
	v_mfma_f32_16x16x32_bf16 v[34:37], v[158:161], v[196:199], v[34:37]
	v_mfma_f32_16x16x32_bf16 v[22:25], v[146:149], v[206:209], v[22:25]
	v_mfma_f32_16x16x32_bf16 v[14:17], v[158:161], v[206:209], v[14:17]
	v_mfma_f32_16x16x32_bf16 v[6:9], v[146:149], v[214:217], v[6:9]
	s_barrier
	v_mfma_f32_16x16x32_bf16 v[2:5], v[158:161], v[214:217], v[2:5]
	s_setprio 0
	s_add_i32 s59, 0, 0x18000
	s_add_i32 s60, 0, 0x1c000
	v_add_u32_e32 v134, s59, v182
	v_add_u32_e32 v158, s60, v182
	ds_read_b128 v[122:125], v134
	ds_read_b128 v[126:129], v134 offset:1024
	ds_read_b128 v[130:133], v134 offset:2048
	ds_read_b128 v[134:137], v134 offset:3072
	ds_read_b128 v[142:145], v158
	ds_read_b128 v[146:149], v158 offset:1024
	ds_read_b128 v[150:153], v158 offset:2048
	ds_read_b128 v[158:161], v158 offset:3072
	s_add_u32 s30, s38, 0x40000
	s_addc_u32 s31, s39, 0
	s_mov_b32 m0, s41
	v_lshl_add_u64 v[226:227], s[30:31], 0, v[162:163]
	ds_read_b128 v[178:181], v186 offset:32768
	ds_read_b128 v[188:191], v186 offset:33792
	ds_read_b128 v[192:195], v186 offset:34816
	ds_read_b128 v[196:199], v186 offset:35840
	ds_read_b128 v[200:203], v186 offset:36864
	ds_read_b128 v[206:209], v186 offset:37888
	ds_read_b128 v[210:213], v186 offset:38912
	ds_read_b128 v[214:217], v186 offset:39936
	global_load_lds_dwordx4 v[226:227], off
	v_lshl_add_u64 v[226:227], s[30:31], 0, v[166:167]
	s_mov_b32 m0, s42
	s_nop 0
	global_load_lds_dwordx4 v[226:227], off
	s_waitcnt vmcnt(8)
	s_waitcnt lgkmcnt(0)
	s_barrier
	s_setprio 1
	s_waitcnt lgkmcnt(0)
	v_mfma_f32_16x16x32_bf16 v[154:157], v[122:125], v[178:181], v[154:157]
	v_mfma_f32_16x16x32_bf16 v[138:141], v[130:133], v[178:181], v[138:141]
	v_mfma_f32_16x16x32_bf16 v[114:117], v[122:125], v[192:195], v[114:117]
	v_mfma_f32_16x16x32_bf16 v[106:109], v[130:133], v[192:195], v[106:109]
	v_mfma_f32_16x16x32_bf16 v[94:97], v[122:125], v[200:203], v[94:97]
	v_mfma_f32_16x16x32_bf16 v[90:93], v[130:133], v[200:203], v[90:93]
	v_mfma_f32_16x16x32_bf16 v[82:85], v[122:125], v[210:213], v[82:85]
	v_mfma_f32_16x16x32_bf16 v[74:77], v[130:133], v[210:213], v[74:77]
	v_mfma_f32_16x16x32_bf16 v[154:157], v[126:129], v[188:191], v[154:157]
	v_mfma_f32_16x16x32_bf16 v[138:141], v[134:137], v[188:191], v[138:141]
	v_mfma_f32_16x16x32_bf16 v[114:117], v[126:129], v[196:199], v[114:117]
	v_mfma_f32_16x16x32_bf16 v[106:109], v[134:137], v[196:199], v[106:109]
	v_mfma_f32_16x16x32_bf16 v[94:97], v[126:129], v[206:209], v[94:97]
	v_mfma_f32_16x16x32_bf16 v[90:93], v[134:137], v[206:209], v[90:93]
	v_mfma_f32_16x16x32_bf16 v[82:85], v[126:129], v[214:217], v[82:85]
	v_mfma_f32_16x16x32_bf16 v[74:77], v[134:137], v[214:217], v[74:77]
	s_setprio 0
	s_setprio 1
	v_mfma_f32_16x16x32_bf16 v[118:121], v[142:145], v[178:181], v[118:121]
	v_mfma_f32_16x16x32_bf16 v[110:113], v[150:153], v[178:181], v[110:113]
	v_mfma_f32_16x16x32_bf16 v[102:105], v[142:145], v[192:195], v[102:105]
	v_mfma_f32_16x16x32_bf16 v[98:101], v[150:153], v[192:195], v[98:101]
	v_mfma_f32_16x16x32_bf16 v[86:89], v[142:145], v[200:203], v[86:89]
	v_mfma_f32_16x16x32_bf16 v[78:81], v[150:153], v[200:203], v[78:81]
	v_mfma_f32_16x16x32_bf16 v[70:73], v[142:145], v[210:213], v[70:73]
	v_mfma_f32_16x16x32_bf16 v[66:69], v[150:153], v[210:213], v[66:69]
	v_mfma_f32_16x16x32_bf16 v[118:121], v[146:149], v[188:191], v[118:121]
	v_mfma_f32_16x16x32_bf16 v[110:113], v[158:161], v[188:191], v[110:113]
	v_mfma_f32_16x16x32_bf16 v[102:105], v[146:149], v[196:199], v[102:105]
	v_mfma_f32_16x16x32_bf16 v[98:101], v[158:161], v[196:199], v[98:101]
	v_mfma_f32_16x16x32_bf16 v[86:89], v[146:149], v[206:209], v[86:89]
	v_mfma_f32_16x16x32_bf16 v[78:81], v[158:161], v[206:209], v[78:81]
	v_mfma_f32_16x16x32_bf16 v[70:73], v[146:149], v[214:217], v[70:73]
	s_barrier
; #define PG8_STAGE(bufoff, gbase, voff) do { _Pragma("unroll") for (int _i = 0; _i < 2; ++_i) \
;         __builtin_amdgcn_global_load_lds((const unsigned*)((const char*)(gbase) + (voff)[_i]), (PG8_LAS unsigned*)(lds + (bufoff) + ldsw + _i * 8192), 16, 0, 0); } while (0)
; #define PG8_LDA(dst, b, h) do { _Pragma("unroll") for (int m = 0; m < 4; ++m) _Pragma("unroll") for (int k = 0; k < 2; ++k) dst[m][k] = *(const PG8_LAS bf16x8*)(lds + PG8_SA(b, h) + aoff + m * 2048 + k * 1024); } while (0)
; #define PG8_MMA(ai, bj, At, Bt) do { __builtin_amdgcn_s_setprio(1); _Pragma("unroll") for (int m = 0; m < 4; ++m) _Pragma("unroll") for (int n = 0; n < 2; ++n) _Pragma("unroll") for (int k = 0; k < 2; ++k) \
;         acc[ai][bj][m][n] = __builtin_amdgcn_mfma_f32_16x16x32_bf16(Bt[n][k], At[m][k], acc[ai][bj][m][n], 0, 0, 0); __builtin_amdgcn_s_setprio(0); } while (0)
; #define PG8_WAIT_V(n) asm volatile("s_waitcnt vmcnt(" #n ")" ::: "memory")
; #define PG8_WAIT_L(n) asm volatile("s_waitcnt lgkmcnt(" #n ")" ::: "memory")
; #define PG8_BAR __builtin_amdgcn_s_barrier()
; #define PG8_SCHED __builtin_amdgcn_sched_barrier(0)
; template <class Epi, class Sched, bool ALIGN_EPI = false, bool SP2 = false>
; __device__ __forceinline__ void gemm_phase(PG8_LAS unsigned char* lds, const Gemm g, const Sched& S, const Epi& E) {
;     ...
;         for (int t = 0; t < nt; t += 2) {
;             const bool last = (t == nt - 2);
;             const char* a1 = cA + (size_t)(t + 1) * kstep;
;             const char* a2 = last ? nA : cA + (size_t)(t + 2) * kstep; const char* b2 = last ? nB : cB + (size_t)(t + 2) * kstep;
;             const char* a3 = a2 + kstep; const char* b3 = b2 + kstep;
;     ...
;             PG8_WAIT_V(8); PG8_WAIT_L(0); PG8_BAR; PG8_MMA(0, 0, At, B0); PG8_MMA(0, 1, At, B1); PG8_BAR; PG8_SCHED;
;             PG8_LDA(At, 1, 1); PG8_STAGE(PG8_SB(1, 0), b3, voffB); PG8_STAGE(PG8_SB(1, 1), b3 + hstep, voffB); PG8_STAGE(PG8_SA(1, 0), a3, voffA);
;             PG8_WAIT_V(8); PG8_WAIT_L(0); PG8_BAR; PG8_MMA(1, 0, At, B0); PG8_MMA(1, 1, At, B1); PG8_BAR; PG8_SCHED;
;     ...
;         if constexpr (ALIGN_EPI) { if (wr == 0) PG8_BAR; }
	v_mfma_f32_16x16x32_bf16 v[66:69], v[158:161], v[214:217], v[66:69]
	s_setprio 0
	s_add_i32 s30, s59, s33
	v_lshl_add_u64 v[218:219], v[218:219], 0, s[10:11]
	s_mov_b32 m0, s30
	ds_read_b128 v[178:181], v186 offset:49152
	ds_read_b128 v[188:191], v186 offset:50176
	ds_read_b128 v[192:195], v186 offset:51200
	ds_read_b128 v[196:199], v186 offset:52224
	ds_read_b128 v[200:203], v186 offset:53248
	ds_read_b128 v[206:209], v186 offset:54272
	ds_read_b128 v[210:213], v186 offset:55296
	ds_read_b128 v[214:217], v186 offset:56320
	global_load_lds_dwordx4 v[218:219], off
	s_add_i32 m0, s30, 0x2000
	s_add_u32 s30, s36, 0x40080
	v_lshl_add_u64 v[218:219], v[220:221], 0, s[10:11]
	s_addc_u32 s31, s37, 0
	s_add_i32 s36, s60, s33
	global_load_lds_dwordx4 v[218:219], off
	v_lshl_add_u64 v[218:219], s[30:31], 0, v[164:165]
	s_mov_b32 m0, s36
	s_nop 0
	global_load_lds_dwordx4 v[218:219], off
	v_lshl_add_u64 v[218:219], s[30:31], 0, v[168:169]
	s_add_i32 m0, s36, 0x2000
	s_nop 0
	global_load_lds_dwordx4 v[218:219], off
	v_lshl_add_u64 v[218:219], v[222:223], 0, s[10:11]
	s_mov_b32 m0, s44
	s_nop 0
	global_load_lds_dwordx4 v[218:219], off
	v_lshl_add_u64 v[218:219], v[224:225], 0, s[10:11]
	s_mov_b32 m0, s45
	s_nop 0
	global_load_lds_dwordx4 v[218:219], off
	s_waitcnt vmcnt(8)
	s_waitcnt lgkmcnt(0)
	s_barrier
	s_setprio 1
	s_waitcnt lgkmcnt(0)
	v_mfma_f32_16x16x32_bf16 v[62:65], v[122:125], v[178:181], v[62:65]
	v_mfma_f32_16x16x32_bf16 v[58:61], v[130:133], v[178:181], v[58:61]
	v_mfma_f32_16x16x32_bf16 v[50:53], v[122:125], v[192:195], v[50:53]
	v_mfma_f32_16x16x32_bf16 v[42:45], v[130:133], v[192:195], v[42:45]
	v_mfma_f32_16x16x32_bf16 v[30:33], v[122:125], v[200:203], v[30:33]
	v_mfma_f32_16x16x32_bf16 v[26:29], v[130:133], v[200:203], v[26:29]
	v_mfma_f32_16x16x32_bf16 v[18:21], v[122:125], v[210:213], v[18:21]
	v_mfma_f32_16x16x32_bf16 v[10:13], v[130:133], v[210:213], v[10:13]
	v_mfma_f32_16x16x32_bf16 v[62:65], v[126:129], v[188:191], v[62:65]
	v_mfma_f32_16x16x32_bf16 v[58:61], v[134:137], v[188:191], v[58:61]
	v_mfma_f32_16x16x32_bf16 v[50:53], v[126:129], v[196:199], v[50:53]
	v_mfma_f32_16x16x32_bf16 v[42:45], v[134:137], v[196:199], v[42:45]
	v_mfma_f32_16x16x32_bf16 v[30:33], v[126:129], v[206:209], v[30:33]
	v_mfma_f32_16x16x32_bf16 v[26:29], v[134:137], v[206:209], v[26:29]
	v_mfma_f32_16x16x32_bf16 v[18:21], v[126:129], v[214:217], v[18:21]
	v_mfma_f32_16x16x32_bf16 v[10:13], v[134:137], v[214:217], v[10:13]
	s_setprio 0
	s_setprio 1
	v_mfma_f32_16x16x32_bf16 v[54:57], v[142:145], v[178:181], v[54:57]
	v_mfma_f32_16x16x32_bf16 v[46:49], v[150:153], v[178:181], v[46:49]
	v_mfma_f32_16x16x32_bf16 v[38:41], v[142:145], v[192:195], v[38:41]
	v_mfma_f32_16x16x32_bf16 v[34:37], v[150:153], v[192:195], v[34:37]
	v_mfma_f32_16x16x32_bf16 v[22:25], v[142:145], v[200:203], v[22:25]
	v_mfma_f32_16x16x32_bf16 v[14:17], v[150:153], v[200:203], v[14:17]
	v_mfma_f32_16x16x32_bf16 v[6:9], v[142:145], v[210:213], v[6:9]
	v_mfma_f32_16x16x32_bf16 v[2:5], v[150:153], v[210:213], v[2:5]
	v_mfma_f32_16x16x32_bf16 v[54:57], v[146:149], v[188:191], v[54:57]
	v_mfma_f32_16x16x32_bf16 v[46:49], v[158:161], v[188:191], v[46:49]
	v_mfma_f32_16x16x32_bf16 v[38:41], v[146:149], v[196:199], v[38:41]
	v_mfma_f32_16x16x32_bf16 v[34:37], v[158:161], v[196:199], v[34:37]
	v_mfma_f32_16x16x32_bf16 v[22:25], v[146:149], v[206:209], v[22:25]
	v_mfma_f32_16x16x32_bf16 v[14:17], v[158:161], v[206:209], v[14:17]
	v_mfma_f32_16x16x32_bf16 v[6:9], v[146:149], v[214:217], v[6:9]
	s_barrier
	v_mfma_f32_16x16x32_bf16 v[2:5], v[158:161], v[214:217], v[2:5]
	s_setprio 0
	s_add_i32 s58, s58, 2
	s_add_u32 s26, s26, 0x100
	s_addc_u32 s27, s27, 0
	s_add_u32 s56, s56, 0x100
	s_addc_u32 s57, s57, 0
	s_cmp_gt_u32 s58, 13
	s_cbranch_scc0 .LBB0_1673
	s_and_b64 vcc, exec, s[12:13]
	s_cbranch_vccz .LBB0_1676
	s_barrier

; #define PG8_STAGE(bufoff, gbase, voff) do { _Pragma("unroll") for (int _i = 0; _i < 2; ++_i) \
;         __builtin_amdgcn_global_load_lds((const unsigned*)((const char*)(gbase) + (voff)[_i]), (PG8_LAS unsigned*)(lds + (bufoff) + ldsw + _i * 8192), 16, 0, 0); } while (0)
; #define PG8_LDA(dst, b, h) do { _Pragma("unroll") for (int m = 0; m < 4; ++m) _Pragma("unroll") for (int k = 0; k < 2; ++k) dst[m][k] = *(const PG8_LAS bf16x8*)(lds + PG8_SA(b, h) + aoff + m * 2048 + k * 1024); } while (0)
; #define PG8_LDB(dst, b, h) do { _Pragma("unroll") for (int n = 0; n < 2; ++n) _Pragma("unroll") for (int k = 0; k < 2; ++k) dst[n][k] = *(const PG8_LAS bf16x8*)(lds + PG8_SB(b, h) + boff + n * 2048 + k * 1024); } while (0)
; #define PG8_MMA(ai, bj, At, Bt) do { __builtin_amdgcn_s_setprio(1); _Pragma("unroll") for (int m = 0; m < 4; ++m) _Pragma("unroll") for (int n = 0; n < 2; ++n) _Pragma("unroll") for (int k = 0; k < 2; ++k) \
;         acc[ai][bj][m][n] = __builtin_amdgcn_mfma_f32_16x16x32_bf16(Bt[n][k], At[m][k], acc[ai][bj][m][n], 0, 0, 0); __builtin_amdgcn_s_setprio(0); } while (0)
; #define PG8_WAIT_V(n) asm volatile("s_waitcnt vmcnt(" #n ")" ::: "memory")
; #define PG8_WAIT_L(n) asm volatile("s_waitcnt lgkmcnt(" #n ")" ::: "memory")
; #define PG8_BAR __builtin_amdgcn_s_barrier()
; #define PG8_SCHED __builtin_amdgcn_sched_barrier(0)
; template <class Epi, class Sched, bool ALIGN_EPI = false, bool SP2 = false>
; __device__ __forceinline__ void gemm_phase(PG8_LAS unsigned char* lds, const Gemm g, const Sched& S, const Epi& E) {
;     ...
;             const bool last = (t == nt - 2);
;             const char* a1 = cA + (size_t)(t + 1) * kstep;
;             const char* a2 = last ? nA : cA + (size_t)(t + 2) * kstep; const char* b2 = last ? nB : cB + (size_t)(t + 2) * kstep;
;             const char* a3 = a2 + kstep; const char* b3 = b2 + kstep;
;             if (last && has_next) S.a_ready(nxt);
;             if constexpr (SP2) {
;             PG8_LDB(B0, 0, 0); PG8_LDB(B1, 0, 1); PG8_SCHED; PG8_LDA(At, 0, 0); PG8_STAGE(PG8_SA(1, 1), a1 + hstep, voffA);
;             PG8_WAIT_V(8); PG8_WAIT_L(0); PG8_BAR; PG8_MMA(0, 0, At, B0); PG8_MMA(0, 1, At, B1); PG8_BAR; PG8_SCHED;
;             PG8_LDA(At, 0, 1); PG8_STAGE(PG8_SB(0, 0), b2, voffB); PG8_STAGE(PG8_SB(0, 1), b2 + hstep, voffB); PG8_STAGE(PG8_SA(0, 0), a2, voffA);
.LBB0_1822:
	ds_read_b128 v[154:157], v150
	ds_read_b128 v[158:161], v150 offset:1024
	ds_read_b128 v[162:165], v150 offset:2048
	ds_read_b128 v[166:169], v150 offset:3072
	ds_read_b128 v[170:173], v151
	ds_read_b128 v[174:177], v151 offset:1024
	ds_read_b128 v[178:181], v151 offset:2048
	ds_read_b128 v[182:185], v151 offset:3072
	s_add_u32 s30, s40, 0xfffc0080
	s_addc_u32 s31, s41, -1
	s_cmp_eq_u32 s69, 12
	s_cselect_b32 s45, s25, s31
	s_cselect_b32 s44, s65, s30
	s_cselect_b32 s43, s23, s68
	s_cselect_b32 s42, s66, s67
	v_lshl_add_u64 v[146:147], s[40:41], 0, v[138:139]
	s_add_i32 m0, s39, 0xc000
	ds_read_b128 v[186:189], v152
	ds_read_b128 v[190:193], v152 offset:1024
	ds_read_b128 v[194:197], v152 offset:2048
	ds_read_b128 v[198:201], v152 offset:3072
	ds_read_b128 v[206:209], v152 offset:4096
	ds_read_b128 v[210:213], v152 offset:5120
	ds_read_b128 v[214:217], v152 offset:6144
	ds_read_b128 v[218:221], v152 offset:7168
	global_load_lds_dwordx4 v[146:147], off
	v_lshl_add_u64 v[146:147], s[40:41], 0, v[140:141]
	s_add_i32 m0, s39, 0xe000
	s_nop 0
	global_load_lds_dwordx4 v[146:147], off
	s_waitcnt vmcnt(8)
	s_waitcnt lgkmcnt(0)
	s_barrier
	s_setprio 1
	s_waitcnt lgkmcnt(0)
	v_mfma_f32_16x16x32_bf16 v[126:129], v[154:157], v[186:189], v[126:129]
	v_mfma_f32_16x16x32_bf16 v[122:125], v[162:165], v[186:189], v[122:125]
	v_mfma_f32_16x16x32_bf16 v[114:117], v[154:157], v[194:197], v[114:117]
	v_mfma_f32_16x16x32_bf16 v[106:109], v[162:165], v[194:197], v[106:109]
	v_mfma_f32_16x16x32_bf16 v[98:101], v[154:157], v[206:209], v[98:101]
	v_mfma_f32_16x16x32_bf16 v[90:93], v[162:165], v[206:209], v[90:93]
	v_mfma_f32_16x16x32_bf16 v[82:85], v[154:157], v[214:217], v[82:85]
	v_mfma_f32_16x16x32_bf16 v[74:77], v[162:165], v[214:217], v[74:77]
	v_mfma_f32_16x16x32_bf16 v[126:129], v[158:161], v[190:193], v[126:129]
	v_mfma_f32_16x16x32_bf16 v[122:125], v[166:169], v[190:193], v[122:125]
	v_mfma_f32_16x16x32_bf16 v[114:117], v[158:161], v[198:201], v[114:117]
	v_mfma_f32_16x16x32_bf16 v[106:109], v[166:169], v[198:201], v[106:109]
	v_mfma_f32_16x16x32_bf16 v[98:101], v[158:161], v[210:213], v[98:101]
	v_mfma_f32_16x16x32_bf16 v[90:93], v[166:169], v[210:213], v[90:93]
	v_mfma_f32_16x16x32_bf16 v[82:85], v[158:161], v[218:221], v[82:85]
	v_mfma_f32_16x16x32_bf16 v[74:77], v[166:169], v[218:221], v[74:77]
	s_setprio 0
	s_setprio 1
	v_mfma_f32_16x16x32_bf16 v[118:121], v[170:173], v[186:189], v[118:121]
	v_mfma_f32_16x16x32_bf16 v[110:113], v[178:181], v[186:189], v[110:113]
	v_mfma_f32_16x16x32_bf16 v[102:105], v[170:173], v[194:197], v[102:105]
	v_mfma_f32_16x16x32_bf16 v[94:97], v[178:181], v[194:197], v[94:97]
	v_mfma_f32_16x16x32_bf16 v[86:89], v[170:173], v[206:209], v[86:89]
	v_mfma_f32_16x16x32_bf16 v[78:81], v[178:181], v[206:209], v[78:81]
	v_mfma_f32_16x16x32_bf16 v[70:73], v[170:173], v[214:217], v[70:73]
	v_mfma_f32_16x16x32_bf16 v[66:69], v[178:181], v[214:217], v[66:69]
	v_mfma_f32_16x16x32_bf16 v[118:121], v[174:177], v[190:193], v[118:121]
	v_mfma_f32_16x16x32_bf16 v[110:113], v[182:185], v[190:193], v[110:113]
	v_mfma_f32_16x16x32_bf16 v[102:105], v[174:177], v[198:201], v[102:105]
	v_mfma_f32_16x16x32_bf16 v[94:97], v[182:185], v[198:201], v[94:97]
	v_mfma_f32_16x16x32_bf16 v[86:89], v[174:177], v[210:213], v[86:89]
	v_mfma_f32_16x16x32_bf16 v[78:81], v[182:185], v[210:213], v[78:81]
	v_mfma_f32_16x16x32_bf16 v[70:73], v[174:177], v[218:221], v[70:73]
	s_barrier
	v_mfma_f32_16x16x32_bf16 v[66:69], v[182:185], v[218:221], v[66:69]
	s_setprio 0
	s_add_i32 s30, s58, s50
	v_lshl_add_u64 v[146:147], s[42:43], 0, v[132:133]
	s_mov_b32 m0, s30
	ds_read_b128 v[186:189], v152 offset:16384
	ds_read_b128 v[190:193], v152 offset:17408
	ds_read_b128 v[194:197], v152 offset:18432
	ds_read_b128 v[198:201], v152 offset:19456
	ds_read_b128 v[206:209], v152 offset:20480
	ds_read_b128 v[210:213], v152 offset:21504
	ds_read_b128 v[214:217], v152 offset:22528
	ds_read_b128 v[218:221], v152 offset:23552
	global_load_lds_dwordx4 v[146:147], off
	s_add_i32 m0, s30, 0x2000
	s_add_u32 s30, s42, 0x40000
	v_lshl_add_u64 v[202:203], s[42:43], 0, v[136:137]
	s_addc_u32 s31, s43, 0
	s_add_i32 s70, s59, s50
	global_load_lds_dwordx4 v[202:203], off
	v_lshl_add_u64 v[222:223], s[30:31], 0, v[132:133]
	s_mov_b32 m0, s70
	v_lshl_add_u64 v[224:225], s[44:45], 0, v[134:135]
	global_load_lds_dwordx4 v[222:223], off
	v_lshl_add_u64 v[222:223], s[30:31], 0, v[136:137]
	s_add_i32 m0, s70, 0x2000
	s_nop 0
	global_load_lds_dwordx4 v[222:223], off
	v_lshl_add_u64 v[222:223], s[44:45], 0, v[130:131]
	s_mov_b32 m0, s39
	s_nop 0
	global_load_lds_dwordx4 v[222:223], off
	s_mov_b32 m0, s51
	s_nop 0
	global_load_lds_dwordx4 v[224:225], off
	s_waitcnt vmcnt(8)
	s_waitcnt lgkmcnt(0)
	s_barrier
; #define PG8_STAGE(bufoff, gbase, voff) do { _Pragma("unroll") for (int _i = 0; _i < 2; ++_i) \
;         __builtin_amdgcn_global_load_lds((const unsigned*)((const char*)(gbase) + (voff)[_i]), (PG8_LAS unsigned*)(lds + (bufoff) + ldsw + _i * 8192), 16, 0, 0); } while (0)
; #define PG8_LDA(dst, b, h) do { _Pragma("unroll") for (int m = 0; m < 4; ++m) _Pragma("unroll") for (int k = 0; k < 2; ++k) dst[m][k] = *(const PG8_LAS bf16x8*)(lds + PG8_SA(b, h) + aoff + m * 2048 + k * 1024); } while (0)
; #define PG8_LDB(dst, b, h) do { _Pragma("unroll") for (int n = 0; n < 2; ++n) _Pragma("unroll") for (int k = 0; k < 2; ++k) dst[n][k] = *(const PG8_LAS bf16x8*)(lds + PG8_SB(b, h) + boff + n * 2048 + k * 1024); } while (0)
; #define PG8_MMA(ai, bj, At, Bt) do { __builtin_amdgcn_s_setprio(1); _Pragma("unroll") for (int m = 0; m < 4; ++m) _Pragma("unroll") for (int n = 0; n < 2; ++n) _Pragma("unroll") for (int k = 0; k < 2; ++k) \
;         acc[ai][bj][m][n] = __builtin_amdgcn_mfma_f32_16x16x32_bf16(Bt[n][k], At[m][k], acc[ai][bj][m][n], 0, 0, 0); __builtin_amdgcn_s_setprio(0); } while (0)
; #define PG8_WAIT_V(n) asm volatile("s_waitcnt vmcnt(" #n ")" ::: "memory")
; #define PG8_WAIT_L(n) asm volatile("s_waitcnt lgkmcnt(" #n ")" ::: "memory")
; #define PG8_BAR __builtin_amdgcn_s_barrier()
; #define PG8_SCHED __builtin_amdgcn_sched_barrier(0)
; template <class Epi, class Sched, bool ALIGN_EPI = false, bool SP2 = false>
; __device__ __forceinline__ void gemm_phase(PG8_LAS unsigned char* lds, const Gemm g, const Sched& S, const Epi& E) {
;     ...
;             PG8_WAIT_V(8); PG8_WAIT_L(0); PG8_BAR; PG8_MMA(1, 0, At, B0); PG8_MMA(1, 1, At, B1); PG8_BAR; PG8_SCHED;
;             PG8_LDB(B0, 1, 0); PG8_LDB(B1, 1, 1); PG8_SCHED; PG8_LDA(At, 1, 0); PG8_STAGE(PG8_SA(0, 1), a2 + hstep, voffA);
;             PG8_WAIT_V(8); PG8_WAIT_L(0); PG8_BAR; PG8_MMA(0, 0, At, B0); PG8_MMA(0, 1, At, B1); PG8_BAR; PG8_SCHED;
	s_setprio 1
	s_waitcnt lgkmcnt(0)
	v_mfma_f32_16x16x32_bf16 v[62:65], v[154:157], v[186:189], v[62:65]
	v_mfma_f32_16x16x32_bf16 v[58:61], v[162:165], v[186:189], v[58:61]
	v_mfma_f32_16x16x32_bf16 v[50:53], v[154:157], v[194:197], v[50:53]
	v_mfma_f32_16x16x32_bf16 v[42:45], v[162:165], v[194:197], v[42:45]
	v_mfma_f32_16x16x32_bf16 v[34:37], v[154:157], v[206:209], v[34:37]
	v_mfma_f32_16x16x32_bf16 v[26:29], v[162:165], v[206:209], v[26:29]
	v_mfma_f32_16x16x32_bf16 v[18:21], v[154:157], v[214:217], v[18:21]
	v_mfma_f32_16x16x32_bf16 v[10:13], v[162:165], v[214:217], v[10:13]
	v_mfma_f32_16x16x32_bf16 v[62:65], v[158:161], v[190:193], v[62:65]
	v_mfma_f32_16x16x32_bf16 v[58:61], v[166:169], v[190:193], v[58:61]
	v_mfma_f32_16x16x32_bf16 v[50:53], v[158:161], v[198:201], v[50:53]
	v_mfma_f32_16x16x32_bf16 v[42:45], v[166:169], v[198:201], v[42:45]
	v_mfma_f32_16x16x32_bf16 v[34:37], v[158:161], v[210:213], v[34:37]
	v_mfma_f32_16x16x32_bf16 v[26:29], v[166:169], v[210:213], v[26:29]
	v_mfma_f32_16x16x32_bf16 v[18:21], v[158:161], v[218:221], v[18:21]
	v_mfma_f32_16x16x32_bf16 v[10:13], v[166:169], v[218:221], v[10:13]
	s_setprio 0
	s_setprio 1
	v_mfma_f32_16x16x32_bf16 v[54:57], v[170:173], v[186:189], v[54:57]
	v_mfma_f32_16x16x32_bf16 v[46:49], v[178:181], v[186:189], v[46:49]
	v_mfma_f32_16x16x32_bf16 v[38:41], v[170:173], v[194:197], v[38:41]
	v_mfma_f32_16x16x32_bf16 v[30:33], v[178:181], v[194:197], v[30:33]
	v_mfma_f32_16x16x32_bf16 v[22:25], v[170:173], v[206:209], v[22:25]
	v_mfma_f32_16x16x32_bf16 v[14:17], v[178:181], v[206:209], v[14:17]
	v_mfma_f32_16x16x32_bf16 v[6:9], v[170:173], v[214:217], v[6:9]
	v_mfma_f32_16x16x32_bf16 v[2:5], v[178:181], v[214:217], v[2:5]
	v_mfma_f32_16x16x32_bf16 v[54:57], v[174:177], v[190:193], v[54:57]
	v_mfma_f32_16x16x32_bf16 v[46:49], v[182:185], v[190:193], v[46:49]
	v_mfma_f32_16x16x32_bf16 v[38:41], v[174:177], v[198:201], v[38:41]
	v_mfma_f32_16x16x32_bf16 v[30:33], v[182:185], v[198:201], v[30:33]
	v_mfma_f32_16x16x32_bf16 v[22:25], v[174:177], v[210:213], v[22:25]
	v_mfma_f32_16x16x32_bf16 v[14:17], v[182:185], v[210:213], v[14:17]
	v_mfma_f32_16x16x32_bf16 v[6:9], v[174:177], v[218:221], v[6:9]
	s_barrier
	v_mfma_f32_16x16x32_bf16 v[2:5], v[182:185], v[218:221], v[2:5]
	s_setprio 0
	s_add_i32 s70, 0, 0x18000
	v_add_u32_e32 v153, s70, v148
	s_add_i32 s71, 0, 0x1c000
	ds_read_b128 v[154:157], v153
	ds_read_b128 v[158:161], v153 offset:1024
	ds_read_b128 v[162:165], v153 offset:2048
	ds_read_b128 v[166:169], v153 offset:3072
	v_add_u32_e32 v153, s71, v148
	ds_read_b128 v[170:173], v153
	ds_read_b128 v[174:177], v153 offset:1024
	ds_read_b128 v[178:181], v153 offset:2048
	ds_read_b128 v[182:185], v153 offset:3072
	s_add_u32 s30, s44, 0x40000
	s_addc_u32 s31, s45, 0
	s_mov_b32 m0, s52
	v_lshl_add_u64 v[226:227], s[30:31], 0, v[130:131]
	ds_read_b128 v[186:189], v152 offset:32768
	ds_read_b128 v[190:193], v152 offset:33792
	ds_read_b128 v[194:197], v152 offset:34816
	ds_read_b128 v[198:201], v152 offset:35840
	ds_read_b128 v[206:209], v152 offset:36864
	ds_read_b128 v[210:213], v152 offset:37888
	ds_read_b128 v[214:217], v152 offset:38912
	ds_read_b128 v[218:221], v152 offset:39936
	global_load_lds_dwordx4 v[226:227], off
	v_lshl_add_u64 v[226:227], s[30:31], 0, v[134:135]
	s_mov_b32 m0, s53
	s_nop 0
	global_load_lds_dwordx4 v[226:227], off
	s_waitcnt vmcnt(8)
	s_waitcnt lgkmcnt(0)
	s_barrier
	s_setprio 1
	s_waitcnt lgkmcnt(0)
	v_mfma_f32_16x16x32_bf16 v[126:129], v[154:157], v[186:189], v[126:129]
	v_mfma_f32_16x16x32_bf16 v[122:125], v[162:165], v[186:189], v[122:125]
	v_mfma_f32_16x16x32_bf16 v[114:117], v[154:157], v[194:197], v[114:117]
	v_mfma_f32_16x16x32_bf16 v[106:109], v[162:165], v[194:197], v[106:109]
	v_mfma_f32_16x16x32_bf16 v[98:101], v[154:157], v[206:209], v[98:101]
	v_mfma_f32_16x16x32_bf16 v[90:93], v[162:165], v[206:209], v[90:93]
	v_mfma_f32_16x16x32_bf16 v[82:85], v[154:157], v[214:217], v[82:85]
	v_mfma_f32_16x16x32_bf16 v[74:77], v[162:165], v[214:217], v[74:77]
	v_mfma_f32_16x16x32_bf16 v[126:129], v[158:161], v[190:193], v[126:129]
	v_mfma_f32_16x16x32_bf16 v[122:125], v[166:169], v[190:193], v[122:125]
	v_mfma_f32_16x16x32_bf16 v[114:117], v[158:161], v[198:201], v[114:117]
	v_mfma_f32_16x16x32_bf16 v[106:109], v[166:169], v[198:201], v[106:109]
	v_mfma_f32_16x16x32_bf16 v[98:101], v[158:161], v[210:213], v[98:101]
	v_mfma_f32_16x16x32_bf16 v[90:93], v[166:169], v[210:213], v[90:93]
	v_mfma_f32_16x16x32_bf16 v[82:85], v[158:161], v[218:221], v[82:85]
	v_mfma_f32_16x16x32_bf16 v[74:77], v[166:169], v[218:221], v[74:77]
	s_setprio 0
	s_setprio 1
	v_mfma_f32_16x16x32_bf16 v[118:121], v[170:173], v[186:189], v[118:121]
	v_mfma_f32_16x16x32_bf16 v[110:113], v[178:181], v[186:189], v[110:113]
	v_mfma_f32_16x16x32_bf16 v[102:105], v[170:173], v[194:197], v[102:105]
	v_mfma_f32_16x16x32_bf16 v[94:97], v[178:181], v[194:197], v[94:97]
	v_mfma_f32_16x16x32_bf16 v[86:89], v[170:173], v[206:209], v[86:89]
	v_mfma_f32_16x16x32_bf16 v[78:81], v[178:181], v[206:209], v[78:81]
	v_mfma_f32_16x16x32_bf16 v[70:73], v[170:173], v[214:217], v[70:73]
	v_mfma_f32_16x16x32_bf16 v[66:69], v[178:181], v[214:217], v[66:69]
	v_mfma_f32_16x16x32_bf16 v[118:121], v[174:177], v[190:193], v[118:121]
	v_mfma_f32_16x16x32_bf16 v[110:113], v[182:185], v[190:193], v[110:113]
	v_mfma_f32_16x16x32_bf16 v[102:105], v[174:177], v[198:201], v[102:105]
	v_mfma_f32_16x16x32_bf16 v[94:97], v[182:185], v[198:201], v[94:97]
	v_mfma_f32_16x16x32_bf16 v[86:89], v[174:177], v[210:213], v[86:89]
	v_mfma_f32_16x16x32_bf16 v[78:81], v[182:185], v[210:213], v[78:81]
	v_mfma_f32_16x16x32_bf16 v[70:73], v[174:177], v[218:221], v[70:73]
	s_barrier
; #define PG8_STAGE(bufoff, gbase, voff) do { _Pragma("unroll") for (int _i = 0; _i < 2; ++_i) \
;         __builtin_amdgcn_global_load_lds((const unsigned*)((const char*)(gbase) + (voff)[_i]), (PG8_LAS unsigned*)(lds + (bufoff) + ldsw + _i * 8192), 16, 0, 0); } while (0)
; #define PG8_LDA(dst, b, h) do { _Pragma("unroll") for (int m = 0; m < 4; ++m) _Pragma("unroll") for (int k = 0; k < 2; ++k) dst[m][k] = *(const PG8_LAS bf16x8*)(lds + PG8_SA(b, h) + aoff + m * 2048 + k * 1024); } while (0)
; #define PG8_MMA(ai, bj, At, Bt) do { __builtin_amdgcn_s_setprio(1); _Pragma("unroll") for (int m = 0; m < 4; ++m) _Pragma("unroll") for (int n = 0; n < 2; ++n) _Pragma("unroll") for (int k = 0; k < 2; ++k) \
;         acc[ai][bj][m][n] = __builtin_amdgcn_mfma_f32_16x16x32_bf16(Bt[n][k], At[m][k], acc[ai][bj][m][n], 0, 0, 0); __builtin_amdgcn_s_setprio(0); } while (0)
; #define PG8_WAIT_V(n) asm volatile("s_waitcnt vmcnt(" #n ")" ::: "memory")
; #define PG8_WAIT_L(n) asm volatile("s_waitcnt lgkmcnt(" #n ")" ::: "memory")
; #define PG8_BAR __builtin_amdgcn_s_barrier()
; #define PG8_SCHED __builtin_amdgcn_sched_barrier(0)
; template <class Epi, class Sched, bool ALIGN_EPI = false, bool SP2 = false>
; __device__ __forceinline__ void gemm_phase(PG8_LAS unsigned char* lds, const Gemm g, const Sched& S, const Epi& E) {
;     ...
;         for (int t = 0; t < nt; t += 2) {
;             const bool last = (t == nt - 2);
;             const char* a1 = cA + (size_t)(t + 1) * kstep;
;             const char* a2 = last ? nA : cA + (size_t)(t + 2) * kstep; const char* b2 = last ? nB : cB + (size_t)(t + 2) * kstep;
;             const char* a3 = a2 + kstep; const char* b3 = b2 + kstep;
;     ...
;             PG8_WAIT_V(8); PG8_WAIT_L(0); PG8_BAR; PG8_MMA(0, 0, At, B0); PG8_MMA(0, 1, At, B1); PG8_BAR; PG8_SCHED;
;             PG8_LDA(At, 1, 1); PG8_STAGE(PG8_SB(1, 0), b3, voffB); PG8_STAGE(PG8_SB(1, 1), b3 + hstep, voffB); PG8_STAGE(PG8_SA(1, 0), a3, voffA);
;             PG8_WAIT_V(8); PG8_WAIT_L(0); PG8_BAR; PG8_MMA(1, 0, At, B0); PG8_MMA(1, 1, At, B1); PG8_BAR; PG8_SCHED;
;     ...
;         if constexpr (ALIGN_EPI) { if (wr == 0) PG8_BAR; }
	v_mfma_f32_16x16x32_bf16 v[66:69], v[182:185], v[218:221], v[66:69]
	s_setprio 0
	s_add_i32 s30, s70, s50
	v_lshl_add_u64 v[146:147], v[146:147], 0, s[10:11]
	s_mov_b32 m0, s30
	ds_read_b128 v[186:189], v152 offset:49152
	ds_read_b128 v[190:193], v152 offset:50176
	ds_read_b128 v[194:197], v152 offset:51200
	ds_read_b128 v[198:201], v152 offset:52224
	ds_read_b128 v[206:209], v152 offset:53248
	ds_read_b128 v[210:213], v152 offset:54272
	ds_read_b128 v[214:217], v152 offset:55296
	ds_read_b128 v[218:221], v152 offset:56320
	global_load_lds_dwordx4 v[146:147], off
	s_add_i32 m0, s30, 0x2000
	s_add_u32 s30, s42, 0x40080
	v_lshl_add_u64 v[146:147], v[202:203], 0, s[10:11]
	s_addc_u32 s31, s43, 0
	s_add_i32 s42, s71, s50
	global_load_lds_dwordx4 v[146:147], off
	v_lshl_add_u64 v[146:147], s[30:31], 0, v[132:133]
	s_mov_b32 m0, s42
	s_nop 0
	global_load_lds_dwordx4 v[146:147], off
	v_lshl_add_u64 v[146:147], s[30:31], 0, v[136:137]
	s_add_i32 m0, s42, 0x2000
	s_nop 0
	global_load_lds_dwordx4 v[146:147], off
	v_lshl_add_u64 v[146:147], v[222:223], 0, s[10:11]
	s_mov_b32 m0, s55
	s_nop 0
	global_load_lds_dwordx4 v[146:147], off
	v_lshl_add_u64 v[146:147], v[224:225], 0, s[10:11]
	s_mov_b32 m0, s56
	s_nop 0
	global_load_lds_dwordx4 v[146:147], off
	s_waitcnt vmcnt(8)
	s_waitcnt lgkmcnt(0)
	s_barrier
	s_setprio 1
	s_waitcnt lgkmcnt(0)
	v_mfma_f32_16x16x32_bf16 v[62:65], v[154:157], v[186:189], v[62:65]
	v_mfma_f32_16x16x32_bf16 v[58:61], v[162:165], v[186:189], v[58:61]
	v_mfma_f32_16x16x32_bf16 v[50:53], v[154:157], v[194:197], v[50:53]
	v_mfma_f32_16x16x32_bf16 v[42:45], v[162:165], v[194:197], v[42:45]
	v_mfma_f32_16x16x32_bf16 v[34:37], v[154:157], v[206:209], v[34:37]
	v_mfma_f32_16x16x32_bf16 v[26:29], v[162:165], v[206:209], v[26:29]
	v_mfma_f32_16x16x32_bf16 v[18:21], v[154:157], v[214:217], v[18:21]
	v_mfma_f32_16x16x32_bf16 v[10:13], v[162:165], v[214:217], v[10:13]
	v_mfma_f32_16x16x32_bf16 v[62:65], v[158:161], v[190:193], v[62:65]
	v_mfma_f32_16x16x32_bf16 v[58:61], v[166:169], v[190:193], v[58:61]
	v_mfma_f32_16x16x32_bf16 v[50:53], v[158:161], v[198:201], v[50:53]
	v_mfma_f32_16x16x32_bf16 v[42:45], v[166:169], v[198:201], v[42:45]
	v_mfma_f32_16x16x32_bf16 v[34:37], v[158:161], v[210:213], v[34:37]
	v_mfma_f32_16x16x32_bf16 v[26:29], v[166:169], v[210:213], v[26:29]
	v_mfma_f32_16x16x32_bf16 v[18:21], v[158:161], v[218:221], v[18:21]
	v_mfma_f32_16x16x32_bf16 v[10:13], v[166:169], v[218:221], v[10:13]
	s_setprio 0
	s_setprio 1
	v_mfma_f32_16x16x32_bf16 v[54:57], v[170:173], v[186:189], v[54:57]
	v_mfma_f32_16x16x32_bf16 v[46:49], v[178:181], v[186:189], v[46:49]
	v_mfma_f32_16x16x32_bf16 v[38:41], v[170:173], v[194:197], v[38:41]
	v_mfma_f32_16x16x32_bf16 v[30:33], v[178:181], v[194:197], v[30:33]
	v_mfma_f32_16x16x32_bf16 v[22:25], v[170:173], v[206:209], v[22:25]
	v_mfma_f32_16x16x32_bf16 v[14:17], v[178:181], v[206:209], v[14:17]
	v_mfma_f32_16x16x32_bf16 v[6:9], v[170:173], v[214:217], v[6:9]
	v_mfma_f32_16x16x32_bf16 v[2:5], v[178:181], v[214:217], v[2:5]
	v_mfma_f32_16x16x32_bf16 v[54:57], v[174:177], v[190:193], v[54:57]
	v_mfma_f32_16x16x32_bf16 v[46:49], v[182:185], v[190:193], v[46:49]
	v_mfma_f32_16x16x32_bf16 v[38:41], v[174:177], v[198:201], v[38:41]
	v_mfma_f32_16x16x32_bf16 v[30:33], v[182:185], v[198:201], v[30:33]
	v_mfma_f32_16x16x32_bf16 v[22:25], v[174:177], v[210:213], v[22:25]
	v_mfma_f32_16x16x32_bf16 v[14:17], v[182:185], v[210:213], v[14:17]
	v_mfma_f32_16x16x32_bf16 v[6:9], v[174:177], v[218:221], v[6:9]
	s_barrier
	v_mfma_f32_16x16x32_bf16 v[2:5], v[182:185], v[218:221], v[2:5]
	s_setprio 0
	s_add_i32 s69, s69, 2
	s_add_u32 s40, s40, 0x100
	s_addc_u32 s41, s41, 0
	s_add_u32 s67, s67, 0x100
	s_addc_u32 s68, s68, 0
	s_cmp_gt_u32 s69, 13
	s_cbranch_scc0 .LBB0_1822
	s_and_b64 vcc, exec, s[12:13]
	s_cbranch_vccz .LBB0_1825
	s_barrier

; #define PG8_STAGE(bufoff, gbase, voff) do { _Pragma("unroll") for (int _i = 0; _i < 2; ++_i) \
;         __builtin_amdgcn_global_load_lds((const unsigned*)((const char*)(gbase) + (voff)[_i]), (PG8_LAS unsigned*)(lds + (bufoff) + ldsw + _i * 8192), 16, 0, 0); } while (0)
; #define PG8_LDA(dst, b, h) do { _Pragma("unroll") for (int m = 0; m < 4; ++m) _Pragma("unroll") for (int k = 0; k < 2; ++k) dst[m][k] = *(const PG8_LAS bf16x8*)(lds + PG8_SA(b, h) + aoff + m * 2048 + k * 1024); } while (0)
; #define PG8_LDB(dst, b, h) do { _Pragma("unroll") for (int n = 0; n < 2; ++n) _Pragma("unroll") for (int k = 0; k < 2; ++k) dst[n][k] = *(const PG8_LAS bf16x8*)(lds + PG8_SB(b, h) + boff + n * 2048 + k * 1024); } while (0)
; #define PG8_MMA(ai, bj, At, Bt) do { __builtin_amdgcn_s_setprio(1); _Pragma("unroll") for (int m = 0; m < 4; ++m) _Pragma("unroll") for (int n = 0; n < 2; ++n) _Pragma("unroll") for (int k = 0; k < 2; ++k) \
;         acc[ai][bj][m][n] = __builtin_amdgcn_mfma_f32_16x16x32_bf16(Bt[n][k], At[m][k], acc[ai][bj][m][n], 0, 0, 0); __builtin_amdgcn_s_setprio(0); } while (0)
; #define PG8_WAIT_V(n) asm volatile("s_waitcnt vmcnt(" #n ")" ::: "memory")
; #define PG8_WAIT_L(n) asm volatile("s_waitcnt lgkmcnt(" #n ")" ::: "memory")
; #define PG8_BAR __builtin_amdgcn_s_barrier()
; #define PG8_SCHED __builtin_amdgcn_sched_barrier(0)
; template <class Epi, class Sched, bool ALIGN_EPI = false, bool SP2 = false>
; __device__ __forceinline__ void gemm_phase(PG8_LAS unsigned char* lds, const Gemm g, const Sched& S, const Epi& E) {
;     ...
;             const bool last = (t == nt - 2);
;             const char* a1 = cA + (size_t)(t + 1) * kstep;
;             const char* a2 = last ? nA : cA + (size_t)(t + 2) * kstep; const char* b2 = last ? nB : cB + (size_t)(t + 2) * kstep;
;             const char* a3 = a2 + kstep; const char* b3 = b2 + kstep;
;             if (last && has_next) S.a_ready(nxt);
;             if constexpr (SP2) {
;             PG8_LDB(B0, 0, 0); PG8_LDB(B1, 0, 1); PG8_SCHED; PG8_LDA(At, 0, 0); PG8_STAGE(PG8_SA(1, 1), a1 + hstep, voffA);
;             PG8_WAIT_V(8); PG8_WAIT_L(0); PG8_BAR; PG8_MMA(0, 0, At, B0); PG8_MMA(0, 1, At, B1); PG8_BAR; PG8_SCHED;
;             PG8_LDA(At, 0, 1); PG8_STAGE(PG8_SB(0, 0), b2, voffB); PG8_STAGE(PG8_SB(0, 1), b2 + hstep, voffB); PG8_STAGE(PG8_SA(0, 0), a2, voffA);
.LBB0_1905:
	ds_read_b128 v[122:125], v184
	ds_read_b128 v[126:129], v184 offset:1024
	ds_read_b128 v[130:133], v184 offset:2048
	ds_read_b128 v[134:137], v184 offset:3072
	ds_read_b128 v[142:145], v185
	ds_read_b128 v[146:149], v185 offset:1024
	ds_read_b128 v[150:153], v185 offset:2048
	ds_read_b128 v[158:161], v185 offset:3072
	s_add_u32 s30, s38, 0xfff00080
	s_addc_u32 s31, s39, -1
	s_cmp_eq_u32 s58, 60
	s_cselect_b32 s43, s23, s31
	s_cselect_b32 s42, s54, s30
	s_cselect_b32 s41, s21, s57
	s_cselect_b32 s40, s55, s56
	v_lshl_add_u64 v[218:219], s[38:39], 0, v[170:171]
	s_add_i32 m0, s37, 0xc000
	ds_read_b128 v[178:181], v186
	ds_read_b128 v[188:191], v186 offset:1024
	ds_read_b128 v[192:195], v186 offset:2048
	ds_read_b128 v[196:199], v186 offset:3072
	ds_read_b128 v[200:203], v186 offset:4096
	ds_read_b128 v[206:209], v186 offset:5120
	ds_read_b128 v[210:213], v186 offset:6144
	ds_read_b128 v[214:217], v186 offset:7168
	global_load_lds_dwordx4 v[218:219], off
	v_lshl_add_u64 v[218:219], s[38:39], 0, v[172:173]
	s_add_i32 m0, s37, 0xe000
	s_nop 0
	global_load_lds_dwordx4 v[218:219], off
	s_waitcnt vmcnt(8)
	s_waitcnt lgkmcnt(0)
	s_barrier
	s_setprio 1
	s_waitcnt lgkmcnt(0)
	v_mfma_f32_16x16x32_bf16 v[154:157], v[122:125], v[178:181], v[154:157]
	v_mfma_f32_16x16x32_bf16 v[138:141], v[130:133], v[178:181], v[138:141]
	v_mfma_f32_16x16x32_bf16 v[114:117], v[122:125], v[192:195], v[114:117]
	v_mfma_f32_16x16x32_bf16 v[106:109], v[130:133], v[192:195], v[106:109]
	v_mfma_f32_16x16x32_bf16 v[94:97], v[122:125], v[200:203], v[94:97]
	v_mfma_f32_16x16x32_bf16 v[90:93], v[130:133], v[200:203], v[90:93]
	v_mfma_f32_16x16x32_bf16 v[82:85], v[122:125], v[210:213], v[82:85]
	v_mfma_f32_16x16x32_bf16 v[74:77], v[130:133], v[210:213], v[74:77]
	v_mfma_f32_16x16x32_bf16 v[154:157], v[126:129], v[188:191], v[154:157]
	v_mfma_f32_16x16x32_bf16 v[138:141], v[134:137], v[188:191], v[138:141]
	v_mfma_f32_16x16x32_bf16 v[114:117], v[126:129], v[196:199], v[114:117]
	v_mfma_f32_16x16x32_bf16 v[106:109], v[134:137], v[196:199], v[106:109]
	v_mfma_f32_16x16x32_bf16 v[94:97], v[126:129], v[206:209], v[94:97]
	v_mfma_f32_16x16x32_bf16 v[90:93], v[134:137], v[206:209], v[90:93]
	v_mfma_f32_16x16x32_bf16 v[82:85], v[126:129], v[214:217], v[82:85]
	v_mfma_f32_16x16x32_bf16 v[74:77], v[134:137], v[214:217], v[74:77]
	s_setprio 0
	s_setprio 1
	v_mfma_f32_16x16x32_bf16 v[118:121], v[142:145], v[178:181], v[118:121]
	v_mfma_f32_16x16x32_bf16 v[110:113], v[150:153], v[178:181], v[110:113]
	v_mfma_f32_16x16x32_bf16 v[102:105], v[142:145], v[192:195], v[102:105]
	v_mfma_f32_16x16x32_bf16 v[98:101], v[150:153], v[192:195], v[98:101]
	v_mfma_f32_16x16x32_bf16 v[86:89], v[142:145], v[200:203], v[86:89]
	v_mfma_f32_16x16x32_bf16 v[78:81], v[150:153], v[200:203], v[78:81]
	v_mfma_f32_16x16x32_bf16 v[70:73], v[142:145], v[210:213], v[70:73]
	v_mfma_f32_16x16x32_bf16 v[66:69], v[150:153], v[210:213], v[66:69]
	v_mfma_f32_16x16x32_bf16 v[118:121], v[146:149], v[188:191], v[118:121]
	v_mfma_f32_16x16x32_bf16 v[110:113], v[158:161], v[188:191], v[110:113]
	v_mfma_f32_16x16x32_bf16 v[102:105], v[146:149], v[196:199], v[102:105]
	v_mfma_f32_16x16x32_bf16 v[98:101], v[158:161], v[196:199], v[98:101]
	v_mfma_f32_16x16x32_bf16 v[86:89], v[146:149], v[206:209], v[86:89]
	v_mfma_f32_16x16x32_bf16 v[78:81], v[158:161], v[206:209], v[78:81]
	v_mfma_f32_16x16x32_bf16 v[70:73], v[146:149], v[214:217], v[70:73]
	s_barrier
	v_mfma_f32_16x16x32_bf16 v[66:69], v[158:161], v[214:217], v[66:69]
	s_setprio 0
	s_add_i32 s30, s49, s33
	v_lshl_add_u64 v[218:219], s[40:41], 0, v[164:165]
	s_mov_b32 m0, s30
	ds_read_b128 v[178:181], v186 offset:16384
	ds_read_b128 v[188:191], v186 offset:17408
	ds_read_b128 v[192:195], v186 offset:18432
	ds_read_b128 v[196:199], v186 offset:19456
	ds_read_b128 v[200:203], v186 offset:20480
	ds_read_b128 v[206:209], v186 offset:21504
	ds_read_b128 v[210:213], v186 offset:22528
	ds_read_b128 v[214:217], v186 offset:23552
	global_load_lds_dwordx4 v[218:219], off
	s_add_i32 m0, s30, 0x2000
	s_add_u32 s30, s40, 0x100000
	v_lshl_add_u64 v[220:221], s[40:41], 0, v[168:169]
	s_addc_u32 s31, s41, 0
	s_add_i32 s59, s52, s33
	global_load_lds_dwordx4 v[220:221], off
	v_lshl_add_u64 v[222:223], s[30:31], 0, v[164:165]
	s_mov_b32 m0, s59
	v_lshl_add_u64 v[224:225], s[42:43], 0, v[166:167]
	global_load_lds_dwordx4 v[222:223], off
	v_lshl_add_u64 v[222:223], s[30:31], 0, v[168:169]
	s_add_i32 m0, s59, 0x2000
	s_nop 0
	global_load_lds_dwordx4 v[222:223], off
	v_lshl_add_u64 v[222:223], s[42:43], 0, v[162:163]
	s_mov_b32 m0, s37
	s_nop 0
	global_load_lds_dwordx4 v[222:223], off
	s_mov_b32 m0, s44
	s_nop 0
	global_load_lds_dwordx4 v[224:225], off
	s_waitcnt vmcnt(8)
	s_waitcnt lgkmcnt(0)
	s_barrier
; #define PG8_STAGE(bufoff, gbase, voff) do { _Pragma("unroll") for (int _i = 0; _i < 2; ++_i) \
;         __builtin_amdgcn_global_load_lds((const unsigned*)((const char*)(gbase) + (voff)[_i]), (PG8_LAS unsigned*)(lds + (bufoff) + ldsw + _i * 8192), 16, 0, 0); } while (0)
; #define PG8_LDA(dst, b, h) do { _Pragma("unroll") for (int m = 0; m < 4; ++m) _Pragma("unroll") for (int k = 0; k < 2; ++k) dst[m][k] = *(const PG8_LAS bf16x8*)(lds + PG8_SA(b, h) + aoff + m * 2048 + k * 1024); } while (0)
; #define PG8_LDB(dst, b, h) do { _Pragma("unroll") for (int n = 0; n < 2; ++n) _Pragma("unroll") for (int k = 0; k < 2; ++k) dst[n][k] = *(const PG8_LAS bf16x8*)(lds + PG8_SB(b, h) + boff + n * 2048 + k * 1024); } while (0)
; #define PG8_MMA(ai, bj, At, Bt) do { __builtin_amdgcn_s_setprio(1); _Pragma("unroll") for (int m = 0; m < 4; ++m) _Pragma("unroll") for (int n = 0; n < 2; ++n) _Pragma("unroll") for (int k = 0; k < 2; ++k) \
;         acc[ai][bj][m][n] = __builtin_amdgcn_mfma_f32_16x16x32_bf16(Bt[n][k], At[m][k], acc[ai][bj][m][n], 0, 0, 0); __builtin_amdgcn_s_setprio(0); } while (0)
; #define PG8_WAIT_V(n) asm volatile("s_waitcnt vmcnt(" #n ")" ::: "memory")
; #define PG8_WAIT_L(n) asm volatile("s_waitcnt lgkmcnt(" #n ")" ::: "memory")
; #define PG8_BAR __builtin_amdgcn_s_barrier()
; #define PG8_SCHED __builtin_amdgcn_sched_barrier(0)
; template <class Epi, class Sched, bool ALIGN_EPI = false, bool SP2 = false>
; __device__ __forceinline__ void gemm_phase(PG8_LAS unsigned char* lds, const Gemm g, const Sched& S, const Epi& E) {
;     ...
;             PG8_WAIT_V(8); PG8_WAIT_L(0); PG8_BAR; PG8_MMA(1, 0, At, B0); PG8_MMA(1, 1, At, B1); PG8_BAR; PG8_SCHED;
;             PG8_LDB(B0, 1, 0); PG8_LDB(B1, 1, 1); PG8_SCHED; PG8_LDA(At, 1, 0); PG8_STAGE(PG8_SA(0, 1), a2 + hstep, voffA);
;             PG8_WAIT_V(8); PG8_WAIT_L(0); PG8_BAR; PG8_MMA(0, 0, At, B0); PG8_MMA(0, 1, At, B1); PG8_BAR; PG8_SCHED;
	s_setprio 1
	s_waitcnt lgkmcnt(0)
	v_mfma_f32_16x16x32_bf16 v[62:65], v[122:125], v[178:181], v[62:65]
	v_mfma_f32_16x16x32_bf16 v[58:61], v[130:133], v[178:181], v[58:61]
	v_mfma_f32_16x16x32_bf16 v[50:53], v[122:125], v[192:195], v[50:53]
	v_mfma_f32_16x16x32_bf16 v[42:45], v[130:133], v[192:195], v[42:45]
	v_mfma_f32_16x16x32_bf16 v[30:33], v[122:125], v[200:203], v[30:33]
	v_mfma_f32_16x16x32_bf16 v[26:29], v[130:133], v[200:203], v[26:29]
	v_mfma_f32_16x16x32_bf16 v[18:21], v[122:125], v[210:213], v[18:21]
	v_mfma_f32_16x16x32_bf16 v[10:13], v[130:133], v[210:213], v[10:13]
	v_mfma_f32_16x16x32_bf16 v[62:65], v[126:129], v[188:191], v[62:65]
	v_mfma_f32_16x16x32_bf16 v[58:61], v[134:137], v[188:191], v[58:61]
	v_mfma_f32_16x16x32_bf16 v[50:53], v[126:129], v[196:199], v[50:53]
	v_mfma_f32_16x16x32_bf16 v[42:45], v[134:137], v[196:199], v[42:45]
	v_mfma_f32_16x16x32_bf16 v[30:33], v[126:129], v[206:209], v[30:33]
	v_mfma_f32_16x16x32_bf16 v[26:29], v[134:137], v[206:209], v[26:29]
	v_mfma_f32_16x16x32_bf16 v[18:21], v[126:129], v[214:217], v[18:21]
	v_mfma_f32_16x16x32_bf16 v[10:13], v[134:137], v[214:217], v[10:13]
	s_setprio 0
	s_setprio 1
	v_mfma_f32_16x16x32_bf16 v[54:57], v[142:145], v[178:181], v[54:57]
	v_mfma_f32_16x16x32_bf16 v[46:49], v[150:153], v[178:181], v[46:49]
	v_mfma_f32_16x16x32_bf16 v[38:41], v[142:145], v[192:195], v[38:41]
	v_mfma_f32_16x16x32_bf16 v[34:37], v[150:153], v[192:195], v[34:37]
	v_mfma_f32_16x16x32_bf16 v[22:25], v[142:145], v[200:203], v[22:25]
	v_mfma_f32_16x16x32_bf16 v[14:17], v[150:153], v[200:203], v[14:17]
	v_mfma_f32_16x16x32_bf16 v[6:9], v[142:145], v[210:213], v[6:9]
	v_mfma_f32_16x16x32_bf16 v[2:5], v[150:153], v[210:213], v[2:5]
	v_mfma_f32_16x16x32_bf16 v[54:57], v[146:149], v[188:191], v[54:57]
	v_mfma_f32_16x16x32_bf16 v[46:49], v[158:161], v[188:191], v[46:49]
	v_mfma_f32_16x16x32_bf16 v[38:41], v[146:149], v[196:199], v[38:41]
	v_mfma_f32_16x16x32_bf16 v[34:37], v[158:161], v[196:199], v[34:37]
	v_mfma_f32_16x16x32_bf16 v[22:25], v[146:149], v[206:209], v[22:25]
	v_mfma_f32_16x16x32_bf16 v[14:17], v[158:161], v[206:209], v[14:17]
	v_mfma_f32_16x16x32_bf16 v[6:9], v[146:149], v[214:217], v[6:9]
	s_barrier
	v_mfma_f32_16x16x32_bf16 v[2:5], v[158:161], v[214:217], v[2:5]
	s_setprio 0
	s_add_i32 s59, 0, 0x18000
	s_add_i32 s60, 0, 0x1c000
	v_add_u32_e32 v134, s59, v182
	v_add_u32_e32 v158, s60, v182
	ds_read_b128 v[122:125], v134
	ds_read_b128 v[126:129], v134 offset:1024
	ds_read_b128 v[130:133], v134 offset:2048
	ds_read_b128 v[134:137], v134 offset:3072
	ds_read_b128 v[142:145], v158
	ds_read_b128 v[146:149], v158 offset:1024
	ds_read_b128 v[150:153], v158 offset:2048
	ds_read_b128 v[158:161], v158 offset:3072
	s_add_u32 s30, s42, 0x100000
	s_addc_u32 s31, s43, 0
	s_mov_b32 m0, s45
	v_lshl_add_u64 v[226:227], s[30:31], 0, v[162:163]
	ds_read_b128 v[178:181], v186 offset:32768
	ds_read_b128 v[188:191], v186 offset:33792
	ds_read_b128 v[192:195], v186 offset:34816
	ds_read_b128 v[196:199], v186 offset:35840
	ds_read_b128 v[200:203], v186 offset:36864
	ds_read_b128 v[206:209], v186 offset:37888
	ds_read_b128 v[210:213], v186 offset:38912
	ds_read_b128 v[214:217], v186 offset:39936
	global_load_lds_dwordx4 v[226:227], off
	v_lshl_add_u64 v[226:227], s[30:31], 0, v[166:167]
	s_mov_b32 m0, s50
	s_nop 0
	global_load_lds_dwordx4 v[226:227], off
	s_waitcnt vmcnt(8)
	s_waitcnt lgkmcnt(0)
	s_barrier
	s_setprio 1
	s_waitcnt lgkmcnt(0)
	v_mfma_f32_16x16x32_bf16 v[154:157], v[122:125], v[178:181], v[154:157]
	v_mfma_f32_16x16x32_bf16 v[138:141], v[130:133], v[178:181], v[138:141]
	v_mfma_f32_16x16x32_bf16 v[114:117], v[122:125], v[192:195], v[114:117]
	v_mfma_f32_16x16x32_bf16 v[106:109], v[130:133], v[192:195], v[106:109]
	v_mfma_f32_16x16x32_bf16 v[94:97], v[122:125], v[200:203], v[94:97]
	v_mfma_f32_16x16x32_bf16 v[90:93], v[130:133], v[200:203], v[90:93]
	v_mfma_f32_16x16x32_bf16 v[82:85], v[122:125], v[210:213], v[82:85]
	v_mfma_f32_16x16x32_bf16 v[74:77], v[130:133], v[210:213], v[74:77]
	v_mfma_f32_16x16x32_bf16 v[154:157], v[126:129], v[188:191], v[154:157]
	v_mfma_f32_16x16x32_bf16 v[138:141], v[134:137], v[188:191], v[138:141]
	v_mfma_f32_16x16x32_bf16 v[114:117], v[126:129], v[196:199], v[114:117]
	v_mfma_f32_16x16x32_bf16 v[106:109], v[134:137], v[196:199], v[106:109]
	v_mfma_f32_16x16x32_bf16 v[94:97], v[126:129], v[206:209], v[94:97]
	v_mfma_f32_16x16x32_bf16 v[90:93], v[134:137], v[206:209], v[90:93]
	v_mfma_f32_16x16x32_bf16 v[82:85], v[126:129], v[214:217], v[82:85]
	v_mfma_f32_16x16x32_bf16 v[74:77], v[134:137], v[214:217], v[74:77]
	s_setprio 0
	s_setprio 1
	v_mfma_f32_16x16x32_bf16 v[118:121], v[142:145], v[178:181], v[118:121]
	v_mfma_f32_16x16x32_bf16 v[110:113], v[150:153], v[178:181], v[110:113]
	v_mfma_f32_16x16x32_bf16 v[102:105], v[142:145], v[192:195], v[102:105]
	v_mfma_f32_16x16x32_bf16 v[98:101], v[150:153], v[192:195], v[98:101]
	v_mfma_f32_16x16x32_bf16 v[86:89], v[142:145], v[200:203], v[86:89]
	v_mfma_f32_16x16x32_bf16 v[78:81], v[150:153], v[200:203], v[78:81]
	v_mfma_f32_16x16x32_bf16 v[70:73], v[142:145], v[210:213], v[70:73]
	v_mfma_f32_16x16x32_bf16 v[66:69], v[150:153], v[210:213], v[66:69]
	v_mfma_f32_16x16x32_bf16 v[118:121], v[146:149], v[188:191], v[118:121]
	v_mfma_f32_16x16x32_bf16 v[110:113], v[158:161], v[188:191], v[110:113]
	v_mfma_f32_16x16x32_bf16 v[102:105], v[146:149], v[196:199], v[102:105]
	v_mfma_f32_16x16x32_bf16 v[98:101], v[158:161], v[196:199], v[98:101]
	v_mfma_f32_16x16x32_bf16 v[86:89], v[146:149], v[206:209], v[86:89]
	v_mfma_f32_16x16x32_bf16 v[78:81], v[158:161], v[206:209], v[78:81]
	v_mfma_f32_16x16x32_bf16 v[70:73], v[146:149], v[214:217], v[70:73]
	s_barrier
; #define PG8_STAGE(bufoff, gbase, voff) do { _Pragma("unroll") for (int _i = 0; _i < 2; ++_i) \
;         __builtin_amdgcn_global_load_lds((const unsigned*)((const char*)(gbase) + (voff)[_i]), (PG8_LAS unsigned*)(lds + (bufoff) + ldsw + _i * 8192), 16, 0, 0); } while (0)
; #define PG8_LDA(dst, b, h) do { _Pragma("unroll") for (int m = 0; m < 4; ++m) _Pragma("unroll") for (int k = 0; k < 2; ++k) dst[m][k] = *(const PG8_LAS bf16x8*)(lds + PG8_SA(b, h) + aoff + m * 2048 + k * 1024); } while (0)
; #define PG8_MMA(ai, bj, At, Bt) do { __builtin_amdgcn_s_setprio(1); _Pragma("unroll") for (int m = 0; m < 4; ++m) _Pragma("unroll") for (int n = 0; n < 2; ++n) _Pragma("unroll") for (int k = 0; k < 2; ++k) \
;         acc[ai][bj][m][n] = __builtin_amdgcn_mfma_f32_16x16x32_bf16(Bt[n][k], At[m][k], acc[ai][bj][m][n], 0, 0, 0); __builtin_amdgcn_s_setprio(0); } while (0)
; #define PG8_WAIT_V(n) asm volatile("s_waitcnt vmcnt(" #n ")" ::: "memory")
; #define PG8_WAIT_L(n) asm volatile("s_waitcnt lgkmcnt(" #n ")" ::: "memory")
; #define PG8_BAR __builtin_amdgcn_s_barrier()
; #define PG8_SCHED __builtin_amdgcn_sched_barrier(0)
; template <class Epi, class Sched, bool ALIGN_EPI = false, bool SP2 = false>
; __device__ __forceinline__ void gemm_phase(PG8_LAS unsigned char* lds, const Gemm g, const Sched& S, const Epi& E) {
;     ...
;         for (int t = 0; t < nt; t += 2) {
;             const bool last = (t == nt - 2);
;             const char* a1 = cA + (size_t)(t + 1) * kstep;
;             const char* a2 = last ? nA : cA + (size_t)(t + 2) * kstep; const char* b2 = last ? nB : cB + (size_t)(t + 2) * kstep;
;             const char* a3 = a2 + kstep; const char* b3 = b2 + kstep;
;     ...
;             PG8_WAIT_V(8); PG8_WAIT_L(0); PG8_BAR; PG8_MMA(0, 0, At, B0); PG8_MMA(0, 1, At, B1); PG8_BAR; PG8_SCHED;
;             PG8_LDA(At, 1, 1); PG8_STAGE(PG8_SB(1, 0), b3, voffB); PG8_STAGE(PG8_SB(1, 1), b3 + hstep, voffB); PG8_STAGE(PG8_SA(1, 0), a3, voffA);
;             PG8_WAIT_V(8); PG8_WAIT_L(0); PG8_BAR; PG8_MMA(1, 0, At, B0); PG8_MMA(1, 1, At, B1); PG8_BAR; PG8_SCHED;
;     ...
;         if constexpr (ALIGN_EPI) { if (wr == 0) PG8_BAR; }
	v_mfma_f32_16x16x32_bf16 v[66:69], v[158:161], v[214:217], v[66:69]
	s_setprio 0
	s_add_i32 s30, s59, s33
	v_lshl_add_u64 v[218:219], v[218:219], 0, s[14:15]
	s_mov_b32 m0, s30
	ds_read_b128 v[178:181], v186 offset:49152
	ds_read_b128 v[188:191], v186 offset:50176
	ds_read_b128 v[192:195], v186 offset:51200
	ds_read_b128 v[196:199], v186 offset:52224
	ds_read_b128 v[200:203], v186 offset:53248
	ds_read_b128 v[206:209], v186 offset:54272
	ds_read_b128 v[210:213], v186 offset:55296
	ds_read_b128 v[214:217], v186 offset:56320
	global_load_lds_dwordx4 v[218:219], off
	s_add_i32 m0, s30, 0x2000
	s_add_u32 s30, s40, 0x100080
	v_lshl_add_u64 v[218:219], v[220:221], 0, s[14:15]
	s_addc_u32 s31, s41, 0
	s_add_i32 s40, s60, s33
	global_load_lds_dwordx4 v[218:219], off
	v_lshl_add_u64 v[218:219], s[30:31], 0, v[164:165]
	s_mov_b32 m0, s40
	s_nop 0
	global_load_lds_dwordx4 v[218:219], off
	v_lshl_add_u64 v[218:219], s[30:31], 0, v[168:169]
	s_add_i32 m0, s40, 0x2000
	s_nop 0
	global_load_lds_dwordx4 v[218:219], off
	v_lshl_add_u64 v[218:219], v[222:223], 0, s[14:15]
	s_mov_b32 m0, s46
	s_nop 0
	global_load_lds_dwordx4 v[218:219], off
	v_lshl_add_u64 v[218:219], v[224:225], 0, s[14:15]
	s_mov_b32 m0, s47
	s_nop 0
	global_load_lds_dwordx4 v[218:219], off
	s_waitcnt vmcnt(8)
	s_waitcnt lgkmcnt(0)
	s_barrier
	s_setprio 1
	s_waitcnt lgkmcnt(0)
	v_mfma_f32_16x16x32_bf16 v[62:65], v[122:125], v[178:181], v[62:65]
	v_mfma_f32_16x16x32_bf16 v[58:61], v[130:133], v[178:181], v[58:61]
	v_mfma_f32_16x16x32_bf16 v[50:53], v[122:125], v[192:195], v[50:53]
	v_mfma_f32_16x16x32_bf16 v[42:45], v[130:133], v[192:195], v[42:45]
	v_mfma_f32_16x16x32_bf16 v[30:33], v[122:125], v[200:203], v[30:33]
	v_mfma_f32_16x16x32_bf16 v[26:29], v[130:133], v[200:203], v[26:29]
	v_mfma_f32_16x16x32_bf16 v[18:21], v[122:125], v[210:213], v[18:21]
	v_mfma_f32_16x16x32_bf16 v[10:13], v[130:133], v[210:213], v[10:13]
	v_mfma_f32_16x16x32_bf16 v[62:65], v[126:129], v[188:191], v[62:65]
	v_mfma_f32_16x16x32_bf16 v[58:61], v[134:137], v[188:191], v[58:61]
	v_mfma_f32_16x16x32_bf16 v[50:53], v[126:129], v[196:199], v[50:53]
	v_mfma_f32_16x16x32_bf16 v[42:45], v[134:137], v[196:199], v[42:45]
	v_mfma_f32_16x16x32_bf16 v[30:33], v[126:129], v[206:209], v[30:33]
	v_mfma_f32_16x16x32_bf16 v[26:29], v[134:137], v[206:209], v[26:29]
	v_mfma_f32_16x16x32_bf16 v[18:21], v[126:129], v[214:217], v[18:21]
	v_mfma_f32_16x16x32_bf16 v[10:13], v[134:137], v[214:217], v[10:13]
	s_setprio 0
	s_setprio 1
	v_mfma_f32_16x16x32_bf16 v[54:57], v[142:145], v[178:181], v[54:57]
	v_mfma_f32_16x16x32_bf16 v[46:49], v[150:153], v[178:181], v[46:49]
	v_mfma_f32_16x16x32_bf16 v[38:41], v[142:145], v[192:195], v[38:41]
	v_mfma_f32_16x16x32_bf16 v[34:37], v[150:153], v[192:195], v[34:37]
	v_mfma_f32_16x16x32_bf16 v[22:25], v[142:145], v[200:203], v[22:25]
	v_mfma_f32_16x16x32_bf16 v[14:17], v[150:153], v[200:203], v[14:17]
	v_mfma_f32_16x16x32_bf16 v[6:9], v[142:145], v[210:213], v[6:9]
	v_mfma_f32_16x16x32_bf16 v[2:5], v[150:153], v[210:213], v[2:5]
	v_mfma_f32_16x16x32_bf16 v[54:57], v[146:149], v[188:191], v[54:57]
	v_mfma_f32_16x16x32_bf16 v[46:49], v[158:161], v[188:191], v[46:49]
	v_mfma_f32_16x16x32_bf16 v[38:41], v[146:149], v[196:199], v[38:41]
	v_mfma_f32_16x16x32_bf16 v[34:37], v[158:161], v[196:199], v[34:37]
	v_mfma_f32_16x16x32_bf16 v[22:25], v[146:149], v[206:209], v[22:25]
	v_mfma_f32_16x16x32_bf16 v[14:17], v[158:161], v[206:209], v[14:17]
	v_mfma_f32_16x16x32_bf16 v[6:9], v[146:149], v[214:217], v[6:9]
	s_barrier
	v_mfma_f32_16x16x32_bf16 v[2:5], v[158:161], v[214:217], v[2:5]
	s_setprio 0
	s_add_i32 s58, s58, 2
	s_add_u32 s38, s38, 0x100
	s_addc_u32 s39, s39, 0
	s_add_u32 s56, s56, 0x100
	s_addc_u32 s57, s57, 0
	s_cmp_gt_u32 s58, 61
	s_cbranch_scc0 .LBB0_1905
	s_and_b64 vcc, exec, s[16:17]
	s_cbranch_vccz .LBB0_1908
	s_barrier
